# m14 + packed fp32 VALU (v_pk_fma/add/mul_f32) split into scalar pairs in indexer, stick, band, DSA, cross and select loops (263 sites, bit-identical)
# baseline (speedup 1.0000x reference)
; #define LAS __attribute__((address_space(3)))
; template <int MODE>
; DEVI void attn_unit(LAS unsigned char* lds, const bf16_t* Qw, int ldq, const bf16_t* Kb, const bf16_t* Vb, int ldk, bf16_t* Ow, int ldo,
;                     int j_first, int ntiles, int jstep, int wj_lo, int wj_hi, int t0) {
;     ...
;     int j = j_first;
;     FA_SLOAD(j);
;     for (int i = 0; i < ntiles; ++i, j += jstep) {
;         const int buf = i & 1;
;         FA_SWRITE(buf);
;         asm volatile("" ::: "memory");
;         if (i + 1 < ntiles) FA_SLOAD(j + jstep);
;         asm volatile("s_waitcnt lgkmcnt(0)" ::: "memory"); __builtin_amdgcn_s_barrier(); asm volatile("" ::: "memory");
;         if constexpr (MODE == M_STICK) {
;             if (i > 0) { const u32x4 f0 = *(LAS const u32x4*)(dflag + ((i - 1) & 1) * 8), f1 = *(LAS const u32x4*)(dflag + ((i - 1) & 1) * 8 + 4);
;                 if ((f0.x & f0.y & f0.z & f0.w & f1.x & f1.y & f1.z & f1.w) != 0u) break; }
;             if (lane == 0) dflag[(i & 1) * 8 + wid] = mydone ? 1u : 0u;
;         }
;         if (j >= wj_lo && j <= wj_hi && !mydone) {
;             f32x16 p0, p1;
;             if constexpr (MODE == M_STICK) {
;                 int qz_ = 0; asm volatile("" : "+v"(qz_)); const bf16_t* qp2 = qp + qz_;
; #pragma unroll
;                 for (int d0 = 0; d0 < 8; ++d0) qr[d0] = *(const bf16x8*)(qp2 + d0 * 16); }
;             qkt(p0, p1, K_lds + buf * SHM_K, qr, r32, hi);
;             bf16x8 pa0, pa1, pa2, pa3;
;             if constexpr (MODE == M_STICK) {
;                 const int tq = t0 + r32; const bool diag = (64 * j + 63 >= t0);
;                 stick_half(p1, carry, diag, 64 * j + 32 + 4 * hi, tq, hi);
;                 stick_half(p0, carry, diag, 64 * j + 4 * hi, tq, hi);
;                 if (__all(carry < -152.f)) { mydone = true; if (lane == 0) dflag[(i & 1) * 8 + wid] = 1u; }
;                 pack_p(p0, p1, pa0, pa1, pa2, pa3);
;             } else {
;                 if constexpr (MODE == M_BAND) {
;                     const int cw = t0 >> 6;
;                     if (j <= cw - 3) { const float bc = bias2[191];
; #pragma unroll
;                         for (int r = 0; r < 16; ++r) { p0[r] = fmaf(p0[r], C2, bc); p1[r] = fmaf(p1[r], C2, bc); }
;                     } else { const int d0 = (t0 + r32) - (64 * j + 4 * hi) + 63;
; #pragma unroll
.LBB11_829:
	s_and_b32 s11, s10, 0x4000
	v_add_u32_e32 v68, s11, v183
	v_add3_u32 v69, v68, v173, v174
	v_add3_u32 v68, v68, v178, v174
	s_add_i32 s12, s11, 0
	s_waitcnt vmcnt(0)
	ds_write_b128 v69, v[136:139]
	ds_write_b128 v68, v[144:147]
	v_add3_u32 v68, s12, v176, v177
	ds_write_b128 v68, v[132:135] offset:32768
	v_add3_u32 v68, s12, v179, v177
	ds_write_b128 v68, v[140:143] offset:32768
	v_lshl_add_u64 v[68:69], v[160:161], 0, s[2:3]
	s_mov_b32 s4, 0x5c280000
	v_add_co_u32_e64 v70, s[4:5], s4, v68
	v_add_u32_e32 v165, s12, v180
	s_nop 0
	v_addc_co_u32_e64 v71, s[4:5], 0, v69, s[4:5]
	s_mov_b32 s4, 0x5c2c0000
	s_nop 0
	v_add_co_u32_e64 v68, s[4:5], s4, v68
	v_add_u32_e32 v84, v165, v181
	s_nop 0
	v_addc_co_u32_e64 v69, s[4:5], 0, v69, s[4:5]
	global_load_dwordx4 v[136:139], v[70:71], off offset:1024
	global_load_dwordx4 v[132:135], v[70:71], off
	global_load_dwordx4 v[144:147], v[68:69], off offset:1024
	global_load_dwordx4 v[140:143], v[68:69], off
	s_waitcnt lgkmcnt(0)
	s_barrier
	ds_read_b128 v[68:71], v84 offset:32768
	v_add_u32_e32 v184, v165, v175
	ds_read_b128 v[200:203], v184 offset:32768
	s_waitcnt lgkmcnt(1)
	v_mfma_f32_32x32x16_bf16 v[68:83], v[68:71], v[128:131], 0
	ds_read_b128 v[84:87], v84 offset:40960
	v_and_b32_e32 v185, 64, v215
	v_add_u32_e32 v185, 64, v185
	s_waitcnt lgkmcnt(1)
	v_mfma_f32_32x32x16_bf16 v[68:83], v[200:203], v[124:127], v[68:83]
	ds_read_b128 v[200:203], v184 offset:40960
	v_add_u32_e32 v184, v165, v172
	s_waitcnt lgkmcnt(1)
	v_mfma_f32_32x32x16_bf16 v[84:99], v[84:87], v[128:131], 0
	s_waitcnt lgkmcnt(0)
	v_mfma_f32_32x32x16_bf16 v[84:99], v[200:203], v[124:127], v[84:99]
	ds_read_b128 v[200:203], v184 offset:32768
	s_waitcnt lgkmcnt(0)
	v_mfma_f32_32x32x16_bf16 v[68:83], v[200:203], v[120:123], v[68:83]
	ds_read_b128 v[200:203], v184 offset:40960
	v_add_u32_e32 v184, v165, v171
	s_waitcnt lgkmcnt(0)
	v_mfma_f32_32x32x16_bf16 v[84:99], v[200:203], v[120:123], v[84:99]
	ds_read_b128 v[200:203], v184 offset:32768
	s_waitcnt lgkmcnt(0)
	v_mfma_f32_32x32x16_bf16 v[68:83], v[200:203], v[116:119], v[68:83]
	ds_read_b128 v[200:203], v184 offset:40960
	v_add_u32_e32 v184, v165, v170
	s_waitcnt lgkmcnt(0)
	v_mfma_f32_32x32x16_bf16 v[84:99], v[200:203], v[116:119], v[84:99]
	ds_read_b128 v[200:203], v184 offset:32768
	s_waitcnt lgkmcnt(0)
	v_mfma_f32_32x32x16_bf16 v[68:83], v[200:203], v[112:115], v[68:83]
	ds_read_b128 v[200:203], v184 offset:40960
	v_add_u32_e32 v184, v165, v169
	s_waitcnt lgkmcnt(0)
	v_mfma_f32_32x32x16_bf16 v[84:99], v[200:203], v[112:115], v[84:99]
	ds_read_b128 v[200:203], v184 offset:32768
	s_waitcnt lgkmcnt(0)
	v_mfma_f32_32x32x16_bf16 v[68:83], v[200:203], v[108:111], v[68:83]
	ds_read_b128 v[200:203], v184 offset:40960
	v_add_u32_e32 v184, v165, v168
	v_add_u32_e32 v165, v165, v167
	s_waitcnt lgkmcnt(0)
	v_mfma_f32_32x32x16_bf16 v[84:99], v[200:203], v[108:111], v[84:99]
	ds_read_b128 v[200:203], v184 offset:32768
	s_waitcnt lgkmcnt(0)
	v_mfma_f32_32x32x16_bf16 v[68:83], v[200:203], v[104:107], v[68:83]
	ds_read_b128 v[200:203], v184 offset:40960
	s_waitcnt lgkmcnt(0)
	v_mfma_f32_32x32x16_bf16 v[84:99], v[200:203], v[104:107], v[84:99]
	ds_read_b128 v[200:203], v165 offset:40960
	s_waitcnt lgkmcnt(0)
	v_mfma_f32_32x32x16_bf16 v[84:99], v[200:203], v[100:103], v[84:99]
	ds_read_b128 v[200:203], v165 offset:32768
	s_waitcnt lgkmcnt(0)
	v_mfma_f32_32x32x16_bf16 v[68:83], v[200:203], v[100:103], v[68:83]
	s_nop 8
	v_max_f32_e32 v165, v84, v84
	s_nop 1
	v_max_f32_e32 v184, v68, v68
	v_max_f32_e32 v165, v184, v165
	v_max3_f32 v165, v165, v69, v70
	s_nop 0
	v_max3_f32 v165, v165, v71, v72
	s_nop 0
	v_max3_f32 v165, v165, v73, v74
	s_nop 0
	v_max3_f32 v165, v165, v75, v76
	s_nop 0
	v_max3_f32 v165, v165, v77, v78
	s_nop 0
	v_max3_f32 v165, v165, v79, v80
	s_nop 0
	v_max3_f32 v165, v165, v81, v82
	s_nop 0
	v_max3_f32 v165, v165, v85, v86
	s_nop 0
	v_max3_f32 v165, v165, v87, v88
	s_nop 0
	v_max3_f32 v165, v165, v89, v90
	s_nop 0
	v_max3_f32 v165, v165, v91, v92
	s_nop 0
	v_max3_f32 v165, v165, v93, v94
	s_nop 0
	v_max3_f32 v165, v165, v95, v96
	s_nop 0
	v_max3_f32 v165, v165, v97, v98
	s_nop 0
	v_max3_f32 v184, v165, v83, v99
	v_xor_b32_e32 v165, 32, v215
	v_cmp_lt_i32_e64 s[4:5], v165, v185
	s_nop 1
	v_cndmask_b32_e64 v165, v215, v165, s[4:5]
	v_lshlrev_b32_e32 v165, 2, v165
	ds_bpermute_b32 v185, v165, v184
	v_max_f32_e32 v184, v184, v184
	s_mov_b32 s4, 0x41000000
	s_waitcnt lgkmcnt(0)
	v_max_f32_e32 v185, v185, v185
	v_max_f32_e32 v198, v184, v185
	v_fma_f32 v184, v198, s0, -v199
	v_cmp_ge_f32_e64 s[4:5], s4, v184
	s_cmp_eq_u64 s[4:5], exec
	s_cbranch_scc1 .LBB11_833
	v_mul_f32_e32 v184, 0x3e0293ee, v198
	v_max_f32_e32 v184, v184, v184
	v_max_f32_e32 v185, v199, v199
	v_max_f32_e32 v198, v185, v184
	v_sub_f32_e32 v184, v199, v198
	v_exp_f32_e32 v199, v184
	s_and_saveexec_b64 s[4:5], vcc
	ds_write_b32 v163, v199 offset:128
	s_or_b64 exec, exec, s[4:5]
	s_waitcnt lgkmcnt(0)
	v_add_u32_e32 v184, v162, v2
	ds_read_b128 v[200:203], v184 offset:128
	ds_read_b128 v[204:207], v184 offset:160
	ds_read_b128 v[220:223], v184 offset:192
	ds_read_b128 v[224:227], v184 offset:224
	v_mul_f32_e32 v166, v166, v199
	s_waitcnt lgkmcnt(3)
	v_mul_f32 v6, v6, v202
	v_mul_f32 v7, v7, v203
	s_waitcnt lgkmcnt(2)
	v_mul_f32 v8, v8, v204
	v_mul_f32 v9, v9, v205
	s_waitcnt lgkmcnt(1)
	v_mul_f32 v12, v12, v220
	v_mul_f32 v13, v13, v221
	s_waitcnt lgkmcnt(0)
	v_mul_f32 v16, v16, v224
	v_mul_f32 v17, v17, v225
	v_mul_f32 v18, v18, v226
	v_mul_f32 v19, v19, v227
	v_mul_f32 v14, v14, v222
	v_mul_f32 v15, v15, v223
	v_mul_f32 v10, v10, v206
	v_mul_f32 v11, v11, v207
	v_mul_f32 v4, v4, v200
	v_mul_f32 v5, v5, v201
	v_mul_f32 v64, v64, v224
	v_mul_f32 v65, v65, v225
	v_mul_f32 v60, v60, v220
	v_mul_f32 v61, v61, v221
	v_mul_f32 v56, v56, v204
	v_mul_f32 v57, v57, v205
	v_mul_f32 v66, v66, v226
	v_mul_f32 v67, v67, v227
	v_mul_f32 v62, v62, v222
	v_mul_f32 v63, v63, v223
	v_mul_f32 v58, v58, v206
	v_mul_f32 v59, v59, v207
	v_mul_f32 v54, v54, v202
	v_mul_f32 v55, v55, v203
	v_mul_f32 v52, v52, v200
	v_mul_f32 v53, v53, v201
	v_mul_f32 v48, v48, v224
	v_mul_f32 v49, v49, v225
	v_mul_f32 v44, v44, v220
	v_mul_f32 v45, v45, v221
	v_mul_f32 v40, v40, v204
	v_mul_f32 v41, v41, v205
	v_mul_f32 v50, v50, v226
	v_mul_f32 v51, v51, v227
	v_mul_f32 v46, v46, v222
	v_mul_f32 v47, v47, v223
	v_mul_f32 v42, v42, v206
	v_mul_f32 v43, v43, v207
	v_mul_f32 v38, v38, v202
	v_mul_f32 v39, v39, v203
	v_mul_f32 v36, v36, v200
	v_mul_f32 v37, v37, v201
	v_mul_f32 v32, v32, v224
	v_mul_f32 v33, v33, v225
	v_mul_f32 v28, v28, v220
	v_mul_f32 v29, v29, v221
	v_mul_f32 v24, v24, v204
	v_mul_f32 v25, v25, v205
	v_mul_f32 v34, v34, v226
	v_mul_f32 v35, v35, v227
	v_mul_f32 v30, v30, v222
	v_mul_f32 v31, v31, v223
	v_mul_f32 v26, v26, v206
	v_mul_f32 v27, v27, v207
	v_mul_f32 v22, v22, v202
	v_mul_f32 v23, v23, v203
	v_mul_f32 v20, v20, v200
	v_mul_f32 v21, v21, v201
	s_branch .LBB11_834

; template <int MODE>
; DEVI void attn_unit(LAS unsigned char* lds, const bf16_t* Qw, int ldq, const bf16_t* Kb, const bf16_t* Vb, int ldk, bf16_t* Ow, int ldo,
;                     int j_first, int ntiles, int jstep, int wj_lo, int wj_hi, int t0) {
;     ...
;                 } else { const float nmn = -mn;
; #pragma unroll
;                     for (int r = 0; r < 16; ++r) { p0[r] = __builtin_amdgcn_exp2f(fmaf(p0[r], C2, nmn)); p1[r] = __builtin_amdgcn_exp2f(fmaf(p1[r], C2, nmn)); }
;                 }
;                 if constexpr (MODE == M_DSA) {
;                     const u64 mw = maskl[r32 * 32 + j]; const int mlo = (int)(unsigned)(mw >> (4 * hi)), mhi = (int)(unsigned)(mw >> (32 + 4 * hi));
; #pragma unroll
;                     for (int r = 0; r < 16; ++r) { const int kbit = (r & 3) + 8 * (r >> 2);
;                         unsigned ma, mb; asm("v_bfe_i32 %0, %1, %2, 1" : "=v"(ma) : "v"(mlo), "n"(kbit)); asm("v_bfe_i32 %0, %1, %2, 1" : "=v"(mb) : "v"(mhi), "n"(kbit));
;                         p0[r] = __uint_as_float(__float_as_uint(p0[r]) & ma); p1[r] = __uint_as_float(__float_as_uint(p1[r]) & mb); }
;                 }
;                 float ps = 0.f;
; #pragma unroll
;                 for (int r = 0; r < 16; ++r) ps += p0[r] + p1[r];
;                 l_reg += ps;
;                 pack_p(p0, p1, pa0, pa1, pa2, pa3);
;             }
;             pv_d0(o, vb0 + buf * SHM_V, pa0, pa1, pa2, pa3);
.LBB11_834:
	v_fma_f32 v68, v68, s0, -v198
	v_exp_f32_e32 v184, v68
	v_fma_f32 v68, v84, s0, -v198
	v_exp_f32_e32 v185, v68
	v_fma_f32 v68, v69, s0, -v198
	v_exp_f32_e32 v186, v68
	v_fma_f32 v68, v85, s0, -v198
	v_exp_f32_e32 v187, v68
	v_fma_f32 v68, v70, s0, -v198
	v_exp_f32_e32 v196, v68
	v_fma_f32 v68, v86, s0, -v198
	v_exp_f32_e32 v197, v68
	v_fma_f32 v68, v71, s0, -v198
	v_exp_f32_e32 v199, v68
	v_fma_f32 v68, v87, s0, -v198
	v_exp_f32_e32 v200, v68
	v_fma_f32 v68, v72, s0, -v198
	v_exp_f32_e32 v201, v68
	v_fma_f32 v68, v88, s0, -v198
	v_exp_f32_e32 v202, v68
	v_fma_f32 v68, v73, s0, -v198
	v_exp_f32_e32 v70, v68
	v_fma_f32 v68, v89, s0, -v198
	v_exp_f32_e32 v84, v68
	v_fma_f32 v68, v74, s0, -v198
	v_exp_f32_e32 v203, v68
	v_fma_f32 v68, v90, s0, -v198
	v_exp_f32_e32 v204, v68
	v_fma_f32 v68, v75, s0, -v198
	v_exp_f32_e32 v72, v68
	v_fma_f32 v68, v91, s0, -v198
	v_exp_f32_e32 v86, v68
	v_fma_f32 v68, v76, s0, -v198
	v_exp_f32_e32 v205, v68
	v_fma_f32 v68, v92, s0, -v198
	v_exp_f32_e32 v206, v68
	v_fma_f32 v68, v77, s0, -v198
	v_exp_f32_e32 v74, v68
	v_fma_f32 v68, v93, s0, -v198
	v_exp_f32_e32 v88, v68
	v_fma_f32 v68, v78, s0, -v198
	v_exp_f32_e32 v207, v68
	v_fma_f32 v68, v94, s0, -v198
	v_exp_f32_e32 v208, v68
	v_fma_f32 v68, v79, s0, -v198
	v_exp_f32_e32 v76, v68
	v_fma_f32 v68, v95, s0, -v198
	v_exp_f32_e32 v90, v68
	v_fma_f32 v68, v80, s0, -v198
	v_exp_f32_e32 v212, v68
	v_fma_f32 v68, v96, s0, -v198
	v_exp_f32_e32 v96, v68
	v_fma_f32 v68, v81, s0, -v198
	v_exp_f32_e32 v78, v68
	v_fma_f32 v68, v97, s0, -v198
	v_exp_f32_e32 v92, v68
	v_fma_f32 v68, v82, s0, -v198
	v_exp_f32_e32 v82, v68
	v_fma_f32 v68, v98, s0, -v198
	v_exp_f32_e32 v97, v68
	v_fma_f32 v68, v83, s0, -v198
	v_exp_f32_e32 v80, v68
	v_fma_f32 v68, v99, s0, -v198
	v_exp_f32_e32 v94, v68
	v_add_f32_e32 v68, v184, v185
	v_add_f32_e32 v68, 0, v68
	v_add_f32_e32 v69, v186, v187
	v_add_f32_e32 v68, v69, v68
	v_add_f32_e32 v69, v196, v197
	v_add_f32_e32 v68, v69, v68
	v_add_f32_e32 v69, v199, v200
	v_add_f32_e32 v85, v69, v68
	v_add_f32_e32 v71, v201, v202
	v_add_f32 v68, v70, v84
	v_add_f32 v69, v71, v85
	v_add_f32_e32 v73, v203, v204
	v_add_f32 v69, v68, v69
	v_add_f32 v68, v68, v68
	v_mov_b32_e32 v87, v69
	v_add_f32 v68, v72, v86
	v_add_f32 v69, v73, v87
	v_add_f32_e32 v75, v205, v206
	v_add_f32 v69, v68, v69
	v_add_f32 v68, v68, v68
	v_mov_b32_e32 v89, v69
	v_add_f32 v68, v74, v88
	v_add_f32 v69, v75, v89
	v_add_f32_e32 v77, v207, v208
	v_add_f32 v69, v68, v69
	v_add_f32 v68, v68, v68
	v_mov_b32_e32 v91, v69
	v_add_f32 v68, v76, v90
	v_add_f32 v69, v77, v91
	v_add_f32_e32 v79, v212, v96
	v_add_f32 v69, v68, v69
	v_add_f32 v68, v68, v68
	v_mov_b32_e32 v93, v69
	v_add_f32 v68, v78, v92
	v_add_f32 v69, v79, v93
	v_add_f32_e32 v81, v82, v97
	v_add_f32 v69, v68, v69
	v_add_f32 v68, v68, v68
	v_mov_b32_e32 v95, v69
	v_add_f32 v68, v80, v94
	v_add_f32 v69, v81, v95
	s_nop 0
	v_add_f32_e32 v68, v68, v69
	v_add_f32_e32 v166, v166, v68
	v_cvt_pk_bf16_f32 v68, v184, v186
	v_cvt_pk_bf16_f32 v69, v196, v199
	v_cvt_pk_bf16_f32 v70, v201, v70
	v_cvt_pk_bf16_f32 v71, v203, v72
	v_cvt_pk_bf16_f32 v72, v205, v74
	v_cvt_pk_bf16_f32 v73, v207, v76
	v_cvt_pk_bf16_f32 v74, v212, v78
	v_cvt_pk_bf16_f32 v75, v82, v80
	v_cvt_pk_bf16_f32 v76, v185, v187
	v_cvt_pk_bf16_f32 v77, v197, v200
	v_cvt_pk_bf16_f32 v78, v202, v84
	v_cvt_pk_bf16_f32 v79, v204, v86
	v_cvt_pk_bf16_f32 v80, v206, v88
	v_cvt_pk_bf16_f32 v81, v208, v90
	v_cvt_pk_bf16_f32 v82, v96, v92
	v_cvt_pk_bf16_f32 v83, v97, v94
	v_add_u32_e32 v184, s11, v164
	ds_read_b64_tr_b16 v[84:85], v184 offset:0
	ds_read_b64_tr_b16 v[86:87], v184 offset:0x800
	ds_read_b64_tr_b16 v[88:89], v184 offset:0x1000
	ds_read_b64_tr_b16 v[90:91], v184 offset:0x1800
	ds_read_b64_tr_b16 v[92:93], v184 offset:0x2000
	ds_read_b64_tr_b16 v[94:95], v184 offset:0x2800
	ds_read_b64_tr_b16 v[96:97], v184 offset:0x3000
	ds_read_b64_tr_b16 v[98:99], v184 offset:0x3800
	s_waitcnt lgkmcnt(0)
	v_permlane32_swap_b32_e32 v68, v70
	v_permlane32_swap_b32_e32 v69, v71
	v_permlane32_swap_b32_e32 v72, v74
	v_permlane32_swap_b32_e32 v73, v75
	v_permlane32_swap_b32_e32 v76, v78
	v_permlane32_swap_b32_e32 v77, v79
	v_permlane32_swap_b32_e32 v80, v82
	v_permlane32_swap_b32_e32 v81, v83
	v_mfma_f32_32x32x16_bf16 v[4:19], v[68:71], v[84:87], v[4:19]
	ds_read_b64_tr_b16 v[84:85], v184 offset:0x200
	ds_read_b64_tr_b16 v[86:87], v184 offset:0xa00
	v_mfma_f32_32x32x16_bf16 v[4:19], v[72:75], v[88:91], v[4:19]
	ds_read_b64_tr_b16 v[88:89], v184 offset:0x1200
	ds_read_b64_tr_b16 v[90:91], v184 offset:0x1a00
	v_mfma_f32_32x32x16_bf16 v[4:19], v[76:79], v[92:95], v[4:19]
	ds_read_b64_tr_b16 v[92:93], v184 offset:0x2200
	ds_read_b64_tr_b16 v[94:95], v184 offset:0x2a00
	v_mfma_f32_32x32x16_bf16 v[4:19], v[80:83], v[96:99], v[4:19]
	ds_read_b64_tr_b16 v[96:97], v184 offset:0x3200
	ds_read_b64_tr_b16 v[98:99], v184 offset:0x3a00
	s_waitcnt lgkmcnt(0)
	v_mfma_f32_32x32x16_bf16 v[52:67], v[68:71], v[84:87], v[52:67]
	ds_read_b64_tr_b16 v[84:85], v184 offset:0x400
	ds_read_b64_tr_b16 v[86:87], v184 offset:0xc00
	v_mfma_f32_32x32x16_bf16 v[52:67], v[72:75], v[88:91], v[52:67]
	ds_read_b64_tr_b16 v[88:89], v184 offset:0x1400
	ds_read_b64_tr_b16 v[90:91], v184 offset:0x1c00
	v_mfma_f32_32x32x16_bf16 v[52:67], v[76:79], v[92:95], v[52:67]
	ds_read_b64_tr_b16 v[92:93], v184 offset:0x2400
	ds_read_b64_tr_b16 v[94:95], v184 offset:0x2c00
	v_mfma_f32_32x32x16_bf16 v[52:67], v[80:83], v[96:99], v[52:67]
	ds_read_b64_tr_b16 v[96:97], v184 offset:0x3400
	ds_read_b64_tr_b16 v[98:99], v184 offset:0x3c00
	s_waitcnt lgkmcnt(0)
	v_mfma_f32_32x32x16_bf16 v[36:51], v[68:71], v[84:87], v[36:51]
	ds_read_b64_tr_b16 v[84:85], v184 offset:0x600
	ds_read_b64_tr_b16 v[86:87], v184 offset:0xe00
	v_mfma_f32_32x32x16_bf16 v[36:51], v[72:75], v[88:91], v[36:51]
	ds_read_b64_tr_b16 v[88:89], v184 offset:0x1600
	ds_read_b64_tr_b16 v[90:91], v184 offset:0x1e00
	v_mfma_f32_32x32x16_bf16 v[36:51], v[76:79], v[92:95], v[36:51]
	ds_read_b64_tr_b16 v[92:93], v184 offset:0x2600
	ds_read_b64_tr_b16 v[94:95], v184 offset:0x2e00
	v_mfma_f32_32x32x16_bf16 v[36:51], v[80:83], v[96:99], v[36:51]
	ds_read_b64_tr_b16 v[96:97], v184 offset:0x3600
	ds_read_b64_tr_b16 v[98:99], v184 offset:0x3e00
	s_waitcnt lgkmcnt(0)
	v_mfma_f32_32x32x16_bf16 v[20:35], v[68:71], v[84:87], v[20:35]
	s_add_u32 s2, s2, 0x80000
	s_addc_u32 s3, s3, 0
	s_addk_i32 s10, 0x4000
	s_cmp_eq_u32 s2, 0x180000
	v_mfma_f32_32x32x16_bf16 v[20:35], v[72:75], v[88:91], v[20:35]
	v_mfma_f32_32x32x16_bf16 v[20:35], v[76:79], v[92:95], v[20:35]
	v_mfma_f32_32x32x16_bf16 v[20:35], v[80:83], v[96:99], v[20:35]
	s_cbranch_scc1 .LBB11_836
	v_mov_b32_e32 v199, v198
	s_branch .LBB11_829
; #define LAS __attribute__((address_space(3)))
; template <int MODE>
; DEVI void attn_unit(LAS unsigned char* lds, const bf16_t* Qw, int ldq, const bf16_t* Kb, const bf16_t* Vb, int ldk, bf16_t* Ow, int ldo,
;                     int j_first, int ntiles, int jstep, int wj_lo, int wj_hi, int t0) {
;     ...
;     for (int i = 0; i < ntiles; ++i, j += jstep) {
;         const int buf = i & 1;
;         FA_SWRITE(buf);
;         asm volatile("" ::: "memory");
;         if (i + 1 < ntiles) FA_SLOAD(j + jstep);
;         asm volatile("s_waitcnt lgkmcnt(0)" ::: "memory"); __builtin_amdgcn_s_barrier(); asm volatile("" ::: "memory");
;         if constexpr (MODE == M_STICK) {
;             if (i > 0) { const u32x4 f0 = *(LAS const u32x4*)(dflag + ((i - 1) & 1) * 8), f1 = *(LAS const u32x4*)(dflag + ((i - 1) & 1) * 8 + 4);
;                 if ((f0.x & f0.y & f0.z & f0.w & f1.x & f1.y & f1.z & f1.w) != 0u) break; }
;             if (lane == 0) dflag[(i & 1) * 8 + wid] = mydone ? 1u : 0u;
;         }
;         if (j >= wj_lo && j <= wj_hi && !mydone) {
;             f32x16 p0, p1;
;             if constexpr (MODE == M_STICK) {
;                 int qz_ = 0; asm volatile("" : "+v"(qz_)); const bf16_t* qp2 = qp + qz_;
; #pragma unroll
;                 for (int d0 = 0; d0 < 8; ++d0) qr[d0] = *(const bf16x8*)(qp2 + d0 * 16); }
;             qkt(p0, p1, K_lds + buf * SHM_K, qr, r32, hi);
;             bf16x8 pa0, pa1, pa2, pa3;
;             if constexpr (MODE == M_STICK) {
;                 const int tq = t0 + r32; const bool diag = (64 * j + 63 >= t0);
;                 stick_half(p1, carry, diag, 64 * j + 32 + 4 * hi, tq, hi);
;                 stick_half(p0, carry, diag, 64 * j + 4 * hi, tq, hi);
;                 if (__all(carry < -152.f)) { mydone = true; if (lane == 0) dflag[(i & 1) * 8 + wid] = 1u; }
;                 pack_p(p0, p1, pa0, pa1, pa2, pa3);
;             } else {
;                 if constexpr (MODE == M_BAND) {
;                     const int cw = t0 >> 6;
;                     if (j <= cw - 3) { const float bc = bias2[191];
; #pragma unroll
;                         for (int r = 0; r < 16; ++r) { p0[r] = fmaf(p0[r], C2, bc); p1[r] = fmaf(p1[r], C2, bc); }
;                     } else { const int d0 = (t0 + r32) - (64 * j + 4 * hi) + 63;
; #pragma unroll
.LBB11_836:
	v_add3_u32 v68, v183, v173, v174
	s_waitcnt vmcnt(3)
	ds_write_b128 v68, v[136:139] offset:16384
	v_add3_u32 v68, v183, v178, v174
	s_waitcnt vmcnt(1)
	ds_write_b128 v68, v[144:147] offset:16384
	v_add3_u32 v68, 0, v176, v177
	ds_write_b128 v68, v[132:135] offset:49152
	v_add3_u32 v68, 0, v179, v177
	s_waitcnt vmcnt(0)
	ds_write_b128 v68, v[140:143] offset:49152
	v_add_u32_e32 v136, 0, v180
	s_waitcnt lgkmcnt(0)
	s_barrier
	v_add_u32_e32 v72, v136, v181
	ds_read_b128 v[68:71], v72 offset:49152
	ds_read_b128 v[72:75], v72 offset:57344
	s_waitcnt lgkmcnt(1)
	v_mfma_f32_32x32x16_bf16 v[84:99], v[68:71], v[128:131], 0
	v_add_u32_e32 v132, v136, v175
	s_mov_b32 s2, 0x41000000
	s_waitcnt lgkmcnt(0)
	v_mfma_f32_32x32x16_bf16 v[68:83], v[72:75], v[128:131], 0
	ds_read_b128 v[128:131], v132 offset:49152
	ds_read_b128 v[132:135], v132 offset:57344
	s_waitcnt lgkmcnt(1)
	v_mfma_f32_32x32x16_bf16 v[84:99], v[128:131], v[124:127], v[84:99]
	v_add_u32_e32 v128, v136, v172
	s_waitcnt lgkmcnt(0)
	v_mfma_f32_32x32x16_bf16 v[68:83], v[132:135], v[124:127], v[68:83]
	ds_read_b128 v[124:127], v128 offset:49152
	ds_read_b128 v[128:131], v128 offset:57344
	s_waitcnt lgkmcnt(1)
	v_mfma_f32_32x32x16_bf16 v[84:99], v[124:127], v[120:123], v[84:99]
	v_add_u32_e32 v124, v136, v171
	s_waitcnt lgkmcnt(0)
	v_mfma_f32_32x32x16_bf16 v[68:83], v[128:131], v[120:123], v[68:83]
	ds_read_b128 v[120:123], v124 offset:49152
	ds_read_b128 v[124:127], v124 offset:57344
	s_waitcnt lgkmcnt(1)
	v_mfma_f32_32x32x16_bf16 v[84:99], v[120:123], v[116:119], v[84:99]
	v_add_u32_e32 v120, v136, v170
	s_waitcnt lgkmcnt(0)
	v_mfma_f32_32x32x16_bf16 v[68:83], v[124:127], v[116:119], v[68:83]
	ds_read_b128 v[116:119], v120 offset:49152
	ds_read_b128 v[120:123], v120 offset:57344
	s_waitcnt lgkmcnt(1)
	v_mfma_f32_32x32x16_bf16 v[84:99], v[116:119], v[112:115], v[84:99]
	v_add_u32_e32 v116, v136, v169
	s_waitcnt lgkmcnt(0)
	v_mfma_f32_32x32x16_bf16 v[68:83], v[120:123], v[112:115], v[68:83]
	ds_read_b128 v[112:115], v116 offset:49152
	ds_read_b128 v[116:119], v116 offset:57344
	s_waitcnt lgkmcnt(1)
	v_mfma_f32_32x32x16_bf16 v[84:99], v[112:115], v[108:111], v[84:99]
	v_add_u32_e32 v112, v136, v168
	s_waitcnt lgkmcnt(0)
	v_mfma_f32_32x32x16_bf16 v[68:83], v[116:119], v[108:111], v[68:83]
	ds_read_b128 v[108:111], v112 offset:49152
	ds_read_b128 v[112:115], v112 offset:57344
	s_waitcnt lgkmcnt(1)
	v_mfma_f32_32x32x16_bf16 v[84:99], v[108:111], v[104:107], v[84:99]
	v_add_u32_e32 v108, v136, v167
	s_waitcnt lgkmcnt(0)
	v_mfma_f32_32x32x16_bf16 v[68:83], v[112:115], v[104:107], v[68:83]
	ds_read_b128 v[104:107], v108 offset:57344
	ds_read_b128 v[108:111], v108 offset:49152
	s_waitcnt lgkmcnt(1)
	v_mfma_f32_32x32x16_bf16 v[68:83], v[104:107], v[100:103], v[68:83]
	s_waitcnt lgkmcnt(0)
	v_mfma_f32_32x32x16_bf16 v[84:99], v[108:111], v[100:103], v[84:99]
	s_nop 9
	v_max_f32_e32 v104, v68, v68
	s_nop 0
	v_max_f32_e32 v100, v84, v84
	v_max_f32_e32 v100, v100, v104
	v_max3_f32 v100, v100, v85, v86
	s_nop 0
	v_max3_f32 v100, v100, v87, v88
	s_nop 0
	v_max3_f32 v100, v100, v89, v90
	s_nop 0
	v_max3_f32 v100, v100, v91, v92
	s_nop 0
	v_max3_f32 v100, v100, v93, v94
	s_nop 0
	v_max3_f32 v100, v100, v95, v96
	s_nop 0
	v_max3_f32 v100, v100, v97, v98
	s_nop 0
	v_max3_f32 v100, v100, v69, v70
	s_nop 0
	v_max3_f32 v100, v100, v71, v72
	s_nop 0
	v_max3_f32 v100, v100, v73, v74
	s_nop 0
	v_max3_f32 v100, v100, v75, v76
	s_nop 0
	v_max3_f32 v100, v100, v77, v78
	s_nop 0
	v_max3_f32 v100, v100, v79, v80
	s_nop 0
	v_max3_f32 v100, v100, v81, v82
	s_nop 0
	v_max3_f32 v100, v100, v99, v83
	ds_bpermute_b32 v101, v165, v100
	v_max_f32_e32 v100, v100, v100
	s_waitcnt lgkmcnt(0)
	v_max_f32_e32 v101, v101, v101
	v_max_f32_e32 v100, v100, v101
	v_fma_f32 v101, v100, s0, -v198
	v_cmp_ge_f32_e64 s[4:5], s2, v101
	s_cmp_eq_u64 s[4:5], exec
	s_cbranch_scc1 .LBB11_840
	v_mul_f32_e32 v100, 0x3e0293ee, v100
	v_max_f32_e32 v100, v100, v100
	v_max_f32_e32 v101, v198, v198
	v_max_f32_e32 v100, v101, v100
	v_sub_f32_e32 v101, v198, v100
	v_exp_f32_e32 v101, v101
	s_and_saveexec_b64 s[2:3], vcc
	ds_write_b32 v163, v101 offset:128
	s_or_b64 exec, exec, s[2:3]
	v_mul_f32_e32 v166, v166, v101
	s_waitcnt lgkmcnt(0)
	v_add_u32_e32 v101, v162, v2
	ds_read_b128 v[102:105], v101 offset:128
	ds_read_b128 v[106:109], v101 offset:160
	ds_read_b128 v[110:113], v101 offset:192
	ds_read_b128 v[114:117], v101 offset:224
	v_xor_b32_e32 v100, 0x80000000, v100
	s_waitcnt lgkmcnt(3)
	v_mul_f32 v6, v6, v104
	v_mul_f32 v7, v7, v105
	s_waitcnt lgkmcnt(2)
	v_mul_f32 v8, v8, v106
	v_mul_f32 v9, v9, v107
	s_waitcnt lgkmcnt(1)
	v_mul_f32 v12, v12, v110
	v_mul_f32 v13, v13, v111
	s_waitcnt lgkmcnt(0)
	v_mul_f32 v16, v16, v114
	v_mul_f32 v17, v17, v115
	v_mul_f32 v18, v18, v116
	v_mul_f32 v19, v19, v117
	v_mul_f32 v14, v14, v112
	v_mul_f32 v15, v15, v113
	v_mul_f32 v10, v10, v108
	v_mul_f32 v11, v11, v109
	v_mul_f32 v4, v4, v102
	v_mul_f32 v5, v5, v103
	v_mul_f32 v64, v64, v114
	v_mul_f32 v65, v65, v115
	v_mul_f32 v60, v60, v110
	v_mul_f32 v61, v61, v111
	v_mul_f32 v56, v56, v106
	v_mul_f32 v57, v57, v107
	v_mul_f32 v66, v66, v116
	v_mul_f32 v67, v67, v117
	v_mul_f32 v62, v62, v112
	v_mul_f32 v63, v63, v113
	v_mul_f32 v58, v58, v108
	v_mul_f32 v59, v59, v109
	v_mul_f32 v54, v54, v104
	v_mul_f32 v55, v55, v105
	v_mul_f32 v52, v52, v102
	v_mul_f32 v53, v53, v103
	v_mul_f32 v48, v48, v114
	v_mul_f32 v49, v49, v115
	v_mul_f32 v44, v44, v110
	v_mul_f32 v45, v45, v111
	v_mul_f32 v40, v40, v106
	v_mul_f32 v41, v41, v107
	v_mul_f32 v50, v50, v116
	v_mul_f32 v51, v51, v117
	v_mul_f32 v46, v46, v112
	v_mul_f32 v47, v47, v113
	v_mul_f32 v42, v42, v108
	v_mul_f32 v43, v43, v109
	v_mul_f32 v38, v38, v104
	v_mul_f32 v39, v39, v105
	v_mul_f32 v36, v36, v102
	v_mul_f32 v37, v37, v103
	v_mul_f32 v32, v32, v114
	v_mul_f32 v33, v33, v115
	v_mul_f32 v28, v28, v110
	v_mul_f32 v29, v29, v111
	v_mul_f32 v24, v24, v106
	v_mul_f32 v25, v25, v107
	v_mul_f32 v34, v34, v116
	v_mul_f32 v35, v35, v117
	v_mul_f32 v30, v30, v112
	v_mul_f32 v31, v31, v113
	v_mul_f32 v26, v26, v108
	v_mul_f32 v27, v27, v109
	v_mul_f32 v22, v22, v104
	v_mul_f32 v23, v23, v105
	v_mul_f32 v20, v20, v102
	v_mul_f32 v21, v21, v103
	s_branch .LBB11_841

; #define LAS __attribute__((address_space(3)))
; DEVI int otid() { int t = threadIdx.x; asm volatile("" : "+v"(t)); return t; }
; DEVI int v_st(int k, int c) { const int kk = (k & ~0xC) | ((k & 4) << 1) | ((k & 8) >> 1); return ((kk >> 3) * 4 + (c >> 5)) * 512 + ((kk & 7) * 32 + (c & 31)) * 2; }
; DEVI int v_rd_base(int lane) { return ((lane & 3) << 3) | (((lane >> 2) & 3) << 6) | (((lane >> 4) & 1) << 5) | (((lane >> 5) & 1) << 8); }
; template <int MODE>
; DEVI void attn_unit(LAS unsigned char* lds, const bf16_t* Qw, int ldq, const bf16_t* Kb, const bf16_t* Vb, int ldk, bf16_t* Ow, int ldo,
;                     int j_first, int ntiles, int jstep, int wj_lo, int wj_hi, int t0) {
;     const int tid = otid(), wid = tid >> 6, lane = tid & 63, r32 = lane & 31, hi = lane >> 5;
;     LAS unsigned char* V_lds = lds + OFF_V; LAS unsigned char* K_lds = lds + OFF_K;
;     LAS float* wsx = (LAS float*)(lds + OFF_WS) + wid * 64; LAS float* li_l = wsx; LAS float* al_l = wsx + 32;
;     LAS const float* bias2 = (LAS const float*)(lds + OFF_BIAS); LAS const u64* maskl = (LAS const u64*)(lds + OFF_MASK);
;     if (wid >= 4) __builtin_amdgcn_s_setprio(1);
;     float m_reg = -1e30f, l_reg = 0.f, carry = 0.f; bool mydone = false;
;     LAS unsigned* dflag = (LAS unsigned*)(lds + OFF_BIAS + 1024);
;     f32x16 o[4];
; #pragma unroll
;     for (int d = 0; d < 4; ++d) o[d] = (f32x16){0.f, 0.f, 0.f, 0.f, 0.f, 0.f, 0.f, 0.f, 0.f, 0.f, 0.f, 0.f, 0.f, 0.f, 0.f, 0.f};
;     bf16x8 qr[8];
;     const bf16_t* qp = Qw + (size_t)r32 * ldq + hi * 8;
;     if constexpr (MODE != M_STICK) {
; #pragma unroll
;       for (int d0 = 0; d0 < 8; ++d0) qr[d0] = *(const bf16x8*)(qp + d0 * 16); }
;     const int sr = tid >> 4, sc = (tid & 15) * 8, vst0 = v_st(sr, sc), vst1 = v_st(32 + sr, sc);
;     const int kst0 = FA_KSWZ(sr, sc * 2), kst1 = FA_KSWZ(32 + sr, sc * 2);
;     const int vb0 = (int)(uintptr_t)V_lds + v_rd_base(lane);
;     bf16x8 vs0, vs1, ks0, ks1;
;     ...
;     int j = j_first;
;     FA_SLOAD(j);
;     for (int i = 0; i < ntiles; ++i, j += jstep) {
;         const int buf = i & 1;
;         FA_SWRITE(buf);
;         asm volatile("" ::: "memory");
;         if (i + 1 < ntiles) FA_SLOAD(j + jstep);
;         asm volatile("s_waitcnt lgkmcnt(0)" ::: "memory"); __builtin_amdgcn_s_barrier(); asm volatile("" ::: "memory");
.LBB11_981:
	v_mov_b32_e32 v70, v0
	s_nop 0
	v_ashrrev_i32_e32 v1, 6, v70
	v_cmp_lt_i32_e32 vcc, 3, v1
	s_and_saveexec_b64 s[4:5], vcc
	s_setprio 1
	s_or_b64 exec, exec, s[4:5]
	s_and_b64 s[4:5], s[18:19], exec
	v_readlane_b32 s1, v253, 36
	v_readlane_b32 s4, v253, 40
	s_cselect_b32 s1, s4, s1
	s_lshl_b32 s29, s1, 2
	s_or_b32 s22, s29, 3
	v_ashrrev_i32_e32 v68, 4, v70
	s_lshl_b32 s30, s22, 6
	v_ashrrev_i32_e32 v69, 31, v68
	v_lshlrev_b32_e32 v22, 3, v70
	v_lshl_add_u64 v[12:13], s[30:31], 0, v[68:69]
	s_movk_i32 s6, 0x3000
	v_and_b32_e32 v2, 0x78, v22
	v_lshl_add_u64 v[20:21], v[68:69], 0, 32
	v_mad_u64_u32 v[16:17], s[4:5], v12, s6, v[124:125]
	v_lshlrev_b32_e32 v2, 1, v2
	v_mad_u64_u32 v[4:5], s[4:5], v12, s6, v[126:127]
	v_lshl_add_u64 v[14:15], v[20:21], 0, s[30:31]
	v_mad_i32_i24 v17, v13, s6, v17
	v_mad_i32_i24 v5, v13, s6, v5
	v_mad_u64_u32 v[6:7], s[4:5], v14, s6, v[126:127]
	v_lshl_add_u64 v[12:13], v[16:17], 0, v[2:3]
	v_mad_u64_u32 v[16:17], s[4:5], v14, s6, v[124:125]
	v_mad_i32_i24 v7, v15, s6, v7
	v_mad_i32_i24 v17, v15, s6, v17
	v_lshl_add_u64 v[4:5], v[4:5], 0, v[2:3]
	v_lshl_add_u64 v[8:9], v[6:7], 0, v[2:3]
	v_lshl_add_u64 v[16:17], v[16:17], 0, v[2:3]
	global_load_dwordx4 v[4:7], v[4:5], off
	s_nop 0
	global_load_dwordx4 v[8:11], v[8:9], off
	s_nop 0
	global_load_dwordx4 v[12:15], v[12:13], off
	s_nop 0
	global_load_dwordx4 v[16:19], v[16:17], off
	v_and_b32_e32 v21, 0xfffff0, v68
	v_lshlrev_b32_e32 v23, 1, v68
	v_lshrrev_b32_e32 v24, 1, v68
	v_bfe_u32 v26, v22, 5, 2
	v_and_b32_e32 v22, 3, v68
	v_add_u32_e32 v25, 32, v68
	v_and_or_b32 v21, v23, 8, v21
	v_and_or_b32 v27, v24, 4, v22
	v_and_b32_e32 v22, 0xfffff0, v25
	v_lshlrev_b32_e32 v23, 1, v25
	v_lshrrev_b32_e32 v21, 1, v21
	v_and_or_b32 v28, v23, 8, v22
	s_movk_i32 s4, 0x70
	s_lshl_b32 s23, s1, 8
	v_lshlrev_b32_e32 v157, 8, v25
	v_and_b32_e32 v158, 48, v2
	v_bitop3_b32 v159, v2, v70, s4 bitop3:0x78
	v_lshl_add_u64 v[22:23], v[126:127], 0, v[2:3]
	v_lshl_add_u64 v[24:25], v[124:125], 0, v[2:3]
	v_or_b32_e32 v2, v21, v26
	v_lshrrev_b32_e32 v21, 1, v28
	v_lshl_add_u32 v160, v27, 6, 0
	s_or_b32 s4, s23, 0x80
	v_lshlrev_b32_e32 v161, 9, v2
	v_or_b32_e32 v2, v21, v26
	v_lshlrev_b32_e32 v156, 8, v68
	v_add_u32_e32 v27, s4, v68
	v_add_u32_e32 v30, s4, v20
	v_lshlrev_b32_e32 v162, 9, v2
	v_add3_u32 v2, v160, v161, v158
	v_add3_u32 v28, 0, v156, v159
	v_add3_u32 v29, 0, v157, v159
	v_mad_i64_i32 v[20:21], s[4:5], v27, s6, v[22:23]
	v_mad_i64_i32 v[22:23], s[4:5], v30, s6, v[22:23]
	v_mad_i64_i32 v[26:27], s[4:5], v27, s6, v[24:25]
	v_mad_i64_i32 v[24:25], s[4:5], v30, s6, v[24:25]
	v_add3_u32 v30, v160, v162, v158
	v_readlane_b32 s4, v252, 12
	s_waitcnt vmcnt(0)
	ds_write_b128 v2, v[4:7]
	ds_write_b128 v30, v[8:11]
	ds_write_b128 v28, v[12:15] offset:32768
	ds_write_b128 v29, v[16:19] offset:32768
	global_load_dwordx4 v[100:103], v[20:21], off
	global_load_dwordx4 v[104:107], v[22:23], off
	global_load_dwordx4 v[108:111], v[26:27], off
	global_load_dwordx4 v[112:115], v[24:25], off
	s_waitcnt lgkmcnt(0)
	s_barrier
	v_and_b32_e32 v4, 63, v70
	v_lshl_add_u32 v163, v1, 2, s4
	v_cmp_ne_u32_e64 s[38:39], 0, v4
	v_cmp_eq_u32_e64 s[40:41], 0, v4
	s_and_saveexec_b64 s[4:5], s[40:41]
	ds_write_b32 v163, v3
	s_or_b64 exec, exec, s[4:5]
	v_add_u32_e32 v165, s23, v137
	v_add_u32_e32 v132, s28, v165
	v_mad_i64_i32 v[6:7], s[4:5], v132, s6, v[122:123]
	v_and_b32_e32 v164, 31, v70
	v_lshrrev_b32_e32 v166, 5, v4
	v_mad_u64_u32 v[6:7], s[4:5], v164, s6, v[6:7]
	v_lshlrev_b32_e32 v2, 4, v166
	v_lshl_add_u64 v[134:135], v[6:7], 0, v[2:3]
	v_lshlrev_b32_e32 v6, 1, v4
	v_lshlrev_b32_e32 v1, 3, v4
	v_and_b32_e32 v6, 32, v6
	s_movk_i32 s4, 0x118
	v_and_or_b32 v6, v1, s4, v6
	v_lshlrev_b32_e32 v1, 4, v70
	s_movk_i32 s4, 0x70
	v_and_b32_e32 v7, 0x70, v1
	v_bitop3_b32 v168, v2, v1, s4 bitop3:0x78
	s_movk_i32 s4, 0x60
	v_bitop3_b32 v171, v2, v7, s4 bitop3:0x36
	s_movk_i32 s4, 0x80
	v_bitop3_b32 v172, v2, v7, s4 bitop3:0x36
	s_movk_i32 s4, 0xa0
	v_lshlrev_b32_e32 v5, 4, v4
	v_bitop3_b32 v173, v2, v7, s4 bitop3:0x36
	s_movk_i32 s4, 0xc0
	v_and_b32_e32 v5, 0xc0, v5
	v_bitop3_b32 v174, v2, v7, s4 bitop3:0x36
	s_movk_i32 s4, 0xe0
	v_or_b32_e32 v136, v165, v164
	v_ashrrev_i32_e32 v178, 6, v165
	v_lshlrev_b32_e32 v167, 8, v164
	v_bitop3_b32 v169, v2, v7, 32 bitop3:0x36
	v_bitop3_b32 v170, v2, v7, 64 bitop3:0x36
	v_bitop3_b32 v175, v2, v7, s4 bitop3:0x36
	v_lshlrev_b32_e32 v176, 2, v166
	v_subrev_u32_e32 v1, 32, v136
	v_cmp_gt_u32_e64 s[42:43], 32, v4
	v_add3_u32 v177, v5, 0, v6
	v_cmp_le_i32_e32 vcc, s22, v178
	s_and_saveexec_b64 s[4:5], vcc
	s_xor_b64 s[16:17], exec, s[4:5]
	s_cbranch_execz .LBB11_989
; #define LAS __attribute__((address_space(3)))
; DEVI void qkt(f32x16& p0, f32x16& p1, LAS const unsigned char* Ks, const bf16x8* qr, int r32, int hi) {
;     p0 = (f32x16){0.f, 0.f, 0.f, 0.f, 0.f, 0.f, 0.f, 0.f, 0.f, 0.f, 0.f, 0.f, 0.f, 0.f, 0.f, 0.f}; p1 = p0;
; #pragma unroll
;     for (int d0 = 0; d0 < 8; ++d0) { const int cb = (d0 * 16 + hi * 8) * 2;
;         const bf16x8 b0 = *(LAS const bf16x8*)(Ks + FA_KSWZ(r32, cb));
;         const bf16x8 b1 = *(LAS const bf16x8*)(Ks + FA_KSWZ(32 + r32, cb));
;         p0 = __builtin_amdgcn_mfma_f32_32x32x16_bf16(b0, qr[d0], p0, 0, 0, 0);
;         p1 = __builtin_amdgcn_mfma_f32_32x32x16_bf16(b1, qr[d0], p1, 0, 0, 0); }
; DEVI void stick_half(f32x16& x, float& carry, bool diag, int kv0, int tq, int hi) {
;     f32x16 lk; const int dq = diag ? tq - kv0 : 64;
; #pragma unroll
;     for (int r = 0; r < 16; ++r) {
;         float z = x[r] * C2;
;         float l = -(fmaxf(z, 0.f) + __builtin_amdgcn_logf(1.f + __builtin_amdgcn_exp2f(-fabsf(z))));
; template <int MODE>
; DEVI void attn_unit(LAS unsigned char* lds, const bf16_t* Qw, int ldq, const bf16_t* Kb, const bf16_t* Vb, int ldk, bf16_t* Ow, int ldo,
;                     int j_first, int ntiles, int jstep, int wj_lo, int wj_hi, int t0) {
;     ...
;         if (j >= wj_lo && j <= wj_hi && !mydone) {
;             f32x16 p0, p1;
;             if constexpr (MODE == M_STICK) {
;                 int qz_ = 0; asm volatile("" : "+v"(qz_)); const bf16_t* qp2 = qp + qz_;
; #pragma unroll
;                 for (int d0 = 0; d0 < 8; ++d0) qr[d0] = *(const bf16x8*)(qp2 + d0 * 16); }
;             qkt(p0, p1, K_lds + buf * SHM_K, qr, r32, hi);
;             bf16x8 pa0, pa1, pa2, pa3;
;             if constexpr (MODE == M_STICK) {
;                 const int tq = t0 + r32; const bool diag = (64 * j + 63 >= t0);
;                 stick_half(p1, carry, diag, 64 * j + 32 + 4 * hi, tq, hi);
;                 stick_half(p0, carry, diag, 64 * j + 4 * hi, tq, hi);
	v_mov_b32_e32 v4, v3
	v_add_u32_e32 v2, 0, v167
	v_ashrrev_i32_e32 v5, 31, v4
	v_lshl_add_u64 v[52:53], v[4:5], 1, v[134:135]
	global_load_dwordx4 v[20:23], v[52:53], off
	global_load_dwordx4 v[36:39], v[52:53], off offset:32
	v_add_u32_e32 v8, v2, v168
	ds_read_b128 v[4:7], v8 offset:32768
	ds_read_b128 v[24:27], v8 offset:40960
	global_load_dwordx4 v[40:43], v[52:53], off offset:64
	v_add_u32_e32 v48, v2, v169
	ds_read_b128 v[44:47], v48 offset:32768
	ds_read_b128 v[48:51], v48 offset:40960
	v_add_u32_e32 v54, v2, v170
	s_or_b32 s4, s30, 63
	s_mov_b32 s14, 0xc3180000
	s_waitcnt vmcnt(2) lgkmcnt(3)
	v_mfma_f32_32x32x16_bf16 v[4:19], v[4:7], v[20:23], 0
	s_waitcnt vmcnt(1) lgkmcnt(1)
	v_mfma_f32_32x32x16_bf16 v[4:19], v[44:47], v[36:39], v[4:19]
	global_load_dwordx4 v[44:47], v[52:53], off offset:96
	v_mfma_f32_32x32x16_bf16 v[20:35], v[24:27], v[20:23], 0
	s_waitcnt lgkmcnt(0)
	v_mfma_f32_32x32x16_bf16 v[20:35], v[48:51], v[36:39], v[20:35]
	ds_read_b128 v[36:39], v54 offset:32768
	ds_read_b128 v[48:51], v54 offset:40960
	v_add_u32_e32 v54, v2, v171
	s_waitcnt vmcnt(1) lgkmcnt(1)
	v_mfma_f32_32x32x16_bf16 v[4:19], v[36:39], v[40:43], v[4:19]
	global_load_dwordx4 v[36:39], v[52:53], off offset:128
	s_waitcnt lgkmcnt(0)
	v_mfma_f32_32x32x16_bf16 v[20:35], v[48:51], v[40:43], v[20:35]
	ds_read_b128 v[40:43], v54 offset:32768
	ds_read_b128 v[48:51], v54 offset:40960
	v_add_u32_e32 v54, v2, v172
	s_waitcnt vmcnt(1) lgkmcnt(1)
	v_mfma_f32_32x32x16_bf16 v[4:19], v[40:43], v[44:47], v[4:19]
	global_load_dwordx4 v[40:43], v[52:53], off offset:160
	s_waitcnt lgkmcnt(0)
	v_mfma_f32_32x32x16_bf16 v[20:35], v[48:51], v[44:47], v[20:35]
	ds_read_b128 v[44:47], v54 offset:32768
	ds_read_b128 v[48:51], v54 offset:40960
	v_add_u32_e32 v54, v2, v173
	s_waitcnt vmcnt(1) lgkmcnt(1)
	v_mfma_f32_32x32x16_bf16 v[4:19], v[44:47], v[36:39], v[4:19]
	global_load_dwordx4 v[44:47], v[52:53], off offset:192
	s_waitcnt lgkmcnt(0)
	v_mfma_f32_32x32x16_bf16 v[20:35], v[48:51], v[36:39], v[20:35]
	ds_read_b128 v[36:39], v54 offset:32768
	ds_read_b128 v[48:51], v54 offset:40960
	s_waitcnt vmcnt(1) lgkmcnt(1)
	v_mfma_f32_32x32x16_bf16 v[4:19], v[36:39], v[40:43], v[4:19]
	global_load_dwordx4 v[36:39], v[52:53], off offset:224
	v_add_u32_e32 v52, v2, v174
	v_add_u32_e32 v2, v2, v175
	s_waitcnt lgkmcnt(0)
	v_mfma_f32_32x32x16_bf16 v[20:35], v[48:51], v[40:43], v[20:35]
	ds_read_b128 v[40:43], v52 offset:32768
	ds_read_b128 v[48:51], v52 offset:40960
	s_waitcnt vmcnt(1) lgkmcnt(1)
	v_mfma_f32_32x32x16_bf16 v[4:19], v[40:43], v[44:47], v[4:19]
	ds_read_b128 v[40:43], v2 offset:32768
	s_waitcnt lgkmcnt(1)
	v_mfma_f32_32x32x16_bf16 v[20:35], v[48:51], v[44:47], v[20:35]
	ds_read_b128 v[44:47], v2 offset:40960
	v_or_b32_e32 v2, s30, v176
	s_waitcnt vmcnt(0) lgkmcnt(0)
	v_mfma_f32_32x32x16_bf16 v[20:35], v[44:47], v[36:39], v[20:35]
	s_nop 11
	v_mul_f32_e32 v45, 0x3e0293ee, v22
	v_mfma_f32_32x32x16_bf16 v[4:19], v[40:43], v[36:39], v[4:19]
	v_mul_f32_e32 v53, 0x3e0293ee, v30
	v_and_b32_e32 v41, 64, v215
	v_mul_f32_e32 v43, 0x3e0293ee, v20
	v_mul_f32_e32 v46, 0x3e0293ee, v23
	v_mul_f32_e32 v54, 0x3e0293ee, v31
	v_exp_f32_e64 v20, -|v45|
	v_exp_f32_e64 v37, -|v53|
	v_xor_b32_e32 v40, 32, v215
	v_add_u32_e32 v41, 64, v41
	v_exp_f32_e64 v22, -|v46|
	v_exp_f32_e64 v39, -|v54|
	v_cmp_lt_i32_e32 vcc, v40, v41
	v_mul_f32_e32 v51, 0x3e0293ee, v28
	v_mul_f32_e32 v52, 0x3e0293ee, v29
	v_cndmask_b32_e32 v40, v215, v40, vcc
	v_lshlrev_b32_e32 v94, 2, v40
	v_mul_f32_e32 v57, 0x3e0293ee, v34
	v_mul_f32_e32 v40, 0x3e0293ee, v4
	v_mul_f32_e32 v41, 0x3e0293ee, v5
	v_exp_f32_e64 v4, -|v43|
	v_exp_f32_e64 v34, -|v51|
	v_add_f32_e32 v20, 1.0, v20
	v_add_f32_e32 v76, 1.0, v37
	v_mul_f32_e32 v47, 0x3e0293ee, v24
	v_mul_f32_e32 v55, 0x3e0293ee, v32
	v_mul_f32_e32 v58, 0x3e0293ee, v35
	v_mul_f32_e32 v42, 0x3e0293ee, v6
	v_exp_f32_e64 v35, -|v52|
	v_exp_f32_e64 v73, -|v41|
	v_add_f32_e32 v22, 1.0, v22
	v_add_f32_e32 v77, 1.0, v39
	v_log_f32_e32 v39, v20
	v_log_f32_e32 v20, v76
	v_exp_f32_e64 v24, -|v47|
	v_exp_f32_e64 v61, -|v55|
	v_exp_f32_e64 v74, -|v42|
	v_log_f32_e32 v85, v22
	v_log_f32_e32 v22, v77
	v_mul_f32_e32 v44, 0x3e0293ee, v21
	v_exp_f32_e64 v6, -|v44|
	v_max_f32_e32 v38, 0, v53
	v_add_f32_e32 v4, 1.0, v4
	v_add_f32_e32 v34, 1.0, v34
	v_max_f32_e32 v59, 0, v54
	v_add_f32_e32 v75, 1.0, v35
	v_log_f32_e32 v35, v4
	v_log_f32_e32 v4, v34
	v_add_f32_e32 v76, v38, v20
	v_add_f32_e32 v20, 1.0, v73
	v_add_f32_e32 v24, 1.0, v24
	v_add_f32_e32 v61, 1.0, v61
	v_add_f32_e32 v78, v59, v22
	v_log_f32_e32 v20, v20
	v_add_f32_e32 v22, 1.0, v74
	v_mul_f32_e32 v59, 0x3e0293ee, v7
	v_mul_f32_e32 v48, 0x3e0293ee, v25
	v_mul_f32_e32 v56, 0x3e0293ee, v33
	v_log_f32_e32 v87, v24
	v_log_f32_e32 v24, v61
	v_log_f32_e32 v22, v22
	v_exp_f32_e64 v7, -|v59|
	v_mul_f32_e32 v49, 0x3e0293ee, v26
	v_exp_f32_e64 v26, -|v48|
	v_max_f32_e32 v32, 0, v51
	v_exp_f32_e64 v63, -|v56|
	v_exp_f32_e64 v72, -|v40|
	v_add_f32_e32 v6, 1.0, v6
	v_log_f32_e32 v37, v6
	v_log_f32_e32 v6, v75
	v_add_f32_e32 v75, v32, v4
	v_max_f32_e32 v4, 0, v41
	v_max_f32_e32 v60, 0, v55
	v_add_f32_e32 v98, v4, v20
	v_max_f32_e32 v4, 0, v42
	v_add_f32_e32 v80, v60, v24
	v_add_f32_e32 v99, v4, v22
	v_add_f32_e32 v4, 1.0, v7
	v_mul_f32_e32 v60, 0x3e0293ee, v8
	v_add_f32_e32 v26, 1.0, v26
	v_add_f32_e32 v63, 1.0, v63
	v_add_f32_e32 v72, 1.0, v72
	v_log_f32_e32 v4, v4
	v_exp_f32_e64 v7, -|v60|
	v_log_f32_e32 v89, v26
	v_log_f32_e32 v26, v63
	v_log_f32_e32 v34, v72
	v_exp_f32_e64 v28, -|v49|
	v_exp_f32_e64 v65, -|v57|
	v_max_f32_e32 v8, 0, v59
	v_max_f32_e32 v62, 0, v56
	v_max_f32_e32 v71, 0, v40
	v_add_f32_e32 v133, v8, v4
	v_add_f32_e32 v4, 1.0, v7
; DEVI float xlane32(float v) { return __shfl_xor(v, 32); }
; DEVI void stick_half(f32x16& x, float& carry, bool diag, int kv0, int tq, int hi) {
;     f32x16 lk; const int dq = diag ? tq - kv0 : 64;
; #pragma unroll
;     for (int r = 0; r < 16; ++r) {
;         float z = x[r] * C2;
;         float l = -(fmaxf(z, 0.f) + __builtin_amdgcn_logf(1.f + __builtin_amdgcn_exp2f(-fabsf(z))));
;         if ((r & 3) + 8 * (r >> 2) >= dq) { l = 0.f; z = -INFINITY; }
;         lk[r] = l; x[r] = z;
;     }
;     float T[4], PT[4], S[4], A[4];
; #pragma unroll
;     for (int g = 0; g < 4; ++g) { T[g] = (lk[4 * g] + lk[4 * g + 1]) + (lk[4 * g + 2] + lk[4 * g + 3]); PT[g] = xlane32(T[g]); S[g] = T[g] + PT[g]; }
;     A[3] = 0.f; A[2] = S[3]; A[1] = A[2] + S[2]; A[0] = A[1] + S[1];
	v_mul_f32_e32 v61, 0x3e0293ee, v9
	v_add_f32_e32 v83, v62, v26
	v_add_f32_e32 v97, v71, v34
	v_log_f32_e32 v34, v4
	v_exp_f32_e64 v4, -|v61|
	v_mul_f32_e32 v62, 0x3e0293ee, v10
	v_add_f32_e32 v28, 1.0, v28
	v_add_f32_e32 v65, 1.0, v65
	v_exp_f32_e64 v7, -|v62|
	v_mul_f32_e32 v50, 0x3e0293ee, v27
	v_log_f32_e32 v91, v28
	v_log_f32_e32 v28, v65
	v_exp_f32_e64 v30, -|v50|
	v_exp_f32_e64 v67, -|v58|
	v_max_f32_e32 v36, 0, v52
	v_add_f32_e32 v4, 1.0, v4
	v_max_f32_e32 v64, 0, v57
	v_add_f32_e32 v6, v36, v6
	v_log_f32_e32 v36, v4
	v_add_f32_e32 v4, 1.0, v7
	v_mul_f32_e32 v63, 0x3e0293ee, v11
	v_add_f32_e32 v95, v64, v28
	v_log_f32_e32 v38, v4
	v_exp_f32_e64 v4, -|v63|
	v_mul_f32_e32 v64, 0x3e0293ee, v12
	v_add_f32_e32 v30, 1.0, v30
	v_add_f32_e32 v67, 1.0, v67
	v_exp_f32_e64 v7, -|v64|
	v_log_f32_e32 v93, v30
	v_log_f32_e32 v30, v67
	v_add_f32_e32 v4, 1.0, v4
	v_max_f32_e32 v66, 0, v58
	v_log_f32_e32 v84, v4
	v_add_f32_e32 v4, 1.0, v7
	v_mul_f32_e32 v65, 0x3e0293ee, v13
	v_add_f32_e32 v96, v66, v30
	v_log_f32_e32 v86, v4
	v_exp_f32_e64 v4, -|v65|
	v_mul_f32_e32 v66, 0x3e0293ee, v14
	v_exp_f32_e64 v7, -|v66|
	v_mul_f32_e32 v67, 0x3e0293ee, v15
	v_add_f32_e32 v4, 1.0, v4
	v_log_f32_e32 v88, v4
	v_add_f32_e32 v4, 1.0, v7
	v_exp_f32_e64 v7, -|v67|
	v_mul_f32_e32 v71, 0x3e0293ee, v16
	v_exp_f32_e64 v8, -|v71|
	v_mul_f32_e32 v72, 0x3e0293ee, v17
	v_add_f32_e32 v7, 1.0, v7
	v_log_f32_e32 v92, v7
	v_add_f32_e32 v7, 1.0, v8
	v_exp_f32_e64 v8, -|v72|
	v_log_f32_e32 v7, v7
	v_max_f32_e32 v9, 0, v71
	v_mul_f32_e32 v73, 0x3e0293ee, v18
	v_add_f32_e32 v8, 1.0, v8
	v_add_f32_e32 v138, v9, v7
	v_log_f32_e32 v8, v8
	v_exp_f32_e64 v9, -|v73|
	v_mul_f32_e32 v74, 0x3e0293ee, v19
	v_exp_f32_e64 v10, -|v74|
	v_max_f32_e32 v7, 0, v72
	v_add_f32_e32 v18, v7, v8
	v_add_f32_e32 v7, 1.0, v9
	v_log_f32_e32 v7, v7
	v_add_f32_e32 v8, 1.0, v10
	v_log_f32_e32 v8, v8
	v_max_f32_e32 v9, 0, v73
	v_add_f32_e32 v139, v9, v7
	v_max_f32_e32 v7, 0, v74
	v_add_f32_e32 v140, v7, v8
	v_sub_u32_e32 v7, v136, v2
	v_sub_u32_e32 v2, v1, v2
	v_cmp_lt_i32_e32 vcc, s4, v165
	v_max_f32_e32 v29, 0, v43
	v_max_f32_e32 v31, 0, v44
	v_cndmask_b32_e64 v2, v2, 64, vcc
	v_max_f32_e32 v33, 0, v45
	v_max_f32_e32 v27, 0, v46
	v_max_f32_e32 v28, 0, v60
	v_max_f32_e32 v30, 0, v61
	v_max_f32_e32 v32, 0, v62
	v_max_f32_e32 v26, 0, v63
	v_log_f32_e32 v90, v4
	v_cndmask_b32_e64 v141, v7, 64, vcc
	v_cmp_lt_i32_e64 s[54:55], 17, v2
	v_cmp_lt_i32_e64 s[72:73], 0, v2
	v_cmp_lt_i32_e64 s[10:11], 8, v141
	v_cndmask_b32_e64 v79, 0, -v6, s[54:55]
	v_add_f32 v6, v28, v34
	v_add_f32 v7, v29, v35
	v_add_f32 v8, v30, v36
	v_add_f32 v9, v31, v37
	v_cmp_lt_i32_e64 s[76:77], 1, v2
	v_cmp_lt_i32_e64 s[44:45], 9, v141
	v_add_f32 v10, v32, v38
	v_add_f32 v11, v33, v39
	v_cmp_lt_i32_e64 s[80:81], 2, v2
	v_cmp_lt_i32_e64 s[46:47], 10, v141
	v_add_f32 v12, v26, v84
	v_add_f32 v13, v27, v85
	v_cmp_lt_i32_e64 s[4:5], 3, v2
	v_cmp_lt_i32_e64 s[48:49], 11, v141
	v_cndmask_b32_e64 v7, 0, -v7, s[72:73]
	v_cndmask_b32_e64 v6, 0, -v6, s[10:11]
	v_cndmask_b32_e64 v9, 0, -v9, s[76:77]
	v_cndmask_b32_e64 v8, 0, -v8, s[44:45]
	v_cndmask_b32_e64 v11, 0, -v11, s[80:81]
	v_cndmask_b32_e64 v10, 0, -v10, s[46:47]
	v_cndmask_b32_e64 v15, 0, -v13, s[4:5]
	v_cndmask_b32_e64 v14, 0, -v12, s[48:49]
	v_max_f32_e32 v25, 0, v47
	v_max_f32_e32 v23, 0, v48
	v_max_f32_e32 v21, 0, v49
	v_max_f32_e32 v5, 0, v50
	v_max_f32_e32 v24, 0, v64
	v_max_f32_e32 v22, 0, v65
	v_max_f32_e32 v20, 0, v66
	v_max_f32_e32 v4, 0, v67
	v_add_f32 v12, v6, v8
	v_add_f32 v13, v7, v9
	v_add_f32 v16, v10, v14
	v_add_f32 v17, v11, v15
	v_cmp_lt_i32_e64 s[6:7], 8, v2
	v_add_f32 v30, v12, v16
	v_add_f32 v31, v13, v17
	v_add_f32 v12, v24, v86
	v_add_f32 v13, v25, v87
	v_cmp_lt_i32_e64 s[50:51], 16, v141
	v_add_f32 v16, v22, v88
	v_add_f32 v17, v23, v89
	v_cmp_lt_i32_e64 s[86:87], 9, v2
	v_cmp_lt_i32_e64 s[64:65], 17, v141
	v_add_f32 v20, v20, v90
	v_add_f32 v21, v21, v91
	v_cmp_lt_i32_e64 s[94:95], 10, v2
	v_cmp_lt_i32_e64 s[68:69], 18, v141
	v_add_f32 v4, v4, v92
	v_add_f32 v5, v5, v93
	v_cmp_lt_i32_e64 s[96:97], 11, v2
	v_cmp_lt_i32_e64 s[70:71], 19, v141
	v_cmp_lt_i32_e64 s[52:53], 16, v2
	v_cmp_lt_i32_e64 s[56:57], 18, v2
	v_cmp_lt_i32_e64 s[58:59], 19, v2
	v_cmp_lt_i32_e64 s[60:61], 24, v2
	v_cmp_lt_i32_e64 s[62:63], 25, v2
	v_cmp_lt_i32_e64 s[66:67], 26, v2
	v_cmp_lt_i32_e64 s[12:13], 27, v2
	v_cndmask_b32_e64 v13, 0, -v13, s[6:7]
	v_cndmask_b32_e64 v12, 0, -v12, s[50:51]
	v_cndmask_b32_e64 v17, 0, -v17, s[86:87]
	v_cndmask_b32_e64 v16, 0, -v16, s[64:65]
	v_cndmask_b32_e64 v21, 0, -v21, s[94:95]
	v_cndmask_b32_e64 v20, 0, -v20, s[68:69]
	v_cndmask_b32_e64 v25, 0, -v5, s[96:97]
	v_cndmask_b32_e64 v24, 0, -v4, s[70:71]
	v_cndmask_b32_e64 v77, 0, -v75, s[52:53]
	v_cndmask_b32_e64 v81, 0, -v76, s[56:57]
	v_cndmask_b32_e64 v82, 0, -v78, s[58:59]
	v_cndmask_b32_e64 v75, 0, -v80, s[60:61]
	v_cndmask_b32_e64 v76, 0, -v83, s[62:63]
	v_cndmask_b32_e64 v78, 0, -v95, s[66:67]
	v_cndmask_b32_e64 v80, 0, -v96, s[12:13]
	v_add_f32 v4, v12, v16
	v_add_f32 v5, v13, v17
	v_add_f32 v22, v20, v24
	v_add_f32 v23, v21, v25
	v_cmp_lt_i32_e64 s[74:75], 24, v141
	v_add_f32 v32, v4, v22
	v_add_f32 v33, v5, v23
	v_add_f32_e32 v2, v75, v76
	v_add_f32_e32 v22, v78, v80
	v_cmp_lt_i32_e64 s[78:79], 25, v141
	v_add_f32_e32 v5, v77, v79
	v_add_f32_e32 v23, v81, v82
	v_cndmask_b32_e64 v4, 0, -v138, s[74:75]
	v_add_f32_e32 v2, v2, v22
	v_cndmask_b32_e64 v22, 0, -v18, s[78:79]
	v_add_f32 v34, v4, v22
	v_add_f32 v35, v5, v23
	ds_bpermute_b32 v39, v94, v35
	ds_bpermute_b32 v85, v94, v2
	v_cmp_lt_i32_e64 s[82:83], 26, v141
	v_cmp_lt_i32_e64 s[84:85], 27, v141
	v_cmp_lt_i32_e64 s[8:9], 0, v141
	v_cndmask_b32_e64 v5, 0, -v139, s[82:83]
	v_cndmask_b32_e64 v23, 0, -v140, s[84:85]
	v_add_f32_e32 v38, v5, v23
	v_cmp_lt_i32_e64 s[88:89], 1, v141
	v_cmp_lt_i32_e64 s[90:91], 2, v141
	v_cmp_lt_i32_e64 s[92:93], 3, v141
	s_waitcnt lgkmcnt(1)
; DEVI float xlane32(float v) { return __shfl_xor(v, 32); }
; DEVI void stick_half(f32x16& x, float& carry, bool diag, int kv0, int tq, int hi) {
;     ...
;     float T[4], PT[4], S[4], A[4];
; #pragma unroll
;     for (int g = 0; g < 4; ++g) { T[g] = (lk[4 * g] + lk[4 * g + 1]) + (lk[4 * g + 2] + lk[4 * g + 3]); PT[g] = xlane32(T[g]); S[g] = T[g] + PT[g]; }
;     A[3] = 0.f; A[2] = S[3]; A[1] = A[2] + S[2]; A[0] = A[1] + S[1];
; #pragma unroll
;     for (int g = 0; g < 4; ++g) {
;         const float i3 = (carry + A[g] + (hi == 0 ? PT[g] : 0.f)) + lk[4 * g + 3], i2 = i3 + lk[4 * g + 2], i1 = i2 + lk[4 * g + 1], i0 = i1 + lk[4 * g];
;         x[4 * g + 3] = __builtin_amdgcn_exp2f(x[4 * g + 3] + i3); x[4 * g + 2] = __builtin_amdgcn_exp2f(x[4 * g + 2] + i2);
;         x[4 * g + 1] = __builtin_amdgcn_exp2f(x[4 * g + 1] + i1); x[4 * g] = __builtin_amdgcn_exp2f(x[4 * g] + i0);
;     }
;     carry += A[0] + S[0];
; template <int MODE>
; DEVI void attn_unit(LAS unsigned char* lds, const bf16_t* Qw, int ldq, const bf16_t* Kb, const bf16_t* Vb, int ldk, bf16_t* Ow, int ldo,
;                     int j_first, int ntiles, int jstep, int wj_lo, int wj_hi, int t0) {
;     ...
;                 if (__all(carry < -152.f)) { mydone = true; if (lane == 0) dflag[(i & 1) * 8 + wid] = 1u; }
	v_add_f32 v34, v34, v38
	v_add_f32 v35, v35, v39
	v_cndmask_b32_e64 v38, 0, -v97, s[8:9]
	v_cndmask_b32_e64 v83, 0, -v98, s[88:89]
	v_cndmask_b32_e64 v84, 0, -v99, s[90:91]
	v_cndmask_b32_e64 v86, 0, -v133, s[92:93]
	ds_bpermute_b32 v27, v94, v33
	s_waitcnt lgkmcnt(1)
	v_add_f32_e32 v29, v2, v85
	ds_bpermute_b32 v26, v94, v32
	ds_bpermute_b32 v28, v94, v34
	v_add_f32_e32 v2, v38, v83
	v_add_f32_e32 v18, v84, v86
	ds_bpermute_b32 v19, v94, v31
	v_add_f32_e32 v2, v2, v18
	ds_bpermute_b32 v18, v94, v30
	ds_bpermute_b32 v87, v94, v2
	s_waitcnt lgkmcnt(4)
	v_add_f32 v36, v32, v26
	v_add_f32 v37, v33, v27
	s_waitcnt lgkmcnt(3)
	v_add_f32 v32, v34, v28
	v_add_f32 v33, v35, v29
	s_waitcnt lgkmcnt(1)
	v_add_f32 v30, v30, v18
	v_add_f32 v31, v31, v19
	v_add_f32 v34, v36, v32
	v_add_f32 v35, v37, v33
	s_waitcnt lgkmcnt(0)
	v_add_f32_e32 v2, v2, v87
	v_add_f32 v36, v30, v34
	v_add_f32 v37, v31, v35
	s_nop 0
	v_add_f32 v30, v36, v2
	v_add_f32 v31, v37, v3
	s_nop 0
	v_add_f32_e32 v139, v30, v31
	v_cmp_gt_f32_e32 vcc, s14, v139
	s_cmp_eq_u64 vcc, exec
	s_cselect_b64 s[14:15], -1, 0
	s_xor_b64 s[20:21], s[38:39], -1
	s_and_b64 s[24:25], s[20:21], s[14:15]
	s_and_saveexec_b64 s[20:21], s[24:25]
	s_or_b64 s[14:15], s[14:15], exec
	ds_write_b32 v163, v209
	s_or_b64 exec, exec, s[20:21]
	v_add_f32_e32 v35, 0, v35
	v_cndmask_b32_e64 v19, 0, v19, s[42:43]
	v_add_f32_e32 v19, v19, v35
	v_add_f32_e32 v15, v15, v19
	v_add_f32_e32 v11, v11, v15
	v_add_f32_e32 v9, v9, v11
	v_cndmask_b32_e64 v2, v216, v43, s[72:73]
	v_add_f32_e32 v7, v7, v9
	v_add_f32_e32 v34, v34, v31
	v_cndmask_b32_e64 v18, 0, v18, s[42:43]
	v_cndmask_b32_e64 v30, v216, v44, s[76:77]
	v_add_f32_e32 v2, v2, v7
	v_add_f32_e32 v7, 0, v33
	v_cndmask_b32_e64 v19, 0, v27, s[42:43]
	v_add_f32_e32 v18, v18, v34
	v_add_f32_e32 v9, v30, v9
	v_add_f32_e32 v7, v19, v7
	v_add_f32_e32 v30, 0, v85
	v_add_f32_e32 v14, v14, v18
	v_add_f32_e32 v18, v32, v31
	v_cndmask_b32_e64 v26, 0, v26, s[42:43]
	v_add_f32_e32 v7, v25, v7
	v_cndmask_b32_e64 v30, 0, v30, s[42:43]
	v_add_f32_e32 v18, v26, v18
	v_cndmask_b32_e64 v43, v216, v46, s[4:5]
	v_cndmask_b32_e64 v46, v216, v49, s[94:95]
	v_cndmask_b32_e64 v49, v216, v52, s[54:55]
	v_cndmask_b32_e64 v52, v216, v55, s[60:61]
	v_cndmask_b32_e64 v55, v216, v58, s[12:13]
	v_add_f32_e32 v19, v21, v7
	v_add_f32_e32 v21, 0, v29
	v_cndmask_b32_e64 v25, 0, v39, s[42:43]
	v_add_f32_e32 v30, v80, v30
	v_add_f32_e32 v18, v24, v18
	v_cndmask_b32_e64 v24, 0, v28, s[42:43]
	v_add_f32_e32 v21, v25, v21
	v_add_f32_e32 v33, v78, v30
	v_add_f32_e32 v30, v55, v30
	v_add_f32_e32 v36, v36, v31
	v_cndmask_b32_e64 v55, 0, v87, s[42:43]
	v_add_f32_e32 v24, v24, v31
	v_add_f32_e32 v21, v82, v21
	v_add_f32_e32 v36, v55, v36
	v_add_f32_e32 v23, v23, v24
	v_add_f32_e32 v25, v81, v21
	v_add_f32_e32 v36, v86, v36
	v_add_f32_e32 v5, v5, v23
	v_cndmask_b32_e64 v37, v216, v45, s[80:81]
	v_cndmask_b32_e64 v44, v216, v47, s[6:7]
	v_cndmask_b32_e64 v45, v216, v48, s[86:87]
	v_cndmask_b32_e64 v47, v216, v50, s[96:97]
	v_cndmask_b32_e64 v48, v216, v51, s[52:53]
	v_cndmask_b32_e64 v50, v216, v53, s[56:57]
	v_cndmask_b32_e64 v51, v216, v54, s[58:59]
	v_cndmask_b32_e64 v53, v216, v56, s[62:63]
	v_add_f32_e32 v17, v17, v19
	v_add_f32_e32 v27, v79, v25
	v_add_f32_e32 v35, v76, v33
	v_add_f32_e32 v55, v84, v36
	v_add_f32_e32 v10, v10, v14
	v_add_f32_e32 v20, v20, v18
	v_add_f32_e32 v22, v22, v5
	v_cndmask_b32_e64 v54, v216, v57, s[66:67]
	v_add_f32_e32 v11, v37, v11
	v_add_f32_e32 v13, v13, v17
	v_add_f32_e32 v29, v77, v27
	v_add_f32_e32 v21, v51, v21
	v_add_f32_e32 v37, v75, v35
	v_add_f32_e32 v35, v53, v35
	v_cndmask_b32_e64 v51, v216, v71, s[74:75]
	v_cndmask_b32_e64 v53, v216, v73, s[82:83]
	v_add_f32_e32 v56, v83, v55
	v_add_f32_e32 v8, v8, v10
	v_add_f32_e32 v16, v16, v20
	v_add_f32_e32 v4, v4, v22
	v_add_f32_e32 v15, v43, v15
	v_add_f32_e32 v7, v47, v7
	v_add_f32_e32 v19, v46, v19
	v_add_f32_e32 v17, v45, v17
	v_add_f32_e32 v13, v44, v13
	v_add_f32_e32 v25, v50, v25
	v_add_f32_e32 v27, v49, v27
	v_add_f32_e32 v29, v48, v29
	v_add_f32_e32 v33, v54, v33
	v_add_f32_e32 v37, v52, v37
	v_cndmask_b32_e64 v39, v216, v40, s[8:9]
	v_cndmask_b32_e64 v40, v216, v41, s[88:89]
	v_cndmask_b32_e64 v41, v216, v42, s[90:91]
	v_cndmask_b32_e64 v42, v216, v59, s[92:93]
	v_cndmask_b32_e64 v43, v216, v60, s[10:11]
	v_cndmask_b32_e64 v44, v216, v61, s[44:45]
	v_cndmask_b32_e64 v45, v216, v62, s[46:47]
	v_cndmask_b32_e64 v46, v216, v63, s[48:49]
	v_cndmask_b32_e64 v47, v216, v64, s[50:51]
	v_cndmask_b32_e64 v48, v216, v65, s[64:65]
	v_cndmask_b32_e64 v49, v216, v66, s[68:69]
	v_cndmask_b32_e64 v50, v216, v67, s[70:71]
	v_cndmask_b32_e64 v52, v216, v72, s[78:79]
	v_cndmask_b32_e64 v54, v216, v74, s[84:85]
	v_add_f32_e32 v38, v38, v56
	v_add_f32_e32 v6, v6, v8
	v_add_f32_e32 v12, v12, v16
	v_add_f32_e32 v5, v53, v5
	v_add_f32_e32 v4, v51, v4
	v_add_f32_e32 v36, v42, v36
	v_add_f32_e32 v41, v41, v55
	v_add_f32_e32 v40, v40, v56
	v_add_f32_e32 v38, v39, v38
	v_add_f32_e32 v14, v46, v14
	v_add_f32_e32 v10, v45, v10
	v_add_f32_e32 v8, v44, v8
	v_add_f32_e32 v6, v43, v6
	v_add_f32_e32 v18, v50, v18
	v_add_f32_e32 v20, v49, v20
	v_add_f32_e32 v16, v48, v16
	v_add_f32_e32 v12, v47, v12
	v_add_f32_e32 v23, v54, v23
	v_exp_f32_e32 v5, v5
	v_add_f32_e32 v22, v52, v22
	v_exp_f32_e32 v4, v4
	v_exp_f32_e32 v15, v15
	v_exp_f32_e32 v11, v11
	v_exp_f32_e32 v9, v9
	v_exp_f32_e32 v2, v2
	v_exp_f32_e32 v7, v7
	v_exp_f32_e32 v19, v19
	v_exp_f32_e32 v17, v17
	v_exp_f32_e32 v13, v13
	v_exp_f32_e32 v21, v21
	v_exp_f32_e32 v25, v25
	v_exp_f32_e32 v27, v27
	v_exp_f32_e32 v29, v29
	v_exp_f32_e32 v30, v30
	v_exp_f32_e32 v33, v33
	v_exp_f32_e32 v35, v35
	v_exp_f32_e32 v37, v37
	v_exp_f32_e32 v36, v36
	v_exp_f32_e32 v41, v41
	v_exp_f32_e32 v40, v40
	v_exp_f32_e32 v38, v38
	v_exp_f32_e32 v14, v14
	v_exp_f32_e32 v10, v10
	v_exp_f32_e32 v8, v8
	v_exp_f32_e32 v6, v6
	v_exp_f32_e32 v18, v18
	v_exp_f32_e32 v20, v20
	v_exp_f32_e32 v16, v16
	v_exp_f32_e32 v12, v12
	v_exp_f32_e32 v23, v23
	v_exp_f32_e32 v22, v22
	v_cvt_pk_bf16_f32 v52, v38, v40
	v_cvt_pk_bf16_f32 v53, v41, v36
	v_cvt_pk_bf16_f32 v54, v6, v8
	v_cvt_pk_bf16_f32 v55, v10, v14
	v_cvt_pk_bf16_f32 v72, v12, v16
	v_cvt_pk_bf16_f32 v73, v20, v18
	v_cvt_pk_bf16_f32 v74, v4, v22
	v_cvt_pk_bf16_f32 v75, v5, v23
	v_cvt_pk_bf16_f32 v76, v2, v9
	v_cvt_pk_bf16_f32 v77, v11, v15
	v_cvt_pk_bf16_f32 v78, v13, v17
	v_cvt_pk_bf16_f32 v79, v19, v7
	v_cvt_pk_bf16_f32 v80, v29, v27
	v_cvt_pk_bf16_f32 v81, v25, v21
	v_cvt_pk_bf16_f32 v82, v37, v35
	v_cvt_pk_bf16_f32 v83, v33, v30
	ds_read_b64_tr_b16 v[4:5], v177 offset:0
	ds_read_b64_tr_b16 v[6:7], v177 offset:0x800
	ds_read_b64_tr_b16 v[20:21], v177 offset:0x1000
	ds_read_b64_tr_b16 v[22:23], v177 offset:0x1800
	ds_read_b64_tr_b16 v[24:25], v177 offset:0x2000
	ds_read_b64_tr_b16 v[26:27], v177 offset:0x2800
	ds_read_b64_tr_b16 v[28:29], v177 offset:0x3000
	ds_read_b64_tr_b16 v[30:31], v177 offset:0x3800
	s_waitcnt lgkmcnt(0)
; #define FA_SBAR() __builtin_amdgcn_sched_barrier(0)
; template <int OFF> DEVI s16x4 tr_read(int vb) { s16x4 r; asm volatile("ds_read_b64_tr_b16 %0, %1 offset:%2" : "=&v"(r) : "v"(vb), "i"(OFF) : "memory"); return r; }
; template <int D0> DEVI void pv_one(f32x16& od, int vb, bf16x8 pa0, bf16x8 pa1, bf16x8 pa2, bf16x8 pa3) {
;     const s16x4 l0 = tr_read<v_rd_off(D0, 0, 0)>(vb), h0 = tr_read<v_rd_off(D0, 0, 1)>(vb), l1 = tr_read<v_rd_off(D0, 1, 0)>(vb), h1 = tr_read<v_rd_off(D0, 1, 1)>(vb);
;     const s16x4 l2 = tr_read<v_rd_off(D0, 2, 0)>(vb), h2 = tr_read<v_rd_off(D0, 2, 1)>(vb), l3 = tr_read<v_rd_off(D0, 3, 0)>(vb), h3 = tr_read<v_rd_off(D0, 3, 1)>(vb);
;     asm volatile("s_waitcnt lgkmcnt(0)" ::: "memory"); FA_SBAR();
;     ...
;     od = __builtin_amdgcn_mfma_f32_32x32x16_bf16(pa0, FA_PK(l0, h0), od, 0, 0, 0);
;     od = __builtin_amdgcn_mfma_f32_32x32x16_bf16(pa1, FA_PK(l1, h1), od, 0, 0, 0);
;     od = __builtin_amdgcn_mfma_f32_32x32x16_bf16(pa2, FA_PK(l2, h2), od, 0, 0, 0);
;     od = __builtin_amdgcn_mfma_f32_32x32x16_bf16(pa3, FA_PK(l3, h3), od, 0, 0, 0);
;     ...
; }
; DEVI void pv_d0(f32x16* o, int vb, bf16x8 pa0, bf16x8 pa1, bf16x8 pa2, bf16x8 pa3) {
;     pv_one<0>(o[0], vb, pa0, pa1, pa2, pa3); pv_one<1>(o[1], vb, pa0, pa1, pa2, pa3); pv_one<2>(o[2], vb, pa0, pa1, pa2, pa3); pv_one<3>(o[3], vb, pa0, pa1, pa2, pa3);
; }
; DEVI void pack_p(const f32x16& p0, const f32x16& p1, bf16x8& pa0, bf16x8& pa1, bf16x8& pa2, bf16x8& pa3) {
;     ...
;     FA_PK4(p0, 0, pa0); FA_PK4(p0, 8, pa1); FA_PK4(p1, 0, pa2); FA_PK4(p1, 8, pa3);
	s_nop 0
	v_permlane32_swap_b32_e32 v52, v54
	v_permlane32_swap_b32_e32 v53, v55
	v_permlane32_swap_b32_e32 v72, v74
	v_permlane32_swap_b32_e32 v73, v75
	v_permlane32_swap_b32_e32 v76, v78
	v_permlane32_swap_b32_e32 v77, v79
	v_permlane32_swap_b32_e32 v80, v82
	v_permlane32_swap_b32_e32 v81, v83
	v_mfma_f32_32x32x16_bf16 v[4:19], v[52:55], v[4:7], 0
	v_mfma_f32_32x32x16_bf16 v[4:19], v[72:75], v[20:23], v[4:19]
	ds_read_b64_tr_b16 v[20:21], v177 offset:0x200
	ds_read_b64_tr_b16 v[22:23], v177 offset:0xa00
	ds_read_b64_tr_b16 v[36:37], v177 offset:0x1200
	ds_read_b64_tr_b16 v[38:39], v177 offset:0x1a00
	ds_read_b64_tr_b16 v[40:41], v177 offset:0x2200
	ds_read_b64_tr_b16 v[42:43], v177 offset:0x2a00
	ds_read_b64_tr_b16 v[44:45], v177 offset:0x3200
	v_mfma_f32_32x32x16_bf16 v[4:19], v[76:79], v[24:27], v[4:19]
	ds_read_b64_tr_b16 v[46:47], v177 offset:0x3a00
	s_waitcnt lgkmcnt(0)
	v_mfma_f32_32x32x16_bf16 v[4:19], v[80:83], v[28:31], v[4:19]
	v_mfma_f32_32x32x16_bf16 v[20:35], v[52:55], v[20:23], 0
	v_mfma_f32_32x32x16_bf16 v[20:35], v[72:75], v[36:39], v[20:35]
	ds_read_b64_tr_b16 v[36:37], v177 offset:0x400
	ds_read_b64_tr_b16 v[38:39], v177 offset:0xc00
	ds_read_b64_tr_b16 v[56:57], v177 offset:0x1400
	ds_read_b64_tr_b16 v[58:59], v177 offset:0x1c00
	ds_read_b64_tr_b16 v[60:61], v177 offset:0x2400
	ds_read_b64_tr_b16 v[62:63], v177 offset:0x2c00
	ds_read_b64_tr_b16 v[64:65], v177 offset:0x3400
	v_mfma_f32_32x32x16_bf16 v[20:35], v[76:79], v[40:43], v[20:35]
	ds_read_b64_tr_b16 v[66:67], v177 offset:0x3c00
	s_waitcnt lgkmcnt(0)
	v_mfma_f32_32x32x16_bf16 v[20:35], v[80:83], v[44:47], v[20:35]
	v_mfma_f32_32x32x16_bf16 v[36:51], v[52:55], v[36:39], 0
	v_mfma_f32_32x32x16_bf16 v[36:51], v[72:75], v[56:59], v[36:51]
	ds_read_b64_tr_b16 v[56:57], v177 offset:0x600
	ds_read_b64_tr_b16 v[58:59], v177 offset:0xe00
	ds_read_b64_tr_b16 v[84:85], v177 offset:0x1600
	ds_read_b64_tr_b16 v[86:87], v177 offset:0x1e00
	ds_read_b64_tr_b16 v[88:89], v177 offset:0x2600
	ds_read_b64_tr_b16 v[90:91], v177 offset:0x2e00
	ds_read_b64_tr_b16 v[92:93], v177 offset:0x3600
	v_mfma_f32_32x32x16_bf16 v[36:51], v[76:79], v[60:63], v[36:51]
	ds_read_b64_tr_b16 v[94:95], v177 offset:0x3e00
	s_waitcnt lgkmcnt(0)
	v_mfma_f32_32x32x16_bf16 v[36:51], v[80:83], v[64:67], v[36:51]
	v_mfma_f32_32x32x16_bf16 v[52:67], v[52:55], v[56:59], 0
	v_mfma_f32_32x32x16_bf16 v[52:67], v[72:75], v[84:87], v[52:67]
	v_mfma_f32_32x32x16_bf16 v[52:67], v[76:79], v[88:91], v[52:67]
	v_mfma_f32_32x32x16_bf16 v[52:67], v[80:83], v[92:95], v[52:67]

; #define LAS __attribute__((address_space(3)))
; DEVI void qkt(f32x16& p0, f32x16& p1, LAS const unsigned char* Ks, const bf16x8* qr, int r32, int hi) {
;     p0 = (f32x16){0.f, 0.f, 0.f, 0.f, 0.f, 0.f, 0.f, 0.f, 0.f, 0.f, 0.f, 0.f, 0.f, 0.f, 0.f, 0.f}; p1 = p0;
; #pragma unroll
;     for (int d0 = 0; d0 < 8; ++d0) { const int cb = (d0 * 16 + hi * 8) * 2;
;         const bf16x8 b0 = *(LAS const bf16x8*)(Ks + FA_KSWZ(r32, cb));
;         const bf16x8 b1 = *(LAS const bf16x8*)(Ks + FA_KSWZ(32 + r32, cb));
;         p0 = __builtin_amdgcn_mfma_f32_32x32x16_bf16(b0, qr[d0], p0, 0, 0, 0);
;         p1 = __builtin_amdgcn_mfma_f32_32x32x16_bf16(b1, qr[d0], p1, 0, 0, 0); }
; DEVI void stick_half(f32x16& x, float& carry, bool diag, int kv0, int tq, int hi) {
;     f32x16 lk; const int dq = diag ? tq - kv0 : 64;
; #pragma unroll
;     for (int r = 0; r < 16; ++r) {
;         float z = x[r] * C2;
;         float l = -(fmaxf(z, 0.f) + __builtin_amdgcn_logf(1.f + __builtin_amdgcn_exp2f(-fabsf(z))));
; template <int MODE>
; DEVI void attn_unit(LAS unsigned char* lds, const bf16_t* Qw, int ldq, const bf16_t* Kb, const bf16_t* Vb, int ldk, bf16_t* Ow, int ldo,
;                     int j_first, int ntiles, int jstep, int wj_lo, int wj_hi, int t0) {
;     ...
;         if (j >= wj_lo && j <= wj_hi && !mydone) {
;             f32x16 p0, p1;
;             if constexpr (MODE == M_STICK) {
;                 int qz_ = 0; asm volatile("" : "+v"(qz_)); const bf16_t* qp2 = qp + qz_;
; #pragma unroll
;                 for (int d0 = 0; d0 < 8; ++d0) qr[d0] = *(const bf16x8*)(qp2 + d0 * 16); }
;             qkt(p0, p1, K_lds + buf * SHM_K, qr, r32, hi);
;             bf16x8 pa0, pa1, pa2, pa3;
;             if constexpr (MODE == M_STICK) {
;                 const int tq = t0 + r32; const bool diag = (64 * j + 63 >= t0);
;                 stick_half(p1, carry, diag, 64 * j + 32 + 4 * hi, tq, hi);
;                 stick_half(p0, carry, diag, 64 * j + 4 * hi, tq, hi);
.LBB11_996:
	s_and_saveexec_b64 s[4:5], s[40:41]
	v_lshl_add_u32 v2, s25, 5, v163
	v_cndmask_b32_e64 v68, 0, 1, s[14:15]
	ds_write_b32 v2, v68
	s_or_b64 exec, exec, s[4:5]
	s_add_i32 s37, s22, -1
	s_cmp_lt_i32 s22, 1
	s_cselect_b64 s[4:5], -1, 0
	v_cmp_gt_i32_e32 vcc, s37, v178
	s_or_b64 s[4:5], s[4:5], vcc
	s_nor_b64 s[4:5], s[4:5], s[14:15]
	s_and_saveexec_b64 s[20:21], s[4:5]
	s_cbranch_execz .LBB11_1002
	v_mov_b32_e32 v68, 0
	v_add_u32_e32 v2, s6, v167
	v_ashrrev_i32_e32 v69, 31, v68
	v_lshl_add_u64 v[154:155], v[68:69], 1, v[134:135]
	global_load_dwordx4 v[84:87], v[154:155], off
	global_load_dwordx4 v[142:145], v[154:155], off offset:32
	v_add_u32_e32 v72, v2, v168
	ds_read_b128 v[68:71], v72 offset:32768
	ds_read_b128 v[88:91], v72 offset:40960
	global_load_dwordx4 v[146:149], v[154:155], off offset:64
	v_add_u32_e32 v138, v2, v169
	ds_read_b128 v[150:153], v138 offset:32768
	ds_read_b128 v[198:201], v138 offset:40960
	v_add_u32_e32 v138, v2, v170
	s_add_i32 s4, s33, 63
	v_add_u32_e32 v224, s33, v176
	s_mov_b32 s12, 0xc3180000
	s_waitcnt vmcnt(2) lgkmcnt(3)
	v_mfma_f32_32x32x16_bf16 v[68:83], v[68:71], v[84:87], 0
	s_waitcnt vmcnt(1) lgkmcnt(1)
	v_mfma_f32_32x32x16_bf16 v[68:83], v[150:153], v[142:145], v[68:83]
	global_load_dwordx4 v[150:153], v[154:155], off offset:96
	v_mfma_f32_32x32x16_bf16 v[84:99], v[88:91], v[84:87], 0
	s_waitcnt lgkmcnt(0)
	v_mfma_f32_32x32x16_bf16 v[84:99], v[198:201], v[142:145], v[84:99]
	ds_read_b128 v[142:145], v138 offset:32768
	ds_read_b128 v[198:201], v138 offset:40960
	v_add_u32_e32 v138, v2, v171
	s_waitcnt vmcnt(1) lgkmcnt(1)
	v_mfma_f32_32x32x16_bf16 v[68:83], v[142:145], v[146:149], v[68:83]
	global_load_dwordx4 v[142:145], v[154:155], off offset:128
	s_waitcnt lgkmcnt(0)
	v_mfma_f32_32x32x16_bf16 v[84:99], v[198:201], v[146:149], v[84:99]
	ds_read_b128 v[146:149], v138 offset:32768
	ds_read_b128 v[198:201], v138 offset:40960
	v_add_u32_e32 v138, v2, v172
	s_waitcnt vmcnt(1) lgkmcnt(1)
	v_mfma_f32_32x32x16_bf16 v[68:83], v[146:149], v[150:153], v[68:83]
	global_load_dwordx4 v[146:149], v[154:155], off offset:160
	s_waitcnt lgkmcnt(0)
	v_mfma_f32_32x32x16_bf16 v[84:99], v[198:201], v[150:153], v[84:99]
	ds_read_b128 v[150:153], v138 offset:32768
	ds_read_b128 v[198:201], v138 offset:40960
	v_add_u32_e32 v138, v2, v173
	s_waitcnt vmcnt(1) lgkmcnt(1)
	v_mfma_f32_32x32x16_bf16 v[68:83], v[150:153], v[142:145], v[68:83]
	global_load_dwordx4 v[150:153], v[154:155], off offset:192
	s_waitcnt lgkmcnt(0)
	v_mfma_f32_32x32x16_bf16 v[84:99], v[198:201], v[142:145], v[84:99]
	ds_read_b128 v[142:145], v138 offset:32768
	ds_read_b128 v[198:201], v138 offset:40960
	v_add_u32_e32 v138, v2, v174
	v_add_u32_e32 v2, v2, v175
	s_waitcnt vmcnt(1) lgkmcnt(1)
	v_mfma_f32_32x32x16_bf16 v[68:83], v[142:145], v[146:149], v[68:83]
	global_load_dwordx4 v[142:145], v[154:155], off offset:224
	s_waitcnt lgkmcnt(0)
	v_mfma_f32_32x32x16_bf16 v[84:99], v[198:201], v[146:149], v[84:99]
	ds_read_b128 v[146:149], v138 offset:32768
	ds_read_b128 v[198:201], v138 offset:40960
	v_and_b32_e32 v138, 64, v215
	v_add_u32_e32 v138, 64, v138
	s_waitcnt vmcnt(1) lgkmcnt(1)
	v_mfma_f32_32x32x16_bf16 v[68:83], v[146:149], v[150:153], v[68:83]
	ds_read_b128 v[146:149], v2 offset:32768
	s_waitcnt lgkmcnt(1)
	v_mfma_f32_32x32x16_bf16 v[84:99], v[198:201], v[150:153], v[84:99]
	ds_read_b128 v[150:153], v2 offset:40960
	v_xor_b32_e32 v2, 32, v215
	v_cmp_lt_i32_e32 vcc, v2, v138
	s_nop 1
	v_cndmask_b32_e32 v2, v215, v2, vcc
	v_lshlrev_b32_e32 v138, 2, v2
	v_cmp_lt_i32_e32 vcc, s4, v165
	s_waitcnt vmcnt(0) lgkmcnt(0)
	v_mfma_f32_32x32x16_bf16 v[84:99], v[150:153], v[142:145], v[84:99]
	s_nop 11
	v_mul_f32_e32 v198, 0x3e0293ee, v86
	v_mfma_f32_32x32x16_bf16 v[68:83], v[146:149], v[142:145], v[68:83]
	v_mul_f32_e32 v206, 0x3e0293ee, v94
	v_mul_f32_e32 v181, 0x3e0293ee, v84
	v_mul_f32_e32 v199, 0x3e0293ee, v87
	v_mul_f32_e32 v207, 0x3e0293ee, v95
	v_mul_f32_e32 v222, 0x3e0293ee, v98
	v_exp_f32_e64 v84, -|v198|
	v_exp_f32_e64 v143, -|v206|
	v_mul_f32_e32 v221, 0x3e0293ee, v97
	v_exp_f32_e64 v86, -|v199|
	v_exp_f32_e64 v145, -|v207|
	v_exp_f32_e64 v151, -|v222|
	v_exp_f32_e64 v149, -|v221|
	v_mul_f32_e32 v204, 0x3e0293ee, v92
	v_mul_f32_e32 v200, 0x3e0293ee, v88
	v_mul_f32_e32 v220, 0x3e0293ee, v96
	v_mul_f32_e32 v2, 0x3e0293ee, v68
	v_mul_f32_e32 v179, 0x3e0293ee, v69
	v_exp_f32_e64 v68, -|v181|
	v_exp_f32_e64 v98, -|v204|
	v_add_f32_e32 v84, 1.0, v84
	v_add_f32_e32 v196, 1.0, v143
	v_mul_f32_e32 v180, 0x3e0293ee, v70
	v_exp_f32_e64 v88, -|v200|
	v_exp_f32_e64 v147, -|v220|
	v_exp_f32_e64 v155, -|v2|
	v_exp_f32_e64 v185, -|v179|
	v_add_f32_e32 v86, 1.0, v86
	v_add_f32_e32 v197, 1.0, v145
	v_add_f32_e32 v227, 1.0, v151
	v_log_f32_e32 v151, v84
	v_log_f32_e32 v84, v196
	v_exp_f32_e64 v186, -|v180|
	v_add_f32_e32 v226, 1.0, v149
	v_log_f32_e32 v149, v86
	v_log_f32_e32 v86, v197
	v_mul_f32_e32 v183, 0x3e0293ee, v85
	v_mul_f32_e32 v205, 0x3e0293ee, v93
	v_mul_f32_e32 v203, 0x3e0293ee, v91
	v_mul_f32_e32 v223, 0x3e0293ee, v99
	v_exp_f32_e64 v70, -|v183|
	v_exp_f32_e64 v99, -|v205|
	v_max_f32_e32 v144, 0, v206
	v_add_f32_e32 v68, 1.0, v68
	v_add_f32_e32 v98, 1.0, v98
	v_mul_f32_e32 v201, 0x3e0293ee, v89
	v_exp_f32_e64 v94, -|v203|
	v_max_f32_e32 v146, 0, v207
	v_exp_f32_e64 v153, -|v223|
	v_add_f32_e32 v88, 1.0, v88
	v_add_f32_e32 v225, 1.0, v147
	v_add_f32_e32 v229, 1.0, v155
	v_log_f32_e32 v155, v68
	v_log_f32_e32 v68, v98
	v_add_f32_e32 v196, v144, v84
	v_add_f32_e32 v84, 1.0, v185
	v_mul_f32_e32 v202, 0x3e0293ee, v90
	v_exp_f32_e64 v90, -|v201|
	v_log_f32_e32 v147, v88
	v_log_f32_e32 v88, v225
	v_log_f32_e32 v98, v229
	v_add_f32_e32 v197, v146, v86
; DEVI float xlane32(float v) { return __shfl_xor(v, 32); }
; DEVI void stick_half(f32x16& x, float& carry, bool diag, int kv0, int tq, int hi) {
;     f32x16 lk; const int dq = diag ? tq - kv0 : 64;
; #pragma unroll
;     for (int r = 0; r < 16; ++r) {
;         float z = x[r] * C2;
;         float l = -(fmaxf(z, 0.f) + __builtin_amdgcn_logf(1.f + __builtin_amdgcn_exp2f(-fabsf(z))));
;         if ((r & 3) + 8 * (r >> 2) >= dq) { l = 0.f; z = -INFINITY; }
;         lk[r] = l; x[r] = z;
;     }
;     float T[4], PT[4], S[4], A[4];
; #pragma unroll
;     for (int g = 0; g < 4; ++g) { T[g] = (lk[4 * g] + lk[4 * g + 1]) + (lk[4 * g + 2] + lk[4 * g + 3]); PT[g] = xlane32(T[g]); S[g] = T[g] + PT[g]; }
;     A[3] = 0.f; A[2] = S[3]; A[1] = A[2] + S[2]; A[0] = A[1] + S[1];
	v_log_f32_e32 v84, v84
	v_add_f32_e32 v86, 1.0, v186
	v_mul_f32_e32 v225, 0x3e0293ee, v71
	v_log_f32_e32 v86, v86
	v_exp_f32_e64 v71, -|v225|
	v_max_f32_e32 v96, 0, v204
	v_add_f32_e32 v70, 1.0, v70
	v_add_f32_e32 v187, 1.0, v99
	v_max_f32_e32 v184, 0, v2
	v_add_f32_e32 v94, 1.0, v94
	v_add_f32_e32 v228, 1.0, v153
	v_log_f32_e32 v153, v70
	v_log_f32_e32 v70, v187
	v_add_f32_e32 v187, v96, v68
	v_max_f32_e32 v68, 0, v179
	v_add_f32_e32 v90, 1.0, v90
	v_log_f32_e32 v99, v94
	v_log_f32_e32 v94, v228
	v_add_f32_e32 v228, v184, v98
	v_add_f32_e32 v184, v68, v84
	v_max_f32_e32 v68, 0, v180
	v_exp_f32_e64 v92, -|v202|
	v_log_f32_e32 v145, v90
	v_log_f32_e32 v90, v226
	v_add_f32_e32 v185, v68, v86
	v_add_f32_e32 v68, 1.0, v71
	v_mul_f32_e32 v226, 0x3e0293ee, v72
	v_log_f32_e32 v68, v68
	v_exp_f32_e64 v71, -|v226|
	v_add_f32_e32 v92, 1.0, v92
	v_max_f32_e32 v72, 0, v225
	v_max_f32_e32 v154, 0, v223
	v_log_f32_e32 v143, v92
	v_log_f32_e32 v92, v227
	v_add_f32_e32 v186, v72, v68
	v_add_f32_e32 v68, 1.0, v71
	v_mul_f32_e32 v227, 0x3e0293ee, v73
	v_add_f32_e32 v246, v154, v94
	v_log_f32_e32 v154, v68
	v_exp_f32_e64 v68, -|v227|
	v_mul_f32_e32 v229, 0x3e0293ee, v74
	v_exp_f32_e64 v71, -|v229|
	v_max_f32_e32 v152, 0, v222
	v_add_f32_e32 v68, 1.0, v68
	v_max_f32_e32 v150, 0, v221
	v_add_f32_e32 v243, v152, v92
	v_log_f32_e32 v152, v68
	v_add_f32_e32 v68, 1.0, v71
	v_mul_f32_e32 v230, 0x3e0293ee, v75
	v_add_f32_e32 v241, v150, v90
	v_log_f32_e32 v150, v68
	v_exp_f32_e64 v68, -|v230|
	v_mul_f32_e32 v231, 0x3e0293ee, v76
	v_exp_f32_e64 v71, -|v231|
	v_max_f32_e32 v148, 0, v220
	v_add_f32_e32 v68, 1.0, v68
	v_add_f32_e32 v239, v148, v88
	v_log_f32_e32 v148, v68
	v_add_f32_e32 v68, 1.0, v71
	v_mul_f32_e32 v232, 0x3e0293ee, v77
	v_log_f32_e32 v146, v68
	v_exp_f32_e64 v68, -|v232|
	v_mul_f32_e32 v233, 0x3e0293ee, v78
	v_exp_f32_e64 v71, -|v233|
	v_mul_f32_e32 v234, 0x3e0293ee, v79
	v_add_f32_e32 v68, 1.0, v68
	v_log_f32_e32 v144, v68
	v_add_f32_e32 v68, 1.0, v71
	v_exp_f32_e64 v71, -|v234|
	v_mul_f32_e32 v235, 0x3e0293ee, v80
	v_exp_f32_e64 v72, -|v235|
	v_mul_f32_e32 v236, 0x3e0293ee, v81
	v_add_f32_e32 v71, 1.0, v71
	v_log_f32_e32 v98, v71
	v_add_f32_e32 v71, 1.0, v72
	v_exp_f32_e64 v72, -|v236|
	v_log_f32_e32 v71, v71
	v_max_f32_e32 v73, 0, v235
	v_mul_f32_e32 v237, 0x3e0293ee, v82
	v_add_f32_e32 v72, 1.0, v72
	v_add_f32_e32 v247, v73, v71
	v_log_f32_e32 v72, v72
	v_exp_f32_e64 v73, -|v237|
	v_mul_f32_e32 v238, 0x3e0293ee, v83
	v_exp_f32_e64 v74, -|v238|
	v_max_f32_e32 v71, 0, v236
	v_add_f32_e32 v248, v71, v72
	v_add_f32_e32 v71, 1.0, v73
	v_log_f32_e32 v71, v71
	v_add_f32_e32 v72, 1.0, v74
	v_log_f32_e32 v72, v72
	v_max_f32_e32 v73, 0, v237
	v_add_f32_e32 v212, v73, v71
	v_max_f32_e32 v71, 0, v238
	v_add_f32_e32 v208, v71, v72
	v_sub_u32_e32 v72, v1, v224
	v_max_f32_e32 v142, 0, v205
	v_sub_u32_e32 v71, v136, v224
	v_cndmask_b32_e64 v217, v72, 64, vcc
	v_max_f32_e32 v97, 0, v181
	v_max_f32_e32 v95, 0, v183
	v_max_f32_e32 v93, 0, v198
	v_max_f32_e32 v91, 0, v199
	v_add_f32_e32 v70, v142, v70
	v_max_f32_e32 v96, 0, v226
	v_max_f32_e32 v94, 0, v227
	v_max_f32_e32 v92, 0, v229
	v_max_f32_e32 v90, 0, v230
	v_log_f32_e32 v142, v68
	v_cndmask_b32_e64 v218, v71, 64, vcc
	v_cmp_lt_i32_e64 s[52:53], 17, v217
	v_cmp_lt_i32_e64 s[70:71], 0, v217
	v_cmp_lt_i32_e64 s[8:9], 8, v218
	v_cndmask_b32_e64 v242, 0, -v70, s[52:53]
	v_add_f32 v70, v96, v154
	v_add_f32 v71, v97, v155
	v_add_f32 v72, v94, v152
	v_add_f32 v73, v95, v153
	v_cmp_lt_i32_e64 s[74:75], 1, v217
	v_cmp_lt_i32_e64 s[44:45], 9, v218
	v_add_f32 v74, v92, v150
	v_add_f32 v75, v93, v151
	v_cmp_lt_i32_e64 s[76:77], 2, v217
	v_cmp_lt_i32_e64 s[46:47], 10, v218
	v_add_f32 v76, v90, v148
	v_add_f32 v77, v91, v149
	v_cmp_lt_i32_e64 s[80:81], 3, v217
	v_cmp_lt_i32_e64 s[48:49], 11, v218
	v_cndmask_b32_e64 v71, 0, -v71, s[70:71]
	v_cndmask_b32_e64 v70, 0, -v70, s[8:9]
	v_cndmask_b32_e64 v73, 0, -v73, s[74:75]
	v_cndmask_b32_e64 v72, 0, -v72, s[44:45]
	v_cndmask_b32_e64 v75, 0, -v75, s[76:77]
	v_cndmask_b32_e64 v74, 0, -v74, s[46:47]
	v_cndmask_b32_e64 v77, 0, -v77, s[80:81]
	v_cndmask_b32_e64 v76, 0, -v76, s[48:49]
	v_max_f32_e32 v89, 0, v200
	v_max_f32_e32 v87, 0, v201
	v_max_f32_e32 v85, 0, v202
	v_max_f32_e32 v69, 0, v203
	v_max_f32_e32 v88, 0, v231
	v_max_f32_e32 v86, 0, v232
	v_max_f32_e32 v84, 0, v233
	v_max_f32_e32 v68, 0, v234
	v_add_f32 v78, v70, v72
	v_add_f32 v79, v71, v73
	v_add_f32 v80, v74, v76
	v_add_f32 v81, v75, v77
	v_cmp_lt_i32_e64 s[84:85], 8, v217
	v_add_f32 v94, v78, v80
	v_add_f32 v95, v79, v81
	v_add_f32 v78, v88, v146
	v_add_f32 v79, v89, v147
	v_cmp_lt_i32_e64 s[66:67], 16, v218
	v_add_f32 v82, v86, v144
	v_add_f32 v83, v87, v145
	v_cmp_lt_i32_e64 s[90:91], 9, v217
	v_cmp_lt_i32_e64 s[68:69], 17, v218
	v_add_f32 v84, v84, v142
	v_add_f32 v85, v85, v143
	v_cmp_lt_i32_e64 s[4:5], 10, v217
	v_cmp_lt_i32_e64 s[72:73], 18, v218
	v_add_f32 v68, v68, v98
	v_add_f32 v69, v69, v99
	v_cmp_lt_i32_e64 s[92:93], 11, v217
	v_cmp_lt_i32_e64 s[10:11], 19, v218
	v_cmp_lt_i32_e64 s[58:59], 24, v217
	v_cmp_lt_i32_e64 s[60:61], 25, v217
	v_cmp_lt_i32_e64 s[62:63], 26, v217
	v_cmp_lt_i32_e64 s[64:65], 27, v217
	v_cndmask_b32_e64 v79, 0, -v79, s[84:85]
	v_cndmask_b32_e64 v78, 0, -v78, s[66:67]
	v_cndmask_b32_e64 v83, 0, -v83, s[90:91]
	v_cndmask_b32_e64 v82, 0, -v82, s[68:69]
	v_cndmask_b32_e64 v85, 0, -v85, s[4:5]
	v_cndmask_b32_e64 v84, 0, -v84, s[72:73]
	v_cndmask_b32_e64 v89, 0, -v69, s[92:93]
	v_cndmask_b32_e64 v88, 0, -v68, s[10:11]
	v_cmp_lt_i32_e64 s[50:51], 16, v217
	v_cmp_lt_i32_e64 s[54:55], 18, v217
	v_cmp_lt_i32_e64 s[56:57], 19, v217
	v_cndmask_b32_e64 v224, 0, -v239, s[58:59]
	v_cndmask_b32_e64 v239, 0, -v241, s[60:61]
	v_cndmask_b32_e64 v241, 0, -v243, s[62:63]
	v_cndmask_b32_e64 v243, 0, -v246, s[64:65]
	v_add_f32 v68, v78, v82
	v_add_f32 v69, v79, v83
	v_add_f32 v86, v84, v88
	v_add_f32 v87, v85, v89
	v_cndmask_b32_e64 v240, 0, -v187, s[50:51]
	v_cndmask_b32_e64 v244, 0, -v196, s[54:55]
	v_cndmask_b32_e64 v245, 0, -v197, s[56:57]
	v_add_f32 v96, v68, v86
	v_add_f32 v97, v69, v87
	v_cmp_lt_i32_e64 s[78:79], 24, v218
	v_add_f32_e32 v80, v224, v239
	v_add_f32_e32 v86, v241, v243
	v_cmp_lt_i32_e64 s[82:83], 25, v218
	v_add_f32_e32 v69, v240, v242
	v_add_f32_e32 v87, v244, v245
	v_cndmask_b32_e64 v68, 0, -v247, s[78:79]
	v_add_f32_e32 v80, v80, v86
	v_cndmask_b32_e64 v86, 0, -v248, s[82:83]
	v_add_f32 v98, v68, v86
	v_add_f32 v99, v69, v87
	ds_bpermute_b32 v143, v138, v99
	ds_bpermute_b32 v147, v138, v80
	v_cmp_lt_i32_e64 s[86:87], 26, v218
	v_cmp_lt_i32_e64 s[88:89], 27, v218
	v_cmp_lt_i32_e64 s[6:7], 0, v218
	v_cndmask_b32_e64 v87, 0, -v212, s[86:87]
	v_cndmask_b32_e64 v146, 0, -v208, s[88:89]
	v_add_f32_e32 v142, v87, v146
	v_cmp_lt_i32_e64 s[94:95], 1, v218
	v_cmp_lt_i32_e64 s[96:97], 2, v218
	v_cmp_lt_i32_e32 vcc, 3, v218
	s_waitcnt lgkmcnt(1)
; DEVI float xlane32(float v) { return __shfl_xor(v, 32); }
; DEVI void stick_half(f32x16& x, float& carry, bool diag, int kv0, int tq, int hi) {
;     ...
;     float T[4], PT[4], S[4], A[4];
; #pragma unroll
;     for (int g = 0; g < 4; ++g) { T[g] = (lk[4 * g] + lk[4 * g + 1]) + (lk[4 * g + 2] + lk[4 * g + 3]); PT[g] = xlane32(T[g]); S[g] = T[g] + PT[g]; }
;     A[3] = 0.f; A[2] = S[3]; A[1] = A[2] + S[2]; A[0] = A[1] + S[1];
; #pragma unroll
;     for (int g = 0; g < 4; ++g) {
;         const float i3 = (carry + A[g] + (hi == 0 ? PT[g] : 0.f)) + lk[4 * g + 3], i2 = i3 + lk[4 * g + 2], i1 = i2 + lk[4 * g + 1], i0 = i1 + lk[4 * g];
;         x[4 * g + 3] = __builtin_amdgcn_exp2f(x[4 * g + 3] + i3); x[4 * g + 2] = __builtin_amdgcn_exp2f(x[4 * g + 2] + i2);
;         x[4 * g + 1] = __builtin_amdgcn_exp2f(x[4 * g + 1] + i1); x[4 * g] = __builtin_amdgcn_exp2f(x[4 * g] + i0);
;     }
;     carry += A[0] + S[0];
; template <int MODE>
; DEVI void attn_unit(LAS unsigned char* lds, const bf16_t* Qw, int ldq, const bf16_t* Kb, const bf16_t* Vb, int ldk, bf16_t* Ow, int ldo,
;                     int j_first, int ntiles, int jstep, int wj_lo, int wj_hi, int t0) {
;     ...
;                 if (__all(carry < -152.f)) { mydone = true; if (lane == 0) dflag[(i & 1) * 8 + wid] = 1u; }
	v_add_f32 v98, v98, v142
	v_add_f32 v99, v99, v143
	v_cndmask_b32_e64 v142, 0, -v228, s[6:7]
	v_cndmask_b32_e64 v148, 0, -v184, s[94:95]
	v_cndmask_b32_e64 v149, 0, -v185, s[96:97]
	v_cndmask_b32_e64 v150, 0, -v186, vcc
	ds_bpermute_b32 v91, v138, v97
	s_waitcnt lgkmcnt(1)
	v_add_f32_e32 v93, v80, v147
	ds_bpermute_b32 v90, v138, v96
	ds_bpermute_b32 v92, v138, v98
	v_add_f32_e32 v69, v142, v148
	v_add_f32_e32 v80, v149, v150
	ds_bpermute_b32 v81, v138, v95
	v_add_f32_e32 v69, v69, v80
	ds_bpermute_b32 v80, v138, v94
	ds_bpermute_b32 v151, v138, v69
	s_waitcnt lgkmcnt(4)
	v_add_f32 v144, v96, v90
	v_add_f32 v145, v97, v91
	s_waitcnt lgkmcnt(3)
	v_add_f32 v96, v98, v92
	v_add_f32 v97, v99, v93
	s_waitcnt lgkmcnt(1)
	v_add_f32 v94, v94, v80
	v_add_f32 v95, v95, v81
	v_add_f32 v98, v144, v96
	v_add_f32 v99, v145, v97
	s_waitcnt lgkmcnt(0)
	v_add_f32_e32 v138, v69, v151
	v_add_f32 v144, v94, v98
	v_add_f32 v145, v95, v99
	s_nop 0
	v_add_f32 v94, v138, v144
	v_add_f32 v95, v139, v145
	s_nop 0
	v_add_f32_e32 v69, v94, v95
	v_cmp_gt_f32_e64 s[12:13], s12, v69
	s_cmp_eq_u64 s[12:13], exec
	s_cselect_b64 s[12:13], -1, 0
	s_xor_b64 s[22:23], s[38:39], -1
	s_and_b64 s[26:27], s[22:23], s[12:13]
	s_and_saveexec_b64 s[22:23], s[26:27]
	v_lshl_add_u32 v94, s25, 5, v163
	s_or_b64 s[12:13], s[12:13], exec
	ds_write_b32 v94, v209
	s_or_b64 exec, exec, s[22:23]
	v_add_f32_e32 v99, v139, v99
	v_cndmask_b32_e64 v81, 0, v81, s[42:43]
	v_add_f32_e32 v81, v81, v99
	v_add_f32_e32 v77, v77, v81
	v_add_f32_e32 v75, v75, v77
	v_add_f32_e32 v73, v73, v75
	v_cndmask_b32_e64 v138, v216, v181, s[70:71]
	v_cndmask_b32_e64 v145, v216, v183, s[74:75]
	v_add_f32_e32 v71, v71, v73
	v_add_f32_e32 v73, v145, v73
	v_add_f32_e32 v71, v138, v71
	v_exp_f32_e32 v145, v73
	v_exp_f32_e32 v138, v71
	v_add_f32_e32 v71, v139, v97
	v_cndmask_b32_e64 v73, 0, v91, s[42:43]
	v_add_f32_e32 v71, v73, v71
	v_cndmask_b32_e64 v152, v216, v198, s[76:77]
	v_cndmask_b32_e64 v183, v216, v203, s[92:93]
	v_add_f32_e32 v71, v89, v71
	v_cndmask_b32_e64 v153, v216, v199, s[80:81]
	v_cndmask_b32_e64 v181, v216, v202, s[4:5]
	v_add_f32_e32 v75, v152, v75
	v_add_f32_e32 v73, v85, v71
	v_add_f32_e32 v71, v183, v71
	v_cndmask_b32_e64 v155, v216, v201, s[90:91]
	v_add_f32_e32 v77, v153, v77
	v_exp_f32_e32 v99, v75
	v_add_f32_e32 v75, v83, v73
	v_exp_f32_e32 v83, v71
	v_add_f32_e32 v71, v181, v73
	v_cndmask_b32_e64 v154, v216, v200, s[84:85]
	v_exp_f32_e32 v81, v77
	v_add_f32_e32 v77, v79, v75
	v_exp_f32_e32 v85, v71
	v_add_f32_e32 v71, v155, v75
	v_exp_f32_e32 v89, v71
	v_add_f32_e32 v71, v154, v77
	v_exp_f32_e32 v91, v71
	v_add_f32_e32 v71, v139, v93
	v_cndmask_b32_e64 v73, 0, v143, s[42:43]
	v_add_f32_e32 v71, v73, v71
	v_cndmask_b32_e64 v187, v216, v207, s[56:57]
	v_add_f32_e32 v71, v245, v71
	v_cndmask_b32_e64 v186, v216, v206, s[54:55]
	v_add_f32_e32 v73, v244, v71
	v_add_f32_e32 v71, v187, v71
	v_cndmask_b32_e64 v185, v216, v205, s[52:53]
	v_add_f32_e32 v75, v242, v73
	v_exp_f32_e32 v93, v71
	v_add_f32_e32 v71, v186, v73
	v_cndmask_b32_e64 v184, v216, v204, s[50:51]
	v_add_f32_e32 v77, v240, v75
	v_exp_f32_e32 v97, v71
	v_add_f32_e32 v71, v185, v75
	v_add_f32_e32 v94, 0, v139
	v_exp_f32_e32 v139, v71
	v_add_f32_e32 v71, v184, v77
	v_exp_f32_e32 v143, v71
	v_cndmask_b32_e64 v71, 0, v147, s[42:43]
	v_add_f32_e32 v71, v94, v71
	v_add_f32_e32 v98, v98, v95
	v_cndmask_b32_e64 v80, 0, v80, s[42:43]
	v_cndmask_b32_e64 v199, v216, v223, s[64:65]
	v_add_f32_e32 v71, v243, v71
	v_add_f32_e32 v80, v80, v98
	v_cndmask_b32_e64 v198, v216, v222, s[62:63]
	v_add_f32_e32 v73, v241, v71
	v_add_f32_e32 v71, v199, v71
	v_add_f32_e32 v76, v76, v80
	v_cndmask_b32_e64 v197, v216, v221, s[60:61]
	v_add_f32_e32 v75, v239, v73
	v_exp_f32_e32 v94, v71
	v_add_f32_e32 v71, v198, v73
	v_add_f32_e32 v74, v74, v76
	v_cndmask_b32_e64 v196, v216, v220, s[58:59]
	v_add_f32_e32 v77, v224, v75
	v_exp_f32_e32 v147, v71
	v_add_f32_e32 v71, v197, v75
	v_add_f32_e32 v72, v72, v74
	v_exp_f32_e32 v152, v71
	v_add_f32_e32 v71, v196, v77
	v_cndmask_b32_e64 v77, v216, v226, s[8:9]
	v_add_f32_e32 v70, v70, v72
	v_cndmask_b32_e64 v79, v216, v227, s[44:45]
	v_add_f32_e32 v70, v77, v70
	v_add_f32_e32 v72, v79, v72
	v_exp_f32_e32 v77, v70
	v_add_f32_e32 v70, v96, v95
	v_cndmask_b32_e64 v79, 0, v90, s[42:43]
	v_add_f32_e32 v70, v79, v70
	v_cndmask_b32_e64 v183, v216, v234, s[10:11]
	v_add_f32_e32 v70, v88, v70
	v_cndmask_b32_e64 v181, v216, v233, s[72:73]
	v_add_f32_e32 v79, v84, v70
	v_add_f32_e32 v70, v183, v70
	v_cndmask_b32_e64 v73, v216, v180, s[96:97]
	v_cndmask_b32_e64 v180, v216, v232, s[68:69]
	v_add_f32_e32 v80, v82, v79
	v_exp_f32_e32 v82, v70
	v_add_f32_e32 v70, v181, v79
	v_exp_f32_e32 v153, v71
	v_cndmask_b32_e64 v71, v216, v179, s[94:95]
	v_cndmask_b32_e64 v179, v216, v231, s[66:67]
	v_add_f32_e32 v78, v78, v80
	v_exp_f32_e32 v79, v70
	v_add_f32_e32 v70, v180, v80
	v_add_f32_e32 v144, v144, v95
	v_cndmask_b32_e64 v151, 0, v151, s[42:43]
	v_exp_f32_e32 v80, v70
; #define FA_SBAR() __builtin_amdgcn_sched_barrier(0)
; template <int OFF> DEVI s16x4 tr_read(int vb) { s16x4 r; asm volatile("ds_read_b64_tr_b16 %0, %1 offset:%2" : "=&v"(r) : "v"(vb), "i"(OFF) : "memory"); return r; }
; template <int D0> DEVI void pv_one(f32x16& od, int vb, bf16x8 pa0, bf16x8 pa1, bf16x8 pa2, bf16x8 pa3) {
;     const s16x4 l0 = tr_read<v_rd_off(D0, 0, 0)>(vb), h0 = tr_read<v_rd_off(D0, 0, 1)>(vb), l1 = tr_read<v_rd_off(D0, 1, 0)>(vb), h1 = tr_read<v_rd_off(D0, 1, 1)>(vb);
;     const s16x4 l2 = tr_read<v_rd_off(D0, 2, 0)>(vb), h2 = tr_read<v_rd_off(D0, 2, 1)>(vb), l3 = tr_read<v_rd_off(D0, 3, 0)>(vb), h3 = tr_read<v_rd_off(D0, 3, 1)>(vb);
;     asm volatile("s_waitcnt lgkmcnt(0)" ::: "memory"); FA_SBAR();
;     ...
;     od = __builtin_amdgcn_mfma_f32_32x32x16_bf16(pa0, FA_PK(l0, h0), od, 0, 0, 0);
;     od = __builtin_amdgcn_mfma_f32_32x32x16_bf16(pa1, FA_PK(l1, h1), od, 0, 0, 0);
;     od = __builtin_amdgcn_mfma_f32_32x32x16_bf16(pa2, FA_PK(l2, h2), od, 0, 0, 0);
;     od = __builtin_amdgcn_mfma_f32_32x32x16_bf16(pa3, FA_PK(l3, h3), od, 0, 0, 0);
;     ...
; }
; DEVI void pv_d0(f32x16* o, int vb, bf16x8 pa0, bf16x8 pa1, bf16x8 pa2, bf16x8 pa3) {
;     pv_one<0>(o[0], vb, pa0, pa1, pa2, pa3); pv_one<1>(o[1], vb, pa0, pa1, pa2, pa3); pv_one<2>(o[2], vb, pa0, pa1, pa2, pa3); pv_one<3>(o[3], vb, pa0, pa1, pa2, pa3);
; }
; DEVI void pack_p(const f32x16& p0, const f32x16& p1, bf16x8& pa0, bf16x8& pa1, bf16x8& pa2, bf16x8& pa3) {
;     ...
;     FA_PK4(p0, 0, pa0); FA_PK4(p0, 8, pa1); FA_PK4(p1, 0, pa2); FA_PK4(p1, 8, pa3);
; template <int MODE>
; DEVI void attn_unit(LAS unsigned char* lds, const bf16_t* Qw, int ldq, const bf16_t* Kb, const bf16_t* Vb, int ldk, bf16_t* Ow, int ldo,
;                     int j_first, int ntiles, int jstep, int wj_lo, int wj_hi, int t0) {
;     ...
;                 if (__all(carry < -152.f)) { mydone = true; if (lane == 0) dflag[(i & 1) * 8 + wid] = 1u; }
;                 pack_p(p0, p1, pa0, pa1, pa2, pa3);
;     ...
;             pv_d0(o, vb0 + buf * SHM_V, pa0, pa1, pa2, pa3);
	v_add_f32_e32 v70, v179, v78
	v_add_f32_e32 v144, v151, v144
	v_exp_f32_e32 v78, v70
	v_add_f32_e32 v70, 0, v95
	v_cndmask_b32_e64 v84, 0, v92, s[42:43]
	v_add_f32_e32 v144, v150, v144
	v_add_f32_e32 v70, v84, v70
	v_cndmask_b32_e64 v187, v216, v238, s[88:89]
	v_add_f32_e32 v149, v149, v144
	v_add_f32_e32 v70, v146, v70
	v_cndmask_b32_e64 v186, v216, v237, s[86:87]
	v_add_f32_e32 v148, v148, v149
	v_add_f32_e32 v84, v87, v70
	v_add_f32_e32 v70, v187, v70
	v_cndmask_b32_e64 v2, v216, v2, s[6:7]
	v_cndmask_b32_e32 v75, v216, v225, vcc
	v_cndmask_b32_e64 v154, v216, v229, s[46:47]
	v_cndmask_b32_e64 v155, v216, v230, s[48:49]
	v_cndmask_b32_e64 v185, v216, v236, s[82:83]
	v_add_f32_e32 v142, v142, v148
	v_add_f32_e32 v86, v86, v84
	v_exp_f32_e32 v87, v70
	v_add_f32_e32 v70, v186, v84
	v_cndmask_b32_e64 v184, v216, v235, s[78:79]
	v_add_f32_e32 v75, v75, v144
	v_add_f32_e32 v73, v73, v149
	v_add_f32_e32 v71, v71, v148
	v_add_f32_e32 v2, v2, v142
	v_add_f32_e32 v76, v155, v76
	v_add_f32_e32 v74, v154, v74
	v_add_f32_e32 v68, v68, v86
	v_exp_f32_e32 v84, v70
	v_add_f32_e32 v70, v185, v86
	v_exp_f32_e32 v75, v75
	v_exp_f32_e32 v73, v73
	v_exp_f32_e32 v71, v71
	v_exp_f32_e32 v2, v2
	v_exp_f32_e32 v76, v76
	v_exp_f32_e32 v74, v74
	v_exp_f32_e32 v72, v72
	v_exp_f32_e32 v86, v70
	v_add_f32_e32 v68, v184, v68
	v_exp_f32_e32 v68, v68
	v_cvt_pk_bf16_f32 v70, v2, v71
	v_cvt_pk_bf16_f32 v71, v73, v75
	v_cvt_pk_bf16_f32 v72, v77, v72
	v_cvt_pk_bf16_f32 v73, v74, v76
	v_cvt_pk_bf16_f32 v74, v78, v80
	v_cvt_pk_bf16_f32 v75, v79, v82
	v_cvt_pk_bf16_f32 v76, v68, v86
	v_cvt_pk_bf16_f32 v77, v84, v87
	v_cvt_pk_bf16_f32 v78, v138, v145
	v_cvt_pk_bf16_f32 v79, v99, v81
	v_cvt_pk_bf16_f32 v80, v91, v89
	v_cvt_pk_bf16_f32 v81, v85, v83
	v_cvt_pk_bf16_f32 v82, v143, v139
	v_cvt_pk_bf16_f32 v83, v97, v93
	v_cvt_pk_bf16_f32 v84, v153, v152
	v_cvt_pk_bf16_f32 v85, v147, v94
	v_add_u32_e32 v2, s1, v177
	ds_read_b64_tr_b16 v[86:87], v2 offset:0
	ds_read_b64_tr_b16 v[88:89], v2 offset:0x800
	ds_read_b64_tr_b16 v[90:91], v2 offset:0x1000
	ds_read_b64_tr_b16 v[92:93], v2 offset:0x1800
	ds_read_b64_tr_b16 v[94:95], v2 offset:0x2000
	ds_read_b64_tr_b16 v[96:97], v2 offset:0x2800
	ds_read_b64_tr_b16 v[142:143], v2 offset:0x3000
	ds_read_b64_tr_b16 v[144:145], v2 offset:0x3800
	s_waitcnt lgkmcnt(0)
	v_permlane32_swap_b32_e32 v70, v72
	v_permlane32_swap_b32_e32 v71, v73
	v_permlane32_swap_b32_e32 v74, v76
	v_permlane32_swap_b32_e32 v75, v77
	v_permlane32_swap_b32_e32 v78, v80
	v_permlane32_swap_b32_e32 v79, v81
	v_permlane32_swap_b32_e32 v82, v84
	v_permlane32_swap_b32_e32 v83, v85
	v_mfma_f32_32x32x16_bf16 v[4:19], v[70:73], v[86:89], v[4:19]
	ds_read_b64_tr_b16 v[86:87], v2 offset:0x200
	ds_read_b64_tr_b16 v[88:89], v2 offset:0xa00
	v_mfma_f32_32x32x16_bf16 v[4:19], v[74:77], v[90:93], v[4:19]
	ds_read_b64_tr_b16 v[90:91], v2 offset:0x1200
	ds_read_b64_tr_b16 v[92:93], v2 offset:0x1a00
	v_mfma_f32_32x32x16_bf16 v[4:19], v[78:81], v[94:97], v[4:19]
	ds_read_b64_tr_b16 v[94:95], v2 offset:0x2200
	ds_read_b64_tr_b16 v[96:97], v2 offset:0x2a00
	v_mfma_f32_32x32x16_bf16 v[4:19], v[82:85], v[142:145], v[4:19]
	ds_read_b64_tr_b16 v[142:143], v2 offset:0x3200
	ds_read_b64_tr_b16 v[144:145], v2 offset:0x3a00
	s_waitcnt lgkmcnt(0)
	v_mfma_f32_32x32x16_bf16 v[20:35], v[70:73], v[86:89], v[20:35]
	ds_read_b64_tr_b16 v[86:87], v2 offset:0x400
	ds_read_b64_tr_b16 v[88:89], v2 offset:0xc00
	v_mfma_f32_32x32x16_bf16 v[20:35], v[74:77], v[90:93], v[20:35]
	ds_read_b64_tr_b16 v[90:91], v2 offset:0x1400
	ds_read_b64_tr_b16 v[92:93], v2 offset:0x1c00
	v_mfma_f32_32x32x16_bf16 v[20:35], v[78:81], v[94:97], v[20:35]
	ds_read_b64_tr_b16 v[94:95], v2 offset:0x2400
	ds_read_b64_tr_b16 v[96:97], v2 offset:0x2c00
	v_mfma_f32_32x32x16_bf16 v[20:35], v[82:85], v[142:145], v[20:35]
	ds_read_b64_tr_b16 v[142:143], v2 offset:0x3400
	ds_read_b64_tr_b16 v[144:145], v2 offset:0x3c00
	s_waitcnt lgkmcnt(0)
	v_mfma_f32_32x32x16_bf16 v[36:51], v[70:73], v[86:89], v[36:51]
	ds_read_b64_tr_b16 v[86:87], v2 offset:0x600
	ds_read_b64_tr_b16 v[88:89], v2 offset:0xe00
	v_mfma_f32_32x32x16_bf16 v[36:51], v[74:77], v[90:93], v[36:51]
	ds_read_b64_tr_b16 v[90:91], v2 offset:0x1600
	ds_read_b64_tr_b16 v[92:93], v2 offset:0x1e00
	v_mfma_f32_32x32x16_bf16 v[36:51], v[78:81], v[94:97], v[36:51]
	ds_read_b64_tr_b16 v[94:95], v2 offset:0x2600
	ds_read_b64_tr_b16 v[96:97], v2 offset:0x2e00
	v_mfma_f32_32x32x16_bf16 v[36:51], v[82:85], v[142:145], v[36:51]
	ds_read_b64_tr_b16 v[142:143], v2 offset:0x3600
	ds_read_b64_tr_b16 v[144:145], v2 offset:0x3e00
	s_waitcnt lgkmcnt(0)
	v_mfma_f32_32x32x16_bf16 v[52:67], v[70:73], v[86:89], v[52:67]
	s_andn2_b64 s[4:5], s[14:15], exec
	s_and_b64 s[6:7], s[12:13], exec
	s_or_b64 s[14:15], s[4:5], s[6:7]
	v_mov_b32_e32 v139, v69
	v_mfma_f32_32x32x16_bf16 v[52:67], v[74:77], v[90:93], v[52:67]
	v_mfma_f32_32x32x16_bf16 v[52:67], v[78:81], v[94:97], v[52:67]
	v_mfma_f32_32x32x16_bf16 v[52:67], v[82:85], v[142:145], v[52:67]

; #define LAS __attribute__((address_space(3)))
; DEVI int crow(int r, int hi) { return (r & 3) + 8 * (r >> 2) + 4 * hi; }
; DEVI void indexer_phase(LAS unsigned char* lds, const bf16_t* EV, float* SC) {
;     ...
;             for (int h = 0; h < 16; ++h) {
;                 bf16x8 qf[4];
; #pragma unroll
;                 for (int ks = 0; ks < 4; ++ks) qf[ks] = *(LAS const bf16x8*)(lds + r32 * 2064 + (h * 64 + 16 * ks + 8 * hi) * 2);
;                 f32x4 wv[4];
; #pragma unroll
;                 for (int a4 = 0; a4 < 4; ++a4) wv[a4] = *(LAS const f32x4*)(wl + h * 32 + 8 * a4 + 4 * hi);
;                 f32x16 s0 = (f32x16){0.f, 0.f, 0.f, 0.f, 0.f, 0.f, 0.f, 0.f, 0.f, 0.f, 0.f, 0.f, 0.f, 0.f, 0.f, 0.f}, s1 = s0;
; #pragma unroll
;                 for (int ks = 0; ks < 4; ++ks) { s0 = __builtin_amdgcn_mfma_f32_32x32x16_bf16(qf[ks], kf[0][ks], s0, 0, 0, 0); s1 = __builtin_amdgcn_mfma_f32_32x32x16_bf16(qf[ks], kf[1][ks], s1, 0, 0, 0); }
; #pragma unroll
;                 for (int r = 0; r < 16; ++r) { const float w = wv[r >> 2][r & 3];
;                     const float z0 = __int_as_float(max(__float_as_int(s0[r]), 0)), z1 = __int_as_float(max(__float_as_int(s1[r]), 0)); acc0[r] = fmaf(w, z0, acc0[r]); acc1[r] = fmaf(w, z1, acc1[r]); }
;             }
; #pragma unroll
;             for (int r = 0; r < 16; ++r) { float* sp = SC + (size_t)(m0 + crow(r, hi)) * SEQ + 64 * j + r32; sp[0] = acc0[r]; sp[32] = acc1[r]; }
.LBB11_1273:
	v_add_u32_e32 v8, s11, v143
	ds_read_b128 v[4:7], v8
	ds_read_b128 v[164:167], v8 offset:32
	ds_read_b128 v[168:171], v8 offset:64
	ds_read_b128 v[172:175], v8 offset:96
	v_add_u32_e32 v8, s11, v142
	v_add_u32_e32 v9, 0x10400, v8
	ds_read_b128 v[176:179], v9
	v_add_u32_e32 v9, 0x10420, v8
	ds_read_b128 v[198:201], v9
	v_add_u32_e32 v9, 0x10440, v8
	v_add_u32_e32 v8, 0x10460, v8
	ds_read_b128 v[202:205], v9
	ds_read_b128 v[220:223], v8
	s_waitcnt vmcnt(5) lgkmcnt(7)
	v_mfma_f32_32x32x16_bf16 v[20:35], v[4:7], v[44:47], 0
	s_addk_i32 s11, 0x80
	s_cmpk_eq_i32 s11, 0x800
	s_waitcnt vmcnt(1)
	v_mfma_f32_32x32x16_bf16 v[4:19], v[4:7], v[60:63], 0
	s_waitcnt lgkmcnt(6)
	v_mfma_f32_32x32x16_bf16 v[4:19], v[164:167], v[52:55], v[4:19]
	v_mfma_f32_32x32x16_bf16 v[20:35], v[164:167], v[36:39], v[20:35]
	s_waitcnt lgkmcnt(5)
	v_mfma_f32_32x32x16_bf16 v[4:19], v[168:171], v[56:59], v[4:19]
	v_mfma_f32_32x32x16_bf16 v[20:35], v[168:171], v[40:43], v[20:35]
	s_waitcnt vmcnt(0) lgkmcnt(4)
	v_mfma_f32_32x32x16_bf16 v[4:19], v[172:175], v[64:67], v[4:19]
	v_mfma_f32_32x32x16_bf16 v[20:35], v[172:175], v[48:51], v[20:35]
	s_nop 10
	v_max_i32_e32 v5, 0, v5
	v_max_i32_e32 v4, 0, v4
	s_waitcnt lgkmcnt(3)
	v_fma_f32 v128, v176, v4, v128
	v_fma_f32 v129, v177, v5, v129
	v_max_i32_e32 v5, 0, v23
	v_max_i32_e32 v4, 0, v22
	v_fma_f32 v136, v178, v4, v136
	v_fma_f32 v137, v179, v5, v137
	v_max_i32_e32 v5, 0, v7
	v_max_i32_e32 v4, 0, v6
	v_fma_f32 v124, v178, v4, v124
	v_fma_f32 v125, v179, v5, v125
	v_max_i32_e32 v5, 0, v25
	v_max_i32_e32 v4, 0, v24
	s_waitcnt lgkmcnt(2)
	v_fma_f32 v134, v198, v4, v134
	v_fma_f32 v135, v199, v5, v135
	v_max_i32_e32 v5, 0, v9
	v_max_i32_e32 v4, 0, v8
	v_fma_f32 v120, v198, v4, v120
	v_fma_f32 v121, v199, v5, v121
	v_max_i32_e32 v5, 0, v27
	v_max_i32_e32 v4, 0, v26
	v_fma_f32 v132, v200, v4, v132
	v_fma_f32 v133, v201, v5, v133
	v_max_i32_e32 v5, 0, v11
	v_max_i32_e32 v4, 0, v10
	v_fma_f32 v118, v200, v4, v118
	v_fma_f32 v119, v201, v5, v119
	v_max_i32_e32 v5, 0, v29
	v_max_i32_e32 v4, 0, v28
	s_waitcnt lgkmcnt(1)
	v_fma_f32 v130, v202, v4, v130
	v_fma_f32 v131, v203, v5, v131
	v_max_i32_e32 v5, 0, v13
	v_max_i32_e32 v4, 0, v12
	v_fma_f32 v116, v202, v4, v116
	v_fma_f32 v117, v203, v5, v117
	v_max_i32_e32 v5, 0, v31
	v_max_i32_e32 v4, 0, v30
	v_fma_f32 v126, v204, v4, v126
	v_fma_f32 v127, v205, v5, v127
	v_max_i32_e32 v5, 0, v15
	v_max_i32_e32 v4, 0, v14
	v_fma_f32 v114, v204, v4, v114
	v_fma_f32 v115, v205, v5, v115
	v_max_i32_e32 v5, 0, v33
	v_max_i32_e32 v4, 0, v32
	s_waitcnt lgkmcnt(0)
	v_fma_f32 v122, v220, v4, v122
	v_fma_f32 v123, v221, v5, v123
	v_max_i32_e32 v5, 0, v17
	v_max_i32_e32 v4, 0, v16
	v_fma_f32 v112, v220, v4, v112
	v_fma_f32 v113, v221, v5, v113
	v_max_i32_e32 v5, 0, v35
	v_max_i32_e32 v4, 0, v34
	v_max_i32_e32 v21, 0, v21
	v_max_i32_e32 v20, 0, v20
	v_fma_f32 v110, v222, v4, v110
	v_fma_f32 v111, v223, v5, v111
	v_max_i32_e32 v5, 0, v19
	v_max_i32_e32 v4, 0, v18
	v_fma_f32 v138, v176, v20, v138
	v_fma_f32 v139, v177, v21, v139
	v_fma_f32 v106, v222, v4, v106
	v_fma_f32 v107, v223, v5, v107
	s_cbranch_scc0 .LBB11_1273
	v_ashrrev_i32_e32 v109, 31, v108
	v_lshl_add_u64 v[4:5], v[108:109], 2, v[70:71]
	v_lshl_add_u64 v[6:7], v[4:5], 0, v[74:75]
	global_store_dword v[6:7], v138, off
	global_store_dword v[6:7], v128, off offset:128
	v_lshl_add_u64 v[6:7], v[4:5], 0, v[76:77]
	global_store_dword v[6:7], v139, off
	global_store_dword v[6:7], v129, off offset:128
	v_lshl_add_u64 v[6:7], v[4:5], 0, v[78:79]
	global_store_dword v[6:7], v136, off
	global_store_dword v[6:7], v124, off offset:128
	v_lshl_add_u64 v[6:7], v[4:5], 0, v[80:81]
	global_store_dword v[6:7], v137, off
	global_store_dword v[6:7], v125, off offset:128
	v_lshl_add_u64 v[6:7], v[4:5], 0, v[82:83]
	global_store_dword v[6:7], v134, off
	global_store_dword v[6:7], v120, off offset:128
	v_lshl_add_u64 v[6:7], v[4:5], 0, v[84:85]
	global_store_dword v[6:7], v135, off
	global_store_dword v[6:7], v121, off offset:128
	v_lshl_add_u64 v[6:7], v[4:5], 0, v[86:87]
	global_store_dword v[6:7], v132, off
	global_store_dword v[6:7], v118, off offset:128
	v_lshl_add_u64 v[6:7], v[4:5], 0, v[88:89]
	global_store_dword v[6:7], v133, off
	global_store_dword v[6:7], v119, off offset:128
	v_lshl_add_u64 v[6:7], v[4:5], 0, v[90:91]
	global_store_dword v[6:7], v130, off
	global_store_dword v[6:7], v116, off offset:128
	v_lshl_add_u64 v[6:7], v[4:5], 0, v[92:93]
	global_store_dword v[6:7], v131, off
	global_store_dword v[6:7], v117, off offset:128
	v_lshl_add_u64 v[6:7], v[4:5], 0, v[94:95]
	global_store_dword v[6:7], v126, off
	global_store_dword v[6:7], v114, off offset:128
	v_lshl_add_u64 v[6:7], v[4:5], 0, v[96:97]
	global_store_dword v[6:7], v127, off
	global_store_dword v[6:7], v115, off offset:128
	v_lshl_add_u64 v[6:7], v[4:5], 0, v[98:99]
	v_add_u32_e32 v162, 8, v162
	global_store_dword v[6:7], v122, off
	global_store_dword v[6:7], v112, off offset:128
	v_lshl_add_u64 v[6:7], v[4:5], 0, v[100:101]
	v_cmp_lt_i32_e32 vcc, s10, v162
	global_store_dword v[6:7], v123, off
	global_store_dword v[6:7], v113, off offset:128
	v_lshl_add_u64 v[6:7], v[4:5], 0, v[102:103]
	v_lshl_add_u64 v[4:5], v[4:5], 0, v[104:105]
	s_or_b64 s[6:7], vcc, s[6:7]
	global_store_dword v[6:7], v110, off
	global_store_dword v[6:7], v106, off offset:128
	global_store_dword v[4:5], v111, off
	global_store_dword v[4:5], v107, off offset:128
	s_andn2_b64 exec, exec, s[6:7]
	s_cbranch_execnz .LBB11_1272
	s_branch .LBB11_1269

; DEVI int crow(int r, int hi) { return (r & 3) + 8 * (r >> 2) + 4 * hi; }
; template <int MODE>
; DEVI void attn_unit(LAS unsigned char* lds, const bf16_t* Qw, int ldq, const bf16_t* Kb, const bf16_t* Vb, int ldk, bf16_t* Ow, int ldo,
;                     int j_first, int ntiles, int jstep, int wj_lo, int wj_hi, int t0) {
;     ...
;                 if (!__all(pm2 - m_reg <= 8.f)) {
;                     mn = fmaxf(m_reg, pm2); const float alpha = __builtin_amdgcn_exp2f(m_reg - mn); m_reg = mn; l_reg *= alpha;
;                     if (hi == 0) al_l[r32] = alpha; asm volatile("s_waitcnt lgkmcnt(0)" ::: "memory");
; #pragma unroll
;                     for (int r = 0; r < 16; ++r) { const float af = al_l[crow(r, hi)];
; #pragma unroll
;                         for (int d = 0; d < 4; ++d) o[d][r] *= af; }
.LBB11_1284:
	s_or_b64 exec, exec, s[4:5]
	v_mul_f32_e32 v68, v68, v2
	s_waitcnt lgkmcnt(0)
	v_add_u32_e32 v2, v222, v202
	ds_read_b128 v[104:107], v2 offset:128
	ds_read_b128 v[108:111], v2 offset:160
	ds_read_b128 v[112:115], v2 offset:192
	ds_read_b128 v[116:119], v2 offset:224
	s_waitcnt lgkmcnt(3)
	v_mul_f32 v54, v54, v106
	v_mul_f32 v55, v55, v107
	s_waitcnt lgkmcnt(2)
	v_mul_f32 v56, v56, v108
	v_mul_f32 v57, v57, v109
	s_waitcnt lgkmcnt(1)
	v_mul_f32 v60, v60, v112
	v_mul_f32 v61, v61, v113
	s_waitcnt lgkmcnt(0)
	v_mul_f32 v64, v64, v116
	v_mul_f32 v65, v65, v117
	v_mul_f32 v66, v66, v118
	v_mul_f32 v67, v67, v119
	v_mul_f32 v62, v62, v114
	v_mul_f32 v63, v63, v115
	v_mul_f32 v58, v58, v110
	v_mul_f32 v59, v59, v111
	v_mul_f32 v52, v52, v104
	v_mul_f32 v53, v53, v105
	v_mul_f32 v48, v48, v116
	v_mul_f32 v49, v49, v117
	v_mul_f32 v44, v44, v112
	v_mul_f32 v45, v45, v113
	v_mul_f32 v40, v40, v108
	v_mul_f32 v41, v41, v109
	v_mul_f32 v50, v50, v118
	v_mul_f32 v51, v51, v119
	v_mul_f32 v46, v46, v114
	v_mul_f32 v47, v47, v115
	v_mul_f32 v42, v42, v110
	v_mul_f32 v43, v43, v111
	v_mul_f32 v38, v38, v106
	v_mul_f32 v39, v39, v107
	v_mul_f32 v36, v36, v104
	v_mul_f32 v37, v37, v105
	v_mul_f32 v32, v32, v116
	v_mul_f32 v33, v33, v117
	v_mul_f32 v28, v28, v112
	v_mul_f32 v29, v29, v113
	v_mul_f32 v24, v24, v108
	v_mul_f32 v25, v25, v109
	v_mul_f32 v34, v34, v118
	v_mul_f32 v35, v35, v119
	v_mul_f32 v30, v30, v114
	v_mul_f32 v31, v31, v115
	v_mul_f32 v26, v26, v110
	v_mul_f32 v27, v27, v111
	v_mul_f32 v22, v22, v106
	v_mul_f32 v23, v23, v107
	v_mul_f32 v20, v20, v104
	v_mul_f32 v21, v21, v105
	v_mul_f32 v16, v16, v116
	v_mul_f32 v17, v17, v117
	v_mul_f32 v12, v12, v112
	v_mul_f32 v13, v13, v113
	v_mul_f32 v8, v8, v108
	v_mul_f32 v9, v9, v109
	v_mul_f32 v18, v18, v118
	v_mul_f32 v19, v19, v119
	v_mul_f32 v14, v14, v114
	v_mul_f32 v15, v15, v115
	v_mul_f32 v10, v10, v110
	v_mul_f32 v11, v11, v111
	v_mul_f32 v6, v6, v106
	v_mul_f32 v7, v7, v107
	v_mul_f32 v4, v4, v104
	v_mul_f32 v5, v5, v105
; #define FA_SBAR() __builtin_amdgcn_sched_barrier(0)
; template <int D0> DEVI void pv_one(f32x16& od, int vb, bf16x8 pa0, bf16x8 pa1, bf16x8 pa2, bf16x8 pa3) {
;     const s16x4 l0 = tr_read<v_rd_off(D0, 0, 0)>(vb), h0 = tr_read<v_rd_off(D0, 0, 1)>(vb), l1 = tr_read<v_rd_off(D0, 1, 0)>(vb), h1 = tr_read<v_rd_off(D0, 1, 1)>(vb);
;     const s16x4 l2 = tr_read<v_rd_off(D0, 2, 0)>(vb), h2 = tr_read<v_rd_off(D0, 2, 1)>(vb), l3 = tr_read<v_rd_off(D0, 3, 0)>(vb), h3 = tr_read<v_rd_off(D0, 3, 1)>(vb);
;     asm volatile("s_waitcnt lgkmcnt(0)" ::: "memory"); FA_SBAR();
;     ...
;     od = __builtin_amdgcn_mfma_f32_32x32x16_bf16(pa0, FA_PK(l0, h0), od, 0, 0, 0);
;     od = __builtin_amdgcn_mfma_f32_32x32x16_bf16(pa1, FA_PK(l1, h1), od, 0, 0, 0);
; template <int MODE>
; DEVI void attn_unit(LAS unsigned char* lds, const bf16_t* Qw, int ldq, const bf16_t* Kb, const bf16_t* Vb, int ldk, bf16_t* Ow, int ldo,
;                     int j_first, int ntiles, int jstep, int wj_lo, int wj_hi, int t0) {
;     ...
;                 if constexpr (MODE == M_BAND) {
; #pragma unroll
;                     for (int r = 0; r < 16; ++r) { p0[r] = __builtin_amdgcn_exp2f(p0[r] - mn); p1[r] = __builtin_amdgcn_exp2f(p1[r] - mn); }
;                 } else { const float nmn = -mn;
; #pragma unroll
;                     for (int r = 0; r < 16; ++r) { p0[r] = __builtin_amdgcn_exp2f(fmaf(p0[r], C2, nmn)); p1[r] = __builtin_amdgcn_exp2f(fmaf(p1[r], C2, nmn)); }
;                 }
;                 if constexpr (MODE == M_DSA) {
;                     const u64 mw = maskl[r32 * 32 + j]; const int mlo = (int)(unsigned)(mw >> (4 * hi)), mhi = (int)(unsigned)(mw >> (32 + 4 * hi));
; #pragma unroll
;                     for (int r = 0; r < 16; ++r) { const int kbit = (r & 3) + 8 * (r >> 2);
;                         unsigned ma, mb; asm("v_bfe_i32 %0, %1, %2, 1" : "=v"(ma) : "v"(mlo), "n"(kbit)); asm("v_bfe_i32 %0, %1, %2, 1" : "=v"(mb) : "v"(mhi), "n"(kbit));
;                         p0[r] = __uint_as_float(__float_as_uint(p0[r]) & ma); p1[r] = __uint_as_float(__float_as_uint(p1[r]) & mb); }
;                 }
;                 float ps = 0.f;
; #pragma unroll
;                 for (int r = 0; r < 16; ++r) ps += p0[r] + p1[r];
;                 l_reg += ps;
;                 pack_p(p0, p1, pa0, pa1, pa2, pa3);
;             }
;             pv_d0(o, vb0 + buf * SHM_V, pa0, pa1, pa2, pa3);
.LBB11_1285:
	v_sub_f32_e32 v2, v70, v102
	v_exp_f32_e32 v103, v2
	v_sub_f32_e32 v2, v86, v102
	v_exp_f32_e32 v104, v2
	v_sub_f32_e32 v2, v71, v102
	v_sub_f32_e32 v71, v72, v102
	v_exp_f32_e32 v105, v71
	v_sub_f32_e32 v71, v88, v102
	v_exp_f32_e32 v106, v71
	v_sub_f32_e32 v71, v73, v102
	v_exp_f32_e32 v72, v71
	v_sub_f32_e32 v71, v89, v102
	v_exp_f32_e32 v86, v71
	v_sub_f32_e32 v71, v74, v102
	v_exp_f32_e32 v107, v71
	v_sub_f32_e32 v71, v90, v102
	v_exp_f32_e32 v108, v71
	v_sub_f32_e32 v71, v75, v102
	v_exp_f32_e32 v74, v71
	v_sub_f32_e32 v71, v91, v102
	v_exp_f32_e32 v88, v71
	v_sub_f32_e32 v71, v76, v102
	v_exp_f32_e32 v109, v71
	v_sub_f32_e32 v71, v92, v102
	v_exp_f32_e32 v110, v71
	v_sub_f32_e32 v71, v77, v102
	v_exp_f32_e32 v76, v71
	v_sub_f32_e32 v71, v93, v102
	v_exp_f32_e32 v90, v71
	v_sub_f32_e32 v71, v78, v102
	v_exp_f32_e32 v111, v71
	v_sub_f32_e32 v71, v94, v102
	v_exp_f32_e32 v112, v71
	v_sub_f32_e32 v71, v79, v102
	v_exp_f32_e32 v78, v71
	v_sub_f32_e32 v71, v95, v102
	v_exp_f32_e32 v92, v71
	v_sub_f32_e32 v71, v80, v102
	v_exp_f32_e32 v113, v71
	v_sub_f32_e32 v71, v96, v102
	v_exp_f32_e32 v114, v71
	v_sub_f32_e32 v71, v81, v102
	v_exp_f32_e32 v80, v71
	v_sub_f32_e32 v71, v97, v102
	v_exp_f32_e32 v94, v71
	v_sub_f32_e32 v71, v82, v102
	v_exp_f32_e32 v115, v71
	v_sub_f32_e32 v71, v98, v102
	v_exp_f32_e32 v116, v71
	v_sub_f32_e32 v71, v83, v102
	v_exp_f32_e32 v82, v71
	v_sub_f32_e32 v71, v99, v102
	v_exp_f32_e32 v70, v2
	v_sub_f32_e32 v2, v87, v102
	v_exp_f32_e32 v96, v71
	v_sub_f32_e32 v71, v84, v102
	v_exp_f32_e32 v2, v2
	v_exp_f32_e32 v117, v71
	v_sub_f32_e32 v71, v100, v102
	v_exp_f32_e32 v118, v71
	v_sub_f32_e32 v71, v85, v102
	v_exp_f32_e32 v84, v71
	v_sub_f32_e32 v71, v101, v102
	v_exp_f32_e32 v98, v71
	v_add_f32_e32 v71, v103, v104
	v_add_f32 v100, v70, v2
	v_add_f32 v101, v71, v3
	v_add_f32_e32 v73, v105, v106
	v_add_f32 v101, v100, v101
	v_add_f32 v100, v100, v100
	v_mov_b32_e32 v87, v101
	v_add_f32 v100, v72, v86
	v_add_f32 v101, v73, v87
	v_add_f32_e32 v75, v107, v108
	v_add_f32 v101, v100, v101
	v_add_f32 v100, v100, v100
	v_mov_b32_e32 v89, v101
	v_add_f32 v100, v74, v88
	v_add_f32 v101, v75, v89
	v_add_f32_e32 v77, v109, v110
	v_add_f32 v101, v100, v101
	v_add_f32 v100, v100, v100
	v_mov_b32_e32 v91, v101
	v_add_f32 v100, v76, v90
	v_add_f32 v101, v77, v91
	v_add_f32_e32 v79, v111, v112
	v_add_f32 v101, v100, v101
	v_add_f32 v100, v100, v100
	v_mov_b32_e32 v93, v101
	v_add_f32 v100, v78, v92
	v_add_f32 v101, v79, v93
	v_add_f32_e32 v81, v113, v114
	v_add_f32 v101, v100, v101
	v_add_f32 v100, v100, v100
	v_mov_b32_e32 v95, v101
	v_add_f32 v100, v80, v94
	v_add_f32 v101, v81, v95
	v_add_f32_e32 v83, v115, v116
	v_add_f32 v101, v100, v101
	v_add_f32 v100, v100, v100
	v_mov_b32_e32 v97, v101
	v_add_f32 v100, v82, v96
	v_add_f32 v101, v83, v97
	v_add_f32_e32 v85, v117, v118
	v_add_f32 v101, v100, v101
	v_add_f32 v100, v100, v100
	v_mov_b32_e32 v99, v101
	v_add_f32 v100, v84, v98
	v_add_f32 v101, v85, v99
	v_cvt_pk_bf16_f32 v70, v103, v70
	s_nop 0
	v_add_f32_e32 v71, v100, v101
	v_add_f32_e32 v68, v68, v71
	v_cvt_pk_bf16_f32 v71, v105, v72
	v_cvt_pk_bf16_f32 v72, v107, v74
	v_cvt_pk_bf16_f32 v73, v109, v76
	v_cvt_pk_bf16_f32 v74, v111, v78
	v_cvt_pk_bf16_f32 v75, v113, v80
	v_cvt_pk_bf16_f32 v76, v115, v82
	v_cvt_pk_bf16_f32 v77, v117, v84
	v_cvt_pk_bf16_f32 v78, v104, v2
	v_cvt_pk_bf16_f32 v79, v106, v86
	v_cvt_pk_bf16_f32 v80, v108, v88
	v_cvt_pk_bf16_f32 v81, v110, v90
	v_cvt_pk_bf16_f32 v82, v112, v92
	v_cvt_pk_bf16_f32 v83, v114, v94
	v_cvt_pk_bf16_f32 v84, v116, v96
	v_cvt_pk_bf16_f32 v85, v118, v98
	v_add_u32_e32 v2, s18, v242
	ds_read_b64_tr_b16 v[86:87], v2 offset:0
	ds_read_b64_tr_b16 v[88:89], v2 offset:0x800
	ds_read_b64_tr_b16 v[90:91], v2 offset:0x1000
	ds_read_b64_tr_b16 v[92:93], v2 offset:0x1800
	ds_read_b64_tr_b16 v[94:95], v2 offset:0x2000
	ds_read_b64_tr_b16 v[96:97], v2 offset:0x2800
	ds_read_b64_tr_b16 v[98:99], v2 offset:0x3000
	ds_read_b64_tr_b16 v[100:101], v2 offset:0x3800
	s_waitcnt lgkmcnt(0)
	v_permlane32_swap_b32_e32 v70, v72
	v_permlane32_swap_b32_e32 v71, v73
	v_permlane32_swap_b32_e32 v74, v76
	v_permlane32_swap_b32_e32 v75, v77
	v_permlane32_swap_b32_e32 v78, v80
	v_permlane32_swap_b32_e32 v79, v81
	v_permlane32_swap_b32_e32 v82, v84
	v_permlane32_swap_b32_e32 v83, v85
	v_mfma_f32_32x32x16_bf16 v[52:67], v[70:73], v[86:89], v[52:67]
	ds_read_b64_tr_b16 v[86:87], v2 offset:0x200
	ds_read_b64_tr_b16 v[88:89], v2 offset:0xa00
	v_mfma_f32_32x32x16_bf16 v[52:67], v[74:77], v[90:93], v[52:67]
	ds_read_b64_tr_b16 v[90:91], v2 offset:0x1200
	ds_read_b64_tr_b16 v[92:93], v2 offset:0x1a00
	v_mfma_f32_32x32x16_bf16 v[52:67], v[78:81], v[94:97], v[52:67]
	ds_read_b64_tr_b16 v[94:95], v2 offset:0x2200
	ds_read_b64_tr_b16 v[96:97], v2 offset:0x2a00
	v_mfma_f32_32x32x16_bf16 v[52:67], v[82:85], v[98:101], v[52:67]
	ds_read_b64_tr_b16 v[98:99], v2 offset:0x3200
	ds_read_b64_tr_b16 v[100:101], v2 offset:0x3a00
	s_waitcnt lgkmcnt(0)
	v_mfma_f32_32x32x16_bf16 v[36:51], v[70:73], v[86:89], v[36:51]
	ds_read_b64_tr_b16 v[86:87], v2 offset:0x400
	ds_read_b64_tr_b16 v[88:89], v2 offset:0xc00
	v_mfma_f32_32x32x16_bf16 v[36:51], v[74:77], v[90:93], v[36:51]
	ds_read_b64_tr_b16 v[90:91], v2 offset:0x1400
	ds_read_b64_tr_b16 v[92:93], v2 offset:0x1c00
	v_mfma_f32_32x32x16_bf16 v[36:51], v[78:81], v[94:97], v[36:51]
	ds_read_b64_tr_b16 v[94:95], v2 offset:0x2400
	ds_read_b64_tr_b16 v[96:97], v2 offset:0x2c00
	v_mfma_f32_32x32x16_bf16 v[36:51], v[82:85], v[98:101], v[36:51]
	ds_read_b64_tr_b16 v[98:99], v2 offset:0x3400
	ds_read_b64_tr_b16 v[100:101], v2 offset:0x3c00
	s_waitcnt lgkmcnt(0)
	v_mfma_f32_32x32x16_bf16 v[20:35], v[70:73], v[86:89], v[20:35]
	ds_read_b64_tr_b16 v[86:87], v2 offset:0x600
	ds_read_b64_tr_b16 v[88:89], v2 offset:0xe00
	v_mfma_f32_32x32x16_bf16 v[20:35], v[74:77], v[90:93], v[20:35]
	ds_read_b64_tr_b16 v[90:91], v2 offset:0x1600
	ds_read_b64_tr_b16 v[92:93], v2 offset:0x1e00
	v_mfma_f32_32x32x16_bf16 v[20:35], v[78:81], v[94:97], v[20:35]
	ds_read_b64_tr_b16 v[94:95], v2 offset:0x2600
	ds_read_b64_tr_b16 v[96:97], v2 offset:0x2e00
	v_mfma_f32_32x32x16_bf16 v[20:35], v[82:85], v[98:101], v[20:35]
	ds_read_b64_tr_b16 v[98:99], v2 offset:0x3600
	ds_read_b64_tr_b16 v[100:101], v2 offset:0x3e00
	s_waitcnt lgkmcnt(0)
	v_mfma_f32_32x32x16_bf16 v[4:19], v[70:73], v[86:89], v[4:19]
	v_mov_b32_e32 v244, v102
	v_mfma_f32_32x32x16_bf16 v[4:19], v[74:77], v[90:93], v[4:19]
	v_mfma_f32_32x32x16_bf16 v[4:19], v[78:81], v[94:97], v[4:19]
	v_mfma_f32_32x32x16_bf16 v[4:19], v[82:85], v[98:101], v[4:19]

; #define LAS __attribute__((address_space(3)))
; DEVI void qkt(f32x16& p0, f32x16& p1, LAS const unsigned char* Ks, const bf16x8* qr, int r32, int hi) {
;     p0 = (f32x16){0.f, 0.f, 0.f, 0.f, 0.f, 0.f, 0.f, 0.f, 0.f, 0.f, 0.f, 0.f, 0.f, 0.f, 0.f, 0.f}; p1 = p0;
; #pragma unroll
;     for (int d0 = 0; d0 < 8; ++d0) { const int cb = (d0 * 16 + hi * 8) * 2;
;         const bf16x8 b0 = *(LAS const bf16x8*)(Ks + FA_KSWZ(r32, cb));
;         const bf16x8 b1 = *(LAS const bf16x8*)(Ks + FA_KSWZ(32 + r32, cb));
;         p0 = __builtin_amdgcn_mfma_f32_32x32x16_bf16(b0, qr[d0], p0, 0, 0, 0);
;         p1 = __builtin_amdgcn_mfma_f32_32x32x16_bf16(b1, qr[d0], p1, 0, 0, 0); }
; }
; template <int MODE>
; DEVI void attn_unit(LAS unsigned char* lds, const bf16_t* Qw, int ldq, const bf16_t* Kb, const bf16_t* Vb, int ldk, bf16_t* Ow, int ldo,
;                     int j_first, int ntiles, int jstep, int wj_lo, int wj_hi, int t0) {
;     ...
;                 if constexpr (MODE == M_BAND) {
;                     const int cw = t0 >> 6;
;                     if (j <= cw - 3) { const float bc = bias2[191];
; #pragma unroll
;                         for (int r = 0; r < 16; ++r) { p0[r] = fmaf(p0[r], C2, bc); p1[r] = fmaf(p1[r], C2, bc); }
.LBB11_1289:
	s_waitcnt lgkmcnt(0)
	s_barrier
	v_cmp_ge_i32_e64 s[4:5], s19, v230
	v_cmp_le_i32_e64 s[6:7], s19, v229
	s_and_b64 s[4:5], s[4:5], s[6:7]
	s_and_saveexec_b64 s[6:7], s[4:5]
	s_cbranch_execz .LBB11_1286
	v_add_u32_e32 v2, s20, v231
	v_add_u32_e32 v74, v2, v232
	ds_read_b128 v[70:73], v74 offset:32768
	ds_read_b128 v[74:77], v74 offset:40960
	v_cmp_le_i32_e64 s[4:5], s19, v240
	s_waitcnt lgkmcnt(1)
	v_mfma_f32_32x32x16_bf16 v[118:133], v[70:73], v[162:165], 0
	s_waitcnt lgkmcnt(0)
	v_mfma_f32_32x32x16_bf16 v[102:117], v[74:77], v[162:165], 0
	v_add_u32_e32 v74, v2, v233
	ds_read_b128 v[70:73], v74 offset:32768
	ds_read_b128 v[74:77], v74 offset:40960
	s_waitcnt lgkmcnt(1)
	v_mfma_f32_32x32x16_bf16 v[118:133], v[70:73], v[154:157], v[118:133]
	s_waitcnt lgkmcnt(0)
	v_mfma_f32_32x32x16_bf16 v[102:117], v[74:77], v[154:157], v[102:117]
	v_add_u32_e32 v74, v2, v234
	ds_read_b128 v[70:73], v74 offset:32768
	ds_read_b128 v[74:77], v74 offset:40960
	s_waitcnt lgkmcnt(1)
	v_mfma_f32_32x32x16_bf16 v[118:133], v[70:73], v[150:153], v[118:133]
	s_waitcnt lgkmcnt(0)
	v_mfma_f32_32x32x16_bf16 v[102:117], v[74:77], v[150:153], v[102:117]
	v_add_u32_e32 v74, v2, v235
	ds_read_b128 v[70:73], v74 offset:32768
	ds_read_b128 v[74:77], v74 offset:40960
	s_waitcnt lgkmcnt(1)
	v_mfma_f32_32x32x16_bf16 v[118:133], v[70:73], v[146:149], v[118:133]
	s_waitcnt lgkmcnt(0)
	v_mfma_f32_32x32x16_bf16 v[102:117], v[74:77], v[146:149], v[102:117]
	v_add_u32_e32 v74, v2, v236
	ds_read_b128 v[70:73], v74 offset:32768
	ds_read_b128 v[74:77], v74 offset:40960
	s_waitcnt lgkmcnt(1)
	v_mfma_f32_32x32x16_bf16 v[118:133], v[70:73], v[142:145], v[118:133]
	s_waitcnt lgkmcnt(0)
	v_mfma_f32_32x32x16_bf16 v[102:117], v[74:77], v[142:145], v[102:117]
	v_add_u32_e32 v74, v2, v237
	ds_read_b128 v[70:73], v74 offset:32768
	ds_read_b128 v[74:77], v74 offset:40960
	s_waitcnt lgkmcnt(1)
	v_mfma_f32_32x32x16_bf16 v[118:133], v[70:73], v[138:141], v[118:133]
	s_waitcnt lgkmcnt(0)
	v_mfma_f32_32x32x16_bf16 v[102:117], v[74:77], v[138:141], v[102:117]
	v_add_u32_e32 v74, v2, v238
	ds_read_b128 v[70:73], v74 offset:32768
	ds_read_b128 v[74:77], v74 offset:40960
	v_add_u32_e32 v2, v2, v239
	s_waitcnt lgkmcnt(1)
	v_mfma_f32_32x32x16_bf16 v[118:133], v[70:73], v[134:137], v[118:133]
	s_waitcnt lgkmcnt(0)
	v_mfma_f32_32x32x16_bf16 v[102:117], v[74:77], v[134:137], v[102:117]
	ds_read_b128 v[70:73], v2 offset:32768
	ds_read_b128 v[74:77], v2 offset:40960
	s_waitcnt lgkmcnt(1)
	v_mfma_f32_32x32x16_bf16 v[118:133], v[70:73], v[158:161], v[118:133]
	s_waitcnt lgkmcnt(0)
	v_mfma_f32_32x32x16_bf16 v[102:117], v[74:77], v[158:161], v[102:117]
	s_and_saveexec_b64 s[20:21], s[4:5]
	s_xor_b64 s[4:5], exec, s[20:21]
	s_cbranch_execz .LBB11_1292
	v_readlane_b32 s19, v252, 14
	s_nop 1
	v_mov_b32_e32 v2, s19
	ds_read_b32 v2, v2
	s_waitcnt lgkmcnt(0)
	s_nop 0
	v_fma_f32 v84, v132, s0, v2
	v_fma_f32 v85, v133, s0, v2
	v_fma_f32 v82, v130, s0, v2
	v_fma_f32 v83, v131, s0, v2
	v_fma_f32 v80, v128, s0, v2
	v_fma_f32 v81, v129, s0, v2
	v_fma_f32 v78, v126, s0, v2
	v_fma_f32 v79, v127, s0, v2
	v_fma_f32 v76, v124, s0, v2
	v_fma_f32 v77, v125, s0, v2
	v_fma_f32 v74, v122, s0, v2
	v_fma_f32 v75, v123, s0, v2
	v_fma_f32 v72, v120, s0, v2
	v_fma_f32 v73, v121, s0, v2
	v_fma_f32 v70, v118, s0, v2
	v_fma_f32 v71, v119, s0, v2
	v_fma_f32 v100, v116, s0, v2
	v_fma_f32 v101, v117, s0, v2
	v_fma_f32 v98, v114, s0, v2
	v_fma_f32 v99, v115, s0, v2
	v_fma_f32 v96, v112, s0, v2
	v_fma_f32 v97, v113, s0, v2
	v_fma_f32 v94, v110, s0, v2
	v_fma_f32 v95, v111, s0, v2
	v_fma_f32 v92, v108, s0, v2
	v_fma_f32 v93, v109, s0, v2
	v_fma_f32 v90, v106, s0, v2
	v_fma_f32 v91, v107, s0, v2
	v_fma_f32 v88, v104, s0, v2
	v_fma_f32 v89, v105, s0, v2
	v_fma_f32 v86, v102, s0, v2
	v_fma_f32 v87, v103, s0, v2
; template <int MODE>
; DEVI void attn_unit(LAS unsigned char* lds, const bf16_t* Qw, int ldq, const bf16_t* Kb, const bf16_t* Vb, int ldk, bf16_t* Ow, int ldo,
;                     int j_first, int ntiles, int jstep, int wj_lo, int wj_hi, int t0) {
;     ...
;                     } else { const int d0 = (t0 + r32) - (64 * j + 4 * hi) + 63;
; #pragma unroll
;                         for (int r = 0; r < 16; ++r) { const int da = d0 - ((r & 3) + 8 * (r >> 2)); const int ia = da > 191 ? 191 : da; const int db = da - 32; const int ib = db > 191 ? 191 : db;
;                             p0[r] = fmaf(p0[r], C2, bias2[ia]); p1[r] = fmaf(p1[r], C2, bias2[ib]); } }
.LBB11_1292:
	s_andn2_saveexec_b64 s[4:5], s[4:5]
	s_cbranch_execz .LBB11_1294
	v_add_u32_e32 v71, 26, v243
	s_add_i32 s19, 0, 0x12800
	v_min_i32_e32 v72, 0xbf, v71
	v_min_i32_e32 v71, 0xdf, v71
	v_lshl_add_u32 v71, v71, 2, s19
	v_add_u32_e32 v73, 0xffffff80, v71
	v_add_u32_e32 v71, 25, v243
	v_min_i32_e32 v74, 0xbf, v71
	v_min_i32_e32 v71, 0xdf, v71
	v_lshl_add_u32 v71, v71, 2, s19
	v_add_u32_e32 v2, 27, v243
	v_add_u32_e32 v75, 0xffffff80, v71
	v_add_u32_e32 v71, 24, v243
	v_min_i32_e32 v70, 0xbf, v2
	v_min_i32_e32 v2, 0xdf, v2
	v_min_i32_e32 v76, 0xbf, v71
	v_min_i32_e32 v71, 0xdf, v71
	v_lshl_add_u32 v70, v70, 2, s19
	v_lshl_add_u32 v2, v2, 2, s19
	v_lshl_add_u32 v72, v72, 2, s19
	v_lshl_add_u32 v71, v71, 2, s19
	v_add_u32_e32 v2, 0xffffff80, v2
	v_lshl_add_u32 v74, v74, 2, s19
	v_lshl_add_u32 v76, v76, 2, s19
	v_add_u32_e32 v77, 0xffffff80, v71
	ds_read_b32 v70, v70
	ds_read_b32 v86, v2
	ds_read_b32 v71, v72
	ds_read_b32 v87, v73
	ds_read_b32 v72, v74
	ds_read_b32 v88, v75
	ds_read_b32 v73, v76
	ds_read_b32 v89, v77
	v_add_u32_e32 v75, 18, v243
	v_min_i32_e32 v76, 0xbf, v75
	v_min_i32_e32 v75, 0xdf, v75
	v_lshl_add_u32 v75, v75, 2, s19
	v_add_u32_e32 v77, 0xffffff80, v75
	v_add_u32_e32 v75, 17, v243
	v_min_i32_e32 v78, 0xbf, v75
	v_min_i32_e32 v75, 0xdf, v75
	v_lshl_add_u32 v75, v75, 2, s19
	v_add_u32_e32 v2, 19, v243
	v_add_u32_e32 v79, 0xffffff80, v75
	v_add_u32_e32 v75, 16, v243
	v_min_i32_e32 v74, 0xbf, v2
	v_min_i32_e32 v2, 0xdf, v2
	v_min_i32_e32 v80, 0xbf, v75
	v_min_i32_e32 v75, 0xdf, v75
	v_lshl_add_u32 v74, v74, 2, s19
	v_lshl_add_u32 v2, v2, 2, s19
	v_lshl_add_u32 v76, v76, 2, s19
	v_lshl_add_u32 v75, v75, 2, s19
	v_add_u32_e32 v2, 0xffffff80, v2
	v_lshl_add_u32 v78, v78, 2, s19
	v_lshl_add_u32 v80, v80, 2, s19
	v_add_u32_e32 v81, 0xffffff80, v75
	ds_read_b32 v74, v74
	ds_read_b32 v90, v2
	ds_read_b32 v75, v76
	ds_read_b32 v91, v77
	ds_read_b32 v76, v78
	ds_read_b32 v92, v79
	ds_read_b32 v77, v80
	ds_read_b32 v93, v81
	v_add_u32_e32 v79, 10, v243
	v_min_i32_e32 v80, 0xbf, v79
	v_min_i32_e32 v79, 0xdf, v79
	v_lshl_add_u32 v79, v79, 2, s19
	v_add_u32_e32 v81, 0xffffff80, v79
	v_add_u32_e32 v79, 9, v243
	v_min_i32_e32 v82, 0xbf, v79
	v_min_i32_e32 v79, 0xdf, v79
	v_lshl_add_u32 v79, v79, 2, s19
	v_add_u32_e32 v2, 11, v243
	v_add_u32_e32 v83, 0xffffff80, v79
	v_add_u32_e32 v79, 8, v243
	v_min_i32_e32 v78, 0xbf, v2
	v_min_i32_e32 v2, 0xdf, v2
	v_min_i32_e32 v84, 0xbf, v79
	v_min_i32_e32 v79, 0xdf, v79
	v_lshl_add_u32 v78, v78, 2, s19
	v_lshl_add_u32 v2, v2, 2, s19
	v_lshl_add_u32 v80, v80, 2, s19
	v_lshl_add_u32 v79, v79, 2, s19
	v_add_u32_e32 v2, 0xffffff80, v2
	v_lshl_add_u32 v82, v82, 2, s19
	v_lshl_add_u32 v84, v84, 2, s19
	v_add_u32_e32 v85, 0xffffff80, v79
	ds_read_b32 v78, v78
	ds_read_b32 v94, v2
	ds_read_b32 v79, v80
	ds_read_b32 v95, v81
	ds_read_b32 v80, v82
	ds_read_b32 v96, v83
	ds_read_b32 v81, v84
	ds_read_b32 v97, v85
	v_add_u32_e32 v83, 2, v243
	v_min_i32_e32 v84, 0xbf, v83
	v_min_i32_e32 v83, 0xdf, v83
	v_lshl_add_u32 v83, v83, 2, s19
	v_add_u32_e32 v184, 0xffffff80, v83
	v_add_u32_e32 v83, 1, v243
	v_lshl_add_u32 v99, v84, 2, s19
	v_min_i32_e32 v84, 0xbf, v83
	v_min_i32_e32 v83, 0xdf, v83
	v_add_u32_e32 v2, 3, v243
	v_lshl_add_u32 v83, v83, 2, s19
	v_min_i32_e32 v85, 0xdf, v243
	v_min_i32_e32 v82, 0xbf, v2
	v_min_i32_e32 v2, 0xdf, v2
	v_add_u32_e32 v100, 0xffffff80, v83
	v_min_i32_e32 v83, 0xbf, v243
	v_lshl_add_u32 v85, v85, 2, s19
	v_lshl_add_u32 v82, v82, 2, s19
	v_lshl_add_u32 v2, v2, 2, s19
	v_lshl_add_u32 v84, v84, 2, s19
	v_lshl_add_u32 v83, v83, 2, s19
	v_add_u32_e32 v101, 0xffffff80, v85
	v_add_u32_e32 v2, 0xffffff80, v2
	ds_read_b32 v82, v82
	ds_read_b32 v98, v2
	ds_read_b32 v84, v84
	ds_read_b32 v85, v83
	ds_read_b32 v83, v99
	ds_read_b32 v101, v101
	ds_read_b32 v100, v100
	ds_read_b32 v99, v184
	s_waitcnt lgkmcnt(4)
	v_fma_f32 v84, v132, s0, v84
	v_fma_f32 v85, v133, s0, v85
	s_waitcnt lgkmcnt(3)
	v_fma_f32 v82, v130, s0, v82
	v_fma_f32 v83, v131, s0, v83
	v_fma_f32 v80, v128, s0, v80
	v_fma_f32 v81, v129, s0, v81
	v_fma_f32 v78, v126, s0, v78
	v_fma_f32 v79, v127, s0, v79
	v_fma_f32 v76, v124, s0, v76
	v_fma_f32 v77, v125, s0, v77
	v_fma_f32 v74, v122, s0, v74
	v_fma_f32 v75, v123, s0, v75
	v_fma_f32 v72, v120, s0, v72
	v_fma_f32 v73, v121, s0, v73
	v_fma_f32 v70, v118, s0, v70
	v_fma_f32 v71, v119, s0, v71
	s_waitcnt lgkmcnt(1)
	v_fma_f32 v100, v116, s0, v100
	v_fma_f32 v101, v117, s0, v101
	s_waitcnt lgkmcnt(0)
	v_fma_f32 v98, v114, s0, v98
	v_fma_f32 v99, v115, s0, v99
	v_fma_f32 v96, v112, s0, v96
	v_fma_f32 v97, v113, s0, v97
	v_fma_f32 v94, v110, s0, v94
	v_fma_f32 v95, v111, s0, v95
	v_fma_f32 v92, v108, s0, v92
	v_fma_f32 v93, v109, s0, v93
	v_fma_f32 v90, v106, s0, v90
	v_fma_f32 v91, v107, s0, v91
	v_fma_f32 v88, v104, s0, v88
	v_fma_f32 v89, v105, s0, v89
	v_fma_f32 v86, v102, s0, v86
	v_fma_f32 v87, v103, s0, v87

; DEVI unsigned ordkey(float f) { const unsigned u = __float_as_uint(f); return (u & 0x80000000u) ? ~u : (u | 0x80000000u); }
; template <class MP> DEVI void select_row(const float* sc, int c  , MP mrow, int lane) {
;     ...
;     for (int j = 0; j < 32; ++j) { const int jj = j <= c ? j : c; u[j] = __float_as_uint(sc[64 * jj + lane]); }
;     float s1 = 0.f, s2 = 0.f;
; #pragma unroll
;     for (int j = 0; j < 32; ++j) { const float f = (j <= c) ? __uint_as_float(u[j]) : 0.f; s1 += f; s2 = fmaf(f, f, s2); }
; #pragma unroll
;     for (int o = 1; o < 64; o <<= 1) { s1 += __shfl_xor(s1, o); s2 += __shfl_xor(s2, o); }
; #pragma unroll
;     for (int j = 0; j < 32; ++j) u[j] = (j <= c) ? ordkey(__uint_as_float(u[j])) : 0u;
;     unsigned elo, ehi, elo2, ehi2;
;     { const float n = 64.f * (float)(c + 1), p = 256.f / n, pp = p <= 0.5f ? p : 1.f - p, t = sqrtf(-2.f * __logf(pp));
;       float z = t - (2.515517f + t * (0.802853f + t * 0.010328f)) / (1.f + t * (1.432788f + t * (0.189269f + t * 0.001308f))); if (p > 0.5f) z = -z;
;       const float mean = s1 / n, sd = sqrtf(fmaxf(s2 / n - mean * mean, 0.f));
.LBB11_1361:
	s_not_b32 s1, s3
	s_andn2_b32 s4, 63, s3
	s_bfe_u32 s30, s1, 0x50001
	s_cmp_gt_u32 s4, 7
	v_writelane_b32 v252, s9, 30
	s_cselect_b64 s[12:13], -1, 0
	s_min_u32 s1, s30, 5
	s_min_u32 s6, s30, 6
	s_min_u32 s7, s30, 7
	s_min_u32 s8, s30, 8
	s_min_u32 s9, s30, 9
	s_min_u32 s20, s30, 10
	s_min_u32 s21, s30, 11
	s_min_u32 s24, s30, 12
	s_min_u32 s25, s30, 13
	s_min_u32 s33, s30, 14
	s_min_u32 s42, s30, 15
	s_min_u32 s43, s30, 16
	s_min_u32 s44, s30, 17
	s_min_u32 s45, s30, 18
	s_min_u32 s46, s30, 19
	s_min_u32 s47, s30, 20
	s_min_u32 s48, s30, 21
	s_min_u32 s49, s30, 22
	s_min_u32 s50, s30, 23
	s_min_u32 s51, s30, 24
	s_min_u32 s52, s30, 25
	s_min_u32 s53, s30, 26
	s_min_u32 s54, s30, 27
	s_min_u32 s55, s30, 28
	s_min_u32 s56, s30, 29
	s_min_u32 s57, s30, 30
	s_lshl_b32 s58, s30, 6
	s_cmp_eq_u32 s30, 4
	s_cselect_b64 s[16:17], -1, 0
	s_cmp_lg_u32 s30, 4
	s_cselect_b64 s[10:11], -1, 0
	s_cmp_lt_u32 s4, 12
	v_writelane_b32 v252, s10, 31
	s_cselect_b64 s[18:19], -1, 0
	s_cmp_gt_u32 s4, 11
	v_writelane_b32 v252, s11, 32
	s_cselect_b64 s[10:11], -1, 0
	s_cmp_lt_u32 s4, 14
	v_writelane_b32 v252, s10, 33
	s_cselect_b64 s[22:23], -1, 0
	s_cmp_gt_u32 s4, 13
	v_writelane_b32 v252, s11, 34
	s_cselect_b64 s[10:11], -1, 0
	s_cmp_lt_u32 s4, 16
	v_writelane_b32 v252, s10, 35
	s_cselect_b64 s[26:27], -1, 0
	s_cmp_gt_u32 s4, 15
	v_writelane_b32 v252, s11, 36
	s_cselect_b64 s[10:11], -1, 0
	s_cmp_lt_u32 s4, 18
	v_writelane_b32 v252, s10, 37
	s_cselect_b64 s[38:39], -1, 0
	s_cmp_gt_u32 s4, 17
	v_writelane_b32 v252, s11, 38
	s_cselect_b64 s[10:11], -1, 0
	s_cmp_lt_u32 s4, 20
	v_writelane_b32 v252, s10, 39
	s_cselect_b64 s[40:41], -1, 0
	s_cmp_gt_u32 s4, 19
	v_writelane_b32 v252, s11, 40
	s_cselect_b64 s[10:11], -1, 0
	s_cmp_lt_u32 s4, 22
	v_writelane_b32 v252, s10, 41
	s_cselect_b64 s[60:61], -1, 0
	s_cmp_gt_u32 s4, 21
	v_writelane_b32 v252, s11, 42
	s_cselect_b64 s[10:11], -1, 0
	s_cmp_lt_u32 s4, 24
	v_writelane_b32 v252, s10, 43
	s_cselect_b64 s[14:15], -1, 0
	s_cmp_gt_u32 s4, 23
	v_writelane_b32 v252, s11, 44
	s_cselect_b64 s[10:11], -1, 0
	s_cmp_lt_u32 s4, 26
	v_writelane_b32 v252, s10, 45
	s_cselect_b64 s[28:29], -1, 0
	s_cmp_gt_u32 s4, 25
	v_writelane_b32 v252, s11, 46
	s_cselect_b64 s[10:11], -1, 0
	s_cmp_lt_u32 s4, 28
	v_writelane_b32 v252, s10, 47
	s_cselect_b64 s[62:63], -1, 0
	s_cmp_gt_u32 s4, 27
	v_writelane_b32 v252, s11, 48
	s_cselect_b64 s[10:11], -1, 0
	s_cmp_lt_u32 s4, 30
	v_writelane_b32 v252, s10, 49
	s_cselect_b64 s[64:65], -1, 0
	s_cmp_gt_u32 s4, 29
	v_writelane_b32 v252, s11, 50
	s_cselect_b64 s[10:11], -1, 0
	s_cmp_lt_u32 s4, 32
	v_writelane_b32 v252, s10, 51
	s_cselect_b64 s[66:67], -1, 0
	s_cmp_gt_u32 s4, 31
	v_writelane_b32 v252, s11, 52
	s_cselect_b64 s[10:11], -1, 0
	s_cmp_lt_u32 s4, 34
	v_writelane_b32 v252, s10, 53
	s_cselect_b64 s[68:69], -1, 0
	s_cmp_gt_u32 s4, 33
	v_writelane_b32 v252, s11, 54
	s_cselect_b64 s[10:11], -1, 0
	s_cmp_lt_u32 s4, 36
	v_writelane_b32 v252, s10, 55
	s_cselect_b64 s[70:71], -1, 0
	s_cmp_gt_u32 s4, 35
	v_writelane_b32 v252, s11, 56
	s_cselect_b64 s[10:11], -1, 0
	s_cmp_lt_u32 s4, 38
	v_writelane_b32 v252, s10, 57
	s_cselect_b64 s[72:73], -1, 0
	s_cmp_gt_u32 s4, 37
	v_writelane_b32 v252, s11, 58
	s_cselect_b64 s[10:11], -1, 0
	s_cmp_lt_u32 s4, 40
	v_writelane_b32 v252, s10, 59
	s_cselect_b64 s[74:75], -1, 0
	s_cmp_gt_u32 s4, 39
	v_writelane_b32 v252, s11, 60
	s_cselect_b64 s[10:11], -1, 0
	s_cmp_lt_u32 s4, 42
	v_writelane_b32 v252, s10, 61
	s_cselect_b64 s[76:77], -1, 0
	s_cmp_gt_u32 s4, 41
	v_writelane_b32 v252, s11, 62
	s_cselect_b64 s[10:11], -1, 0
	s_cmp_lt_u32 s4, 44
	v_writelane_b32 v252, s10, 63
	s_cselect_b64 s[78:79], -1, 0
	s_cmp_gt_u32 s4, 43
	v_writelane_b32 v253, s11, 0
	s_cselect_b64 s[10:11], -1, 0
	s_cmp_lt_u32 s4, 46
	v_writelane_b32 v253, s10, 1
	s_cselect_b64 s[80:81], -1, 0
	s_cmp_gt_u32 s4, 45
	v_writelane_b32 v253, s11, 2
	s_cselect_b64 s[10:11], -1, 0
	s_cmp_lt_u32 s4, 48
	v_writelane_b32 v253, s10, 3
	s_cselect_b64 s[82:83], -1, 0
	s_cmp_gt_u32 s4, 47
	v_writelane_b32 v253, s11, 4
	s_cselect_b64 s[10:11], -1, 0
	s_cmp_lt_u32 s4, 50
	v_writelane_b32 v253, s10, 5
	s_cselect_b64 s[84:85], -1, 0
	s_cmp_gt_u32 s4, 49
	v_writelane_b32 v253, s11, 6
	s_cselect_b64 s[10:11], -1, 0
	s_cmp_lt_u32 s4, 52
	v_writelane_b32 v253, s10, 7
	s_cselect_b64 s[86:87], -1, 0
	s_cmp_gt_u32 s4, 51
	v_writelane_b32 v253, s11, 8
	s_cselect_b64 s[10:11], -1, 0
	s_cmp_lt_u32 s4, 54
	v_writelane_b32 v253, s10, 9
	s_cselect_b64 s[88:89], -1, 0
	s_cmp_gt_u32 s4, 53
	v_writelane_b32 v253, s11, 10
	s_cselect_b64 s[10:11], -1, 0
	s_cmp_lt_u32 s4, 56
	v_writelane_b32 v253, s10, 11
	s_cselect_b64 s[90:91], -1, 0
	s_cmp_gt_u32 s4, 55
	v_writelane_b32 v253, s11, 12
	s_cselect_b64 s[10:11], -1, 0
	s_cmp_lt_u32 s4, 58
	v_writelane_b32 v253, s10, 13
	s_cselect_b64 s[92:93], -1, 0
	s_cmp_gt_u32 s4, 57
	v_writelane_b32 v253, s11, 14
	s_cselect_b64 s[10:11], -1, 0
	s_cmp_lt_u32 s4, 60
	v_writelane_b32 v253, s10, 15
	s_cselect_b64 s[94:95], -1, 0
	s_cmp_gt_u32 s4, 59
	v_writelane_b32 v253, s11, 16
	s_cselect_b64 s[4:5], -1, 0
	s_cmp_lg_u32 s30, 31
	v_writelane_b32 v253, s4, 17
	s_cselect_b64 s[96:97], -1, 0
	s_cmp_eq_u32 s30, 31
	v_writelane_b32 v253, s5, 18
	s_cselect_b64 s[4:5], -1, 0
	v_writelane_b32 v253, s4, 19
	s_mov_b32 s2, 0x43800000
	s_mov_b32 s10, s3
	v_writelane_b32 v253, s5, 20
	s_add_i32 s4, s58, 64
	v_cvt_f32_u32_e32 v65, s4
	v_writelane_b32 v253, s10, 21
	v_writelane_b32 v249, s62, 41
	v_lshl_or_b32 v12, s7, 6, v154
	v_div_scale_f32 v1, s[4:5], v65, v65, s2
	v_rcp_f32_e32 v4, v1
	s_mov_b32 s4, 0x800000
	v_lshl_or_b32 v14, s8, 6, v154
	v_lshl_or_b32 v16, s9, 6, v154
	v_fma_f32 v5, -v1, v4, 1.0
; DEVI unsigned ordkey(float f) { const unsigned u = __float_as_uint(f); return (u & 0x80000000u) ? ~u : (u | 0x80000000u); }
; template <class MP> DEVI void select_row(const float* sc, int c  , MP mrow, int lane) {
;     ...
;     { const float n = 64.f * (float)(c + 1), p = 256.f / n, pp = p <= 0.5f ? p : 1.f - p, t = sqrtf(-2.f * __logf(pp));
;       float z = t - (2.515517f + t * (0.802853f + t * 0.010328f)) / (1.f + t * (1.432788f + t * (0.189269f + t * 0.001308f))); if (p > 0.5f) z = -z;
;       const float mean = s1 / n, sd = sqrtf(fmaxf(s2 / n - mean * mean, 0.f));
;       elo = ordkey(mean + (z - 0.3f) * sd); ehi = ordkey(mean + (z + 0.3f) * sd); elo2 = ordkey(mean + (z - 1.2f) * sd); ehi2 = ordkey(mean + (z + 1.2f) * sd); }
	v_fmac_f32_e32 v4, v5, v4
	v_div_scale_f32 v5, vcc, s2, v65, s2
	v_mul_f32_e32 v6, v5, v4
	v_fma_f32 v7, -v1, v6, v5
	v_fmac_f32_e32 v6, v7, v4
	v_fma_f32 v1, -v1, v6, v5
	v_div_fmas_f32 v1, v1, v4, v6
	v_div_fixup_f32 v1, v1, v65, s2
	v_sub_f32_e32 v4, 1.0, v1
	v_cmp_ge_f32_e32 vcc, 0.5, v1
	v_mov_b32_e32 v5, 0x41b17218
	s_mov_b32 s2, 0xf800000
	v_cndmask_b32_e32 v4, v4, v1, vcc
	v_cmp_gt_f32_e32 vcc, s4, v4
	s_and_b64 s[4:5], vcc, exec
	s_cselect_b32 s4, 32, 0
	v_ldexp_f32 v4, v4, s4
	v_log_f32_e32 v4, v4
	s_mov_b32 s4, 0x3f317217
	v_cndmask_b32_e32 v5, 0, v5, vcc
	v_lshl_or_b32 v18, s20, 6, v154
	v_mul_f32_e32 v6, 0x3f317217, v4
	v_fma_f32 v6, v4, s4, -v6
	v_fmac_f32_e32 v6, 0x3377d1cf, v4
	s_mov_b32 s4, 0x7f800000
	v_fmac_f32_e32 v6, 0x3f317217, v4
	v_cmp_lt_f32_e64 vcc, |v4|, s4
	v_lshl_or_b32 v20, s21, 6, v154
	v_lshl_or_b32 v22, s24, 6, v154
	v_cndmask_b32_e32 v4, v4, v6, vcc
	v_sub_f32_e32 v4, v4, v5
	v_mul_f32_e32 v4, -2.0, v4
	v_mul_f32_e32 v5, 0x4f800000, v4
	v_cmp_gt_f32_e32 vcc, s2, v4
	s_mov_b32 s2, 0x3f4d87c6
	s_mov_b32 s3, 0x3fb76599
	v_cndmask_b32_e32 v4, v4, v5, vcc
	v_sqrt_f32_e32 v5, v4
	v_lshl_or_b32 v24, s25, 6, v154
	v_lshl_or_b32 v26, s33, 6, v154
	v_lshl_or_b32 v28, s42, 6, v154
	v_add_u32_e32 v6, -1, v5
	v_fma_f32 v7, -v6, v5, v4
	v_cmp_ge_f32_e64 s[4:5], 0, v7
	v_add_u32_e32 v7, 1, v5
	v_lshl_or_b32 v30, s43, 6, v154
	v_cndmask_b32_e64 v6, v5, v6, s[4:5]
	v_fma_f32 v5, -v7, v5, v4
	v_cmp_lt_f32_e64 s[4:5], 0, v5
	v_lshl_or_b32 v32, s44, 6, v154
	v_lshl_or_b32 v34, s45, 6, v154
	v_cndmask_b32_e64 v5, v6, v7, s[4:5]
	v_mul_f32_e32 v6, 0x37800000, v5
	v_cndmask_b32_e32 v5, v5, v6, vcc
	v_cmp_class_f32_e32 vcc, v4, v210
	v_lshl_or_b32 v36, s46, 6, v154
	v_lshl_or_b32 v38, s47, 6, v154
	v_cndmask_b32_e32 v4, v5, v4, vcc
	v_mov_b32_e32 v5, 0x3e41cfbc
	v_fmamk_f32 v183, v4, 0x3aab7132, v5
	v_fma_f32 v6, v4, v182, s2
	v_fma_f32 v7, v4, v183, s3
	s_mov_b32 s2, 0x4020fe3b
	s_mov_b32 s3, 1.0
	v_fma_f32 v6, v4, v6, s2
	v_fma_f32 v7, v4, v7, s3
	v_div_scale_f32 v5, s[4:5], v7, v7, v6
	v_rcp_f32_e32 v8, v5
	s_mov_b32 s2, 0x3e99999a
	s_mov_b32 s3, 0xbe99999a
	v_lshl_or_b32 v40, s48, 6, v154
	v_fma_f32 v9, -v5, v8, 1.0
	v_fmac_f32_e32 v8, v9, v8
	v_div_scale_f32 v9, vcc, v6, v7, v6
	v_mul_f32_e32 v10, v9, v8
	v_fma_f32 v11, -v5, v10, v9
	v_fmac_f32_e32 v10, v11, v8
	v_fma_f32 v5, -v5, v10, v9
	v_div_fmas_f32 v5, v5, v8, v10
	v_div_fixup_f32 v5, v5, v7, v6
	v_sub_f32_e32 v4, v4, v5
	v_cmp_lt_f32_e32 vcc, 0.5, v1
	v_mov_b32_e32 v1, 0x7ffffc0
	v_lshl_or_b32 v8, s1, 6, v154
	v_cndmask_b32_e64 v6, v4, -v4, vcc
	v_add_f32 v4, s2, v6
	v_add_f32 v5, s3, v6
	s_mov_b32 s2, 0x3f99999a
	s_mov_b32 s3, 0xbf99999a
	v_add_f32 v7, s3, v6
	v_add_f32 v6, s2, v6
	v_readlane_b32 s2, v252, 27
	v_readlane_b32 s3, v252, 28
	s_nor_b64 s[4:5], s[2:3], s[16:17]
	v_writelane_b32 v253, s4, 22
	v_lshl_or_b32 v10, s6, 6, v154
	v_lshl_or_b32 v42, s49, 6, v154
	v_writelane_b32 v253, s5, 23
	s_nor_b64 s[4:5], s[2:3], s[18:19]
	v_writelane_b32 v253, s4, 24
	v_lshl_or_b32 v44, s50, 6, v154
	v_lshl_or_b32 v46, s51, 6, v154
	v_writelane_b32 v253, s5, 25
	s_nor_b64 s[4:5], s[2:3], s[22:23]
	v_writelane_b32 v253, s4, 26
	v_lshl_or_b32 v48, s52, 6, v154
	v_lshl_or_b32 v50, s53, 6, v154
	v_writelane_b32 v253, s5, 27
	s_nor_b64 s[4:5], s[2:3], s[26:27]
	v_writelane_b32 v253, s4, 28
	v_lshl_or_b32 v52, s54, 6, v154
	v_lshl_or_b32 v54, s55, 6, v154
	v_writelane_b32 v253, s5, 29
	s_nor_b64 s[4:5], s[2:3], s[38:39]
	v_writelane_b32 v253, s4, 30
	v_lshl_or_b32 v56, s56, 6, v154
	v_lshl_or_b32 v58, s57, 6, v154
	v_writelane_b32 v253, s5, 31
	s_nor_b64 s[4:5], s[2:3], s[40:41]
	v_writelane_b32 v253, s4, 32
	v_or_b32_e32 v60, s58, v154
	v_bitop3_b32 v1, s10, v1, 63 bitop3:0xca
	v_writelane_b32 v253, s5, 33
	s_nor_b64 s[4:5], s[2:3], s[60:61]
	v_writelane_b32 v253, s4, 34
	v_lshlrev_b32_e32 v160, 5, v1
	v_lshlrev_b32_e32 v8, 2, v8
	v_writelane_b32 v253, s5, 35
	v_writelane_b32 v253, s14, 36
	s_nor_b64 s[4:5], s[2:3], s[14:15]
	v_lshlrev_b32_e32 v10, 2, v10
	v_writelane_b32 v253, s15, 37
	v_writelane_b32 v253, s4, 38
	v_lshlrev_b32_e32 v12, 2, v12
	v_lshlrev_b32_e32 v14, 2, v14
; template <class MP> DEVI void select_row(const float* sc, int c  , MP mrow, int lane) {
;     ...
;     for (int j = 0; j < 32; ++j) { const int jj = j <= c ? j : c; u[j] = __float_as_uint(sc[64 * jj + lane]); }
;     float s1 = 0.f, s2 = 0.f;
; #pragma unroll
;     for (int j = 0; j < 32; ++j) { const float f = (j <= c) ? __uint_as_float(u[j]) : 0.f; s1 += f; s2 = fmaf(f, f, s2); }
	v_writelane_b32 v253, s5, 39
	v_writelane_b32 v253, s28, 40
	s_nor_b64 s[4:5], s[2:3], s[28:29]
	v_lshlrev_b32_e32 v16, 2, v16
	v_writelane_b32 v253, s29, 41
	v_writelane_b32 v253, s4, 42
	v_lshlrev_b32_e32 v18, 2, v18
	v_lshlrev_b32_e32 v20, 2, v20
	v_writelane_b32 v253, s5, 43
	s_nor_b64 s[4:5], s[2:3], s[62:63]
	v_writelane_b32 v253, s4, 44
	v_lshlrev_b32_e32 v22, 2, v22
	v_lshlrev_b32_e32 v24, 2, v24
	v_writelane_b32 v253, s5, 45
	v_writelane_b32 v253, s64, 46
	s_nor_b64 s[4:5], s[2:3], s[64:65]
	v_lshlrev_b32_e32 v26, 2, v26
	v_writelane_b32 v253, s65, 47
	v_writelane_b32 v253, s4, 48
	v_lshlrev_b32_e32 v28, 2, v28
	v_lshlrev_b32_e32 v30, 2, v30
	v_writelane_b32 v253, s5, 49
	v_writelane_b32 v253, s66, 50
	s_nor_b64 s[4:5], s[2:3], s[66:67]
	v_lshlrev_b32_e32 v32, 2, v32
	v_writelane_b32 v253, s67, 51
	v_writelane_b32 v253, s4, 52
	v_lshlrev_b32_e32 v34, 2, v34
	v_lshlrev_b32_e32 v36, 2, v36
	v_writelane_b32 v253, s5, 53
	v_writelane_b32 v253, s68, 54
	s_nor_b64 s[4:5], s[2:3], s[68:69]
	v_lshlrev_b32_e32 v38, 2, v38
	v_writelane_b32 v253, s69, 55
	v_writelane_b32 v253, s4, 56
	v_lshlrev_b32_e32 v40, 2, v40
	v_lshlrev_b32_e32 v42, 2, v42
	v_writelane_b32 v253, s5, 57
	v_writelane_b32 v253, s70, 58
	s_nor_b64 s[4:5], s[2:3], s[70:71]
	v_lshlrev_b32_e32 v44, 2, v44
	v_writelane_b32 v253, s71, 59
	v_writelane_b32 v253, s4, 60
	v_lshlrev_b32_e32 v46, 2, v46
	v_lshlrev_b32_e32 v48, 2, v48
	v_writelane_b32 v253, s5, 61
	v_writelane_b32 v253, s72, 62
	s_nor_b64 s[4:5], s[2:3], s[72:73]
	v_writelane_b32 v254, s4, 0
	v_lshlrev_b32_e32 v50, 2, v50
	v_lshlrev_b32_e32 v52, 2, v52
	v_writelane_b32 v254, s5, 1
	v_writelane_b32 v254, s74, 2
	s_nor_b64 s[4:5], s[2:3], s[74:75]
	v_lshlrev_b32_e32 v54, 2, v54
	v_writelane_b32 v254, s75, 3
	v_writelane_b32 v254, s4, 4
	v_lshlrev_b32_e32 v56, 2, v56
	v_lshlrev_b32_e32 v58, 2, v58
	v_writelane_b32 v254, s5, 5
	v_writelane_b32 v254, s76, 6
	s_nor_b64 s[4:5], s[2:3], s[76:77]
	v_lshlrev_b32_e32 v60, 2, v60
	v_writelane_b32 v254, s77, 7
	v_writelane_b32 v254, s4, 8
	s_mov_b32 s1, 0
	v_writelane_b32 v249, s63, 42
	v_writelane_b32 v254, s5, 9
	v_writelane_b32 v254, s78, 10
	s_nor_b64 s[4:5], s[2:3], s[78:79]
	v_writelane_b32 v253, s73, 63
	v_writelane_b32 v254, s79, 11
	v_writelane_b32 v254, s4, 12
	s_nop 1
	v_writelane_b32 v254, s5, 13
	v_writelane_b32 v254, s80, 14
	s_nor_b64 s[4:5], s[2:3], s[80:81]
	s_nop 0
	v_writelane_b32 v254, s81, 15
	v_writelane_b32 v254, s4, 16
	s_nop 1
	v_writelane_b32 v254, s5, 17
	v_writelane_b32 v254, s82, 18
	s_nor_b64 s[4:5], s[2:3], s[82:83]
	s_nop 0
	v_writelane_b32 v254, s83, 19
	v_writelane_b32 v254, s4, 20
	s_nop 1
	v_writelane_b32 v254, s5, 21
	v_writelane_b32 v254, s84, 22
	s_nor_b64 s[4:5], s[2:3], s[84:85]
	s_nop 0
	v_writelane_b32 v254, s85, 23
	v_writelane_b32 v254, s4, 24
	s_nop 1
	v_writelane_b32 v254, s5, 25
	v_writelane_b32 v254, s86, 26
	s_nor_b64 s[4:5], s[2:3], s[86:87]
	s_nop 0
	v_writelane_b32 v254, s87, 27
	v_writelane_b32 v254, s4, 28
	s_nop 1
	v_writelane_b32 v254, s5, 29
	v_writelane_b32 v254, s88, 30
	s_nor_b64 s[4:5], s[2:3], s[88:89]
	s_nop 0
	v_writelane_b32 v254, s89, 31
	v_writelane_b32 v254, s4, 32
	s_nop 1
	v_writelane_b32 v254, s5, 33
	v_writelane_b32 v254, s90, 34
	s_nor_b64 s[4:5], s[2:3], s[90:91]
	s_nop 0
	v_writelane_b32 v254, s91, 35
	v_writelane_b32 v254, s4, 36
	s_nop 1
	v_writelane_b32 v254, s5, 37
	v_writelane_b32 v254, s92, 38
	s_nor_b64 s[4:5], s[2:3], s[92:93]
	s_nop 0
	v_writelane_b32 v254, s93, 39
	v_writelane_b32 v254, s4, 40
	s_nop 1
	v_writelane_b32 v254, s5, 41
	v_writelane_b32 v254, s94, 42
	s_nor_b64 s[4:5], s[2:3], s[94:95]
	s_nop 0
	v_writelane_b32 v254, s95, 43
	v_writelane_b32 v254, s4, 44
	s_nop 1
	v_writelane_b32 v254, s5, 45
	v_writelane_b32 v254, s96, 46
	s_nor_b64 s[2:3], s[2:3], s[96:97]
	s_nop 0
	v_writelane_b32 v254, s97, 47
	v_writelane_b32 v254, s2, 48
	s_nop 1
	v_writelane_b32 v254, s3, 49
	v_cmp_ge_u32_e64 s[2:3], s30, v154
	s_nop 1
	v_writelane_b32 v254, s2, 50
	s_nop 1
	v_writelane_b32 v254, s3, 51
	v_writelane_b32 v254, s60, 52
	s_nop 1
	v_writelane_b32 v254, s61, 53
	s_branch .LBB11_1364

; template <class MP> DEVI void select_row(const float* sc, int c  , MP mrow, int lane) {
;     ...
;     for (int j = 0; j < 32; ++j) { const int jj = j <= c ? j : c; u[j] = __float_as_uint(sc[64 * jj + lane]); }
;     float s1 = 0.f, s2 = 0.f;
; #pragma unroll
;     for (int j = 0; j < 32; ++j) { const float f = (j <= c) ? __uint_as_float(u[j]) : 0.f; s1 += f; s2 = fmaf(f, f, s2); }
; #pragma unroll
;     for (int o = 1; o < 64; o <<= 1) { s1 += __shfl_xor(s1, o); s2 += __shfl_xor(s2, o); }
.LBB11_1366:
	v_add_u32_e32 v62, v1, v160
	v_ashrrev_i32_e32 v63, 31, v62
	v_lshlrev_b64 v[62:63], 13, v[62:63]
	v_lshl_add_u64 v[62:63], v[152:153], 0, v[62:63]
	v_lshl_add_u64 v[66:67], v[62:63], 0, v[2:3]
	v_mov_b32_e32 v9, v3
	global_load_dword v1, v[66:67], off
	global_load_dword v68, v[66:67], off offset:256
	global_load_dword v69, v[66:67], off offset:512
	global_load_dword v64, v[66:67], off offset:768
	global_load_dword v71, v[66:67], off offset:1024
	v_lshl_add_u64 v[66:67], v[62:63], 0, v[8:9]
	v_mov_b32_e32 v11, v3
	global_load_dword v74, v[66:67], off
	v_lshl_add_u64 v[66:67], v[62:63], 0, v[10:11]
	v_mov_b32_e32 v13, v3
	global_load_dword v11, v[66:67], off
	v_lshl_add_u64 v[66:67], v[62:63], 0, v[12:13]
	v_mov_b32_e32 v15, v3
	global_load_dword v13, v[66:67], off
	v_lshl_add_u64 v[66:67], v[62:63], 0, v[14:15]
	v_mov_b32_e32 v17, v3
	global_load_dword v15, v[66:67], off
	v_lshl_add_u64 v[66:67], v[62:63], 0, v[16:17]
	v_mov_b32_e32 v19, v3
	global_load_dword v17, v[66:67], off
	v_lshl_add_u64 v[66:67], v[62:63], 0, v[18:19]
	v_mov_b32_e32 v21, v3
	global_load_dword v19, v[66:67], off
	v_lshl_add_u64 v[66:67], v[62:63], 0, v[20:21]
	v_mov_b32_e32 v23, v3
	global_load_dword v21, v[66:67], off
	v_lshl_add_u64 v[66:67], v[62:63], 0, v[22:23]
	v_mov_b32_e32 v25, v3
	global_load_dword v23, v[66:67], off
	v_lshl_add_u64 v[66:67], v[62:63], 0, v[24:25]
	v_mov_b32_e32 v27, v3
	global_load_dword v25, v[66:67], off
	v_lshl_add_u64 v[66:67], v[62:63], 0, v[26:27]
	v_mov_b32_e32 v29, v3
	global_load_dword v27, v[66:67], off
	v_lshl_add_u64 v[66:67], v[62:63], 0, v[28:29]
	v_mov_b32_e32 v31, v3
	global_load_dword v29, v[66:67], off
	v_lshl_add_u64 v[66:67], v[62:63], 0, v[30:31]
	v_mov_b32_e32 v33, v3
	global_load_dword v31, v[66:67], off
	v_lshl_add_u64 v[66:67], v[62:63], 0, v[32:33]
	v_mov_b32_e32 v35, v3
	global_load_dword v33, v[66:67], off
	v_lshl_add_u64 v[66:67], v[62:63], 0, v[34:35]
	v_mov_b32_e32 v37, v3
	global_load_dword v35, v[66:67], off
	v_lshl_add_u64 v[66:67], v[62:63], 0, v[36:37]
	v_mov_b32_e32 v39, v3
	global_load_dword v75, v[66:67], off
	v_lshl_add_u64 v[66:67], v[62:63], 0, v[38:39]
	v_mov_b32_e32 v41, v3
	global_load_dword v76, v[66:67], off
	v_lshl_add_u64 v[66:67], v[62:63], 0, v[40:41]
	v_mov_b32_e32 v43, v3
	global_load_dword v77, v[66:67], off
	v_lshl_add_u64 v[66:67], v[62:63], 0, v[42:43]
	v_mov_b32_e32 v45, v3
	global_load_dword v78, v[66:67], off
	v_lshl_add_u64 v[66:67], v[62:63], 0, v[44:45]
	v_mov_b32_e32 v47, v3
	global_load_dword v79, v[66:67], off
	v_lshl_add_u64 v[66:67], v[62:63], 0, v[46:47]
	v_mov_b32_e32 v49, v3
	global_load_dword v100, v[66:67], off
	v_lshl_add_u64 v[66:67], v[62:63], 0, v[48:49]
	v_mov_b32_e32 v51, v3
	global_load_dword v101, v[66:67], off
	v_lshl_add_u64 v[66:67], v[62:63], 0, v[50:51]
	v_mov_b32_e32 v53, v3
	global_load_dword v102, v[66:67], off
	v_lshl_add_u64 v[66:67], v[62:63], 0, v[52:53]
	v_mov_b32_e32 v55, v3
	global_load_dword v103, v[66:67], off
	v_lshl_add_u64 v[66:67], v[62:63], 0, v[54:55]
	v_mov_b32_e32 v57, v3
	global_load_dword v104, v[66:67], off
	v_lshl_add_u64 v[66:67], v[62:63], 0, v[56:57]
	v_mov_b32_e32 v59, v3
	global_load_dword v105, v[66:67], off
	v_lshl_add_u64 v[66:67], v[62:63], 0, v[58:59]
	v_mov_b32_e32 v61, v3
	global_load_dword v106, v[66:67], off
	v_lshl_add_u64 v[62:63], v[62:63], 0, v[60:61]
	global_load_dword v107, v[62:63], off
	v_and_b32_e32 v43, 64, v215
	v_add_u32_e32 v43, 64, v43
	v_xor_b32_e32 v62, 1, v215
	v_cmp_lt_i32_e32 vcc, v62, v43
	s_waitcnt vmcnt(0)
	v_add_f32_e32 v9, 0, v1
	v_fma_f32 v66, v1, v1, 0
	v_cndmask_b32_e32 v62, v215, v62, vcc
	v_lshlrev_b32_e32 v92, 2, v62
	v_xor_b32_e32 v62, 2, v215
	v_cmp_lt_i32_e32 vcc, v62, v43
	v_fmac_f32_e32 v66, v68, v68
	v_fmac_f32_e32 v66, v69, v69
	v_cndmask_b32_e32 v62, v215, v62, vcc
	v_lshlrev_b32_e32 v108, 2, v62
	v_xor_b32_e32 v62, 4, v215
	v_cmp_lt_i32_e32 vcc, v62, v43
	v_fmac_f32_e32 v66, v64, v64
	v_cndmask_b32_e64 v37, v74, 0, s[16:17]
	v_cndmask_b32_e32 v62, v215, v62, vcc
	v_lshlrev_b32_e32 v109, 2, v62
	v_xor_b32_e32 v62, 8, v215
	v_cmp_lt_i32_e32 vcc, v62, v43
	v_fmac_f32_e32 v66, v71, v71
	v_cndmask_b32_e64 v39, v11, 0, s[18:19]
	v_cndmask_b32_e32 v62, v215, v62, vcc
	v_lshlrev_b32_e32 v110, 2, v62
	v_xor_b32_e32 v62, 16, v215
	v_cmp_lt_i32_e32 vcc, v62, v43
	v_fmac_f32_e32 v66, v37, v37
	v_cndmask_b32_e64 v41, v13, 0, s[22:23]
	v_cndmask_b32_e32 v62, v215, v62, vcc
	v_lshlrev_b32_e32 v111, 2, v62
	v_xor_b32_e32 v62, 32, v215
	v_cmp_lt_i32_e32 vcc, v62, v43
	v_fmac_f32_e32 v66, v39, v39
	v_cndmask_b32_e64 v45, v15, 0, s[26:27]
	v_cndmask_b32_e32 v43, v215, v62, vcc
	v_lshlrev_b32_e32 v99, 2, v43
	v_not_b32_e32 v43, v1
	v_or_b32_e32 v62, 0x80000000, v1
	v_cmp_gt_i32_e32 vcc, 0, v1
	v_add_f32_e32 v1, v9, v68
	v_add_f32_e32 v9, v1, v69
	v_add_f32_e32 v9, v9, v64
	v_add_f32_e32 v9, v9, v71
	v_add_f32_e32 v9, v9, v37
	v_add_f32_e32 v9, v9, v39
	v_add_f32_e32 v9, v9, v41
	v_fmac_f32_e32 v66, v41, v41
	v_cndmask_b32_e64 v47, v17, 0, s[38:39]
	v_add_f32_e32 v9, v9, v45
	v_fmac_f32_e32 v66, v45, v45
	v_cndmask_b32_e64 v49, v19, 0, s[40:41]
	v_readlane_b32 s2, v253, 36
	v_add_f32_e32 v9, v9, v47
	v_fmac_f32_e32 v66, v47, v47
	v_cndmask_b32_e64 v51, v21, 0, s[60:61]
	v_readlane_b32 s3, v253, 37
	v_readlane_b32 s6, v253, 40
	v_add_f32_e32 v9, v9, v49
	v_fmac_f32_e32 v66, v49, v49
	v_cndmask_b32_e64 v53, v23, 0, s[2:3]
	v_readlane_b32 s7, v253, 41
	v_readlane_b32 s8, v249, 41
	v_add_f32_e32 v9, v9, v51
	v_fmac_f32_e32 v66, v51, v51
	v_cndmask_b32_e64 v55, v25, 0, s[6:7]
	v_readlane_b32 s9, v249, 42
	v_readlane_b32 s10, v253, 46
	v_add_f32_e32 v9, v9, v53
	v_fmac_f32_e32 v66, v53, v53
; DEVI unsigned ordkey(float f) { const unsigned u = __float_as_uint(f); return (u & 0x80000000u) ? ~u : (u | 0x80000000u); }
; template <class MP> DEVI void select_row(const float* sc, int c  , MP mrow, int lane) {
;     ...
;     for (int j = 0; j < 32; ++j) { const float f = (j <= c) ? __uint_as_float(u[j]) : 0.f; s1 += f; s2 = fmaf(f, f, s2); }
; #pragma unroll
;     for (int o = 1; o < 64; o <<= 1) { s1 += __shfl_xor(s1, o); s2 += __shfl_xor(s2, o); }
; #pragma unroll
;     for (int j = 0; j < 32; ++j) u[j] = (j <= c) ? ordkey(__uint_as_float(u[j])) : 0u;
	v_cndmask_b32_e64 v57, v27, 0, s[8:9]
	v_readlane_b32 s11, v253, 47
	v_readlane_b32 s14, v253, 50
	v_add_f32_e32 v9, v9, v55
	v_fmac_f32_e32 v66, v55, v55
	v_cndmask_b32_e64 v59, v29, 0, s[10:11]
	v_readlane_b32 s15, v253, 51
	v_readlane_b32 s20, v253, 54
	v_add_f32_e32 v9, v9, v57
	v_fmac_f32_e32 v66, v57, v57
	v_cndmask_b32_e64 v61, v31, 0, s[14:15]
	v_readlane_b32 s21, v253, 55
	v_readlane_b32 s28, v253, 58
	v_add_f32_e32 v9, v9, v59
	v_fmac_f32_e32 v66, v59, v59
	v_cndmask_b32_e64 v67, v33, 0, s[20:21]
	v_readlane_b32 s29, v253, 59
	v_readlane_b32 s42, v253, 62
	v_add_f32_e32 v9, v9, v61
	v_fmac_f32_e32 v66, v61, v61
	v_cndmask_b32_e64 v72, v35, 0, s[28:29]
	v_readlane_b32 s43, v253, 63
	v_readlane_b32 s44, v254, 2
	v_add_f32_e32 v9, v9, v67
	v_fmac_f32_e32 v66, v67, v67
	v_cndmask_b32_e64 v73, v75, 0, s[42:43]
	v_readlane_b32 s45, v254, 3
	v_readlane_b32 s46, v254, 6
	v_add_f32_e32 v9, v9, v72
	v_fmac_f32_e32 v66, v72, v72
	v_cndmask_b32_e64 v80, v76, 0, s[44:45]
	v_readlane_b32 s47, v254, 7
	v_readlane_b32 s48, v254, 10
	v_add_f32_e32 v9, v9, v73
	v_fmac_f32_e32 v66, v73, v73
	v_cndmask_b32_e64 v81, v77, 0, s[46:47]
	v_readlane_b32 s49, v254, 11
	v_readlane_b32 s50, v254, 14
	v_add_f32_e32 v9, v9, v80
	v_fmac_f32_e32 v66, v80, v80
	v_cndmask_b32_e64 v82, v78, 0, s[48:49]
	v_readlane_b32 s51, v254, 15
	v_readlane_b32 s52, v254, 18
	v_add_f32_e32 v9, v9, v81
	v_fmac_f32_e32 v66, v81, v81
	v_cndmask_b32_e64 v83, v79, 0, s[50:51]
	v_readlane_b32 s53, v254, 19
	v_readlane_b32 s54, v254, 22
	v_add_f32_e32 v9, v9, v82
	v_fmac_f32_e32 v66, v82, v82
	v_cndmask_b32_e64 v84, v100, 0, s[52:53]
	v_readlane_b32 s55, v254, 23
	v_readlane_b32 s56, v254, 26
	v_add_f32_e32 v9, v9, v83
	v_fmac_f32_e32 v66, v83, v83
	v_cndmask_b32_e64 v85, v101, 0, s[54:55]
	v_readlane_b32 s57, v254, 27
	v_readlane_b32 s58, v254, 30
	v_add_f32_e32 v9, v9, v84
	v_fmac_f32_e32 v66, v84, v84
	v_cndmask_b32_e64 v86, v102, 0, s[56:57]
	v_readlane_b32 s59, v254, 31
	v_readlane_b32 s62, v254, 34
	v_add_f32_e32 v9, v9, v85
	v_fmac_f32_e32 v66, v85, v85
	v_cndmask_b32_e64 v87, v103, 0, s[58:59]
	v_readlane_b32 s63, v254, 35
	v_readlane_b32 s64, v254, 38
	v_add_f32_e32 v9, v9, v86
	v_fmac_f32_e32 v66, v86, v86
	v_cndmask_b32_e64 v88, v104, 0, s[62:63]
	v_readlane_b32 s65, v254, 39
	v_readlane_b32 s66, v254, 42
	v_add_f32_e32 v9, v9, v87
	v_fmac_f32_e32 v66, v87, v87
	v_cndmask_b32_e64 v89, v105, 0, s[64:65]
	v_readlane_b32 s67, v254, 43
	v_readlane_b32 s68, v254, 46
	v_add_f32_e32 v9, v9, v88
	v_fmac_f32_e32 v66, v88, v88
	v_cndmask_b32_e64 v90, v106, 0, s[66:67]
	v_readlane_b32 s69, v254, 47
	v_add_f32_e32 v9, v9, v89
	v_fmac_f32_e32 v66, v89, v89
	v_cndmask_b32_e64 v91, v107, 0, s[68:69]
	v_add_f32_e32 v9, v9, v90
	v_fmac_f32_e32 v66, v90, v90
	v_add_f32_e32 v67, v9, v91
	v_fmac_f32_e32 v66, v91, v91
	v_cndmask_b32_e32 v43, v62, v43, vcc
	v_xor_b32_e32 v1, -1, v68
	v_xor_b32_e32 v93, -1, v69
	v_and_b32_e32 v63, 0x7fffffff, v68
	v_and_b32_e32 v62, 0x7fffffff, v69
	v_cmp_gt_i32_e32 vcc, 0, v69
	v_cmp_gt_i32_e64 s[4:5], 0, v68
	ds_bpermute_b32 v69, v92, v67
	ds_bpermute_b32 v68, v92, v66
	v_pk_add_f32 v[62:63], v[62:63], 0 neg_lo:[1,1] neg_hi:[1,1]
	v_and_b32_e32 v73, 0x7fffffff, v64
	v_and_b32_e32 v72, 0x7fffffff, v71
	v_cndmask_b32_e32 v62, v62, v93, vcc
	s_waitcnt lgkmcnt(0)
	v_add_f32 v66, v66, v68
	v_add_f32 v67, v67, v69
	ds_bpermute_b32 v69, v108, v67
	ds_bpermute_b32 v68, v108, v66
	v_xor_b32_e32 v37, -1, v71
	v_pk_add_f32 v[72:73], v[72:73], 0 neg_lo:[1,1] neg_hi:[1,1]
	v_cmp_gt_i32_e32 vcc, 0, v71
	v_cndmask_b32_e64 v1, v63, v1, s[4:5]
	s_waitcnt lgkmcnt(0)
	v_add_f32 v66, v66, v68
	v_add_f32 v67, v67, v69
	ds_bpermute_b32 v69, v109, v67
	ds_bpermute_b32 v68, v109, v66
	v_xor_b32_e32 v9, -1, v64
	v_cmp_gt_i32_e64 s[4:5], 0, v64
	v_cndmask_b32_e32 v64, v72, v37, vcc
	v_not_b32_e32 v37, v74
	v_or_b32_e32 v39, 0x80000000, v74
	v_cmp_gt_i32_e32 vcc, 0, v74
	s_waitcnt lgkmcnt(0)
	v_add_f32 v66, v66, v68
	v_add_f32 v67, v67, v69
	ds_bpermute_b32 v69, v110, v67
	v_cndmask_b32_e32 v98, v39, v37, vcc
	v_not_b32_e32 v37, v11
	v_or_b32_e32 v39, 0x80000000, v11
	v_cmp_gt_i32_e32 vcc, 0, v11
	v_not_b32_e32 v11, v13
	ds_bpermute_b32 v68, v110, v66
	v_cndmask_b32_e32 v97, v39, v37, vcc
	v_or_b32_e32 v37, 0x80000000, v13
	v_cmp_gt_i32_e32 vcc, 0, v13
	v_or_b32_e32 v13, 0x80000000, v15
	s_waitcnt lgkmcnt(0)
	v_add_f32 v66, v66, v68
	v_add_f32 v67, v67, v69
	v_cndmask_b32_e32 v96, v37, v11, vcc
	v_not_b32_e32 v11, v15
	v_cmp_gt_i32_e32 vcc, 0, v15
	ds_bpermute_b32 v69, v111, v67
	ds_bpermute_b32 v68, v111, v66
	v_cndmask_b32_e32 v95, v13, v11, vcc
	v_not_b32_e32 v11, v17
	v_or_b32_e32 v13, 0x80000000, v17
	v_cmp_gt_i32_e32 vcc, 0, v17
	s_waitcnt lgkmcnt(0)
	v_add_f32 v66, v66, v68
	v_add_f32 v67, v67, v69
	ds_bpermute_b32 v69, v99, v67
	v_cndmask_b32_e32 v94, v13, v11, vcc
	v_not_b32_e32 v11, v19
	v_or_b32_e32 v13, 0x80000000, v19
	v_cmp_gt_i32_e32 vcc, 0, v19
	ds_bpermute_b32 v68, v99, v66
	v_cndmask_b32_e64 v9, v73, v9, s[4:5]
	v_cndmask_b32_e32 v93, v13, v11, vcc
	v_not_b32_e32 v11, v21
	v_or_b32_e32 v13, 0x80000000, v21
	v_cmp_gt_i32_e32 vcc, 0, v21
	s_waitcnt lgkmcnt(0)
; DEVI unsigned ordkey(float f) { const unsigned u = __float_as_uint(f); return (u & 0x80000000u) ? ~u : (u | 0x80000000u); }
; template <class MP> DEVI void select_row(const float* sc, int c  , MP mrow, int lane) {
;     ...
;     for (int j = 0; j < 32; ++j) u[j] = (j <= c) ? ordkey(__uint_as_float(u[j])) : 0u;
;     unsigned elo, ehi, elo2, ehi2;
;     { const float n = 64.f * (float)(c + 1), p = 256.f / n, pp = p <= 0.5f ? p : 1.f - p, t = sqrtf(-2.f * __logf(pp));
;       float z = t - (2.515517f + t * (0.802853f + t * 0.010328f)) / (1.f + t * (1.432788f + t * (0.189269f + t * 0.001308f))); if (p > 0.5f) z = -z;
;       const float mean = s1 / n, sd = sqrtf(fmaxf(s2 / n - mean * mean, 0.f));
;       elo = ordkey(mean + (z - 0.3f) * sd); ehi = ordkey(mean + (z + 0.3f) * sd); elo2 = ordkey(mean + (z - 1.2f) * sd); ehi2 = ordkey(mean + (z + 1.2f) * sd); }
;     elo = (unsigned)__builtin_amdgcn_readfirstlane((int)elo); ehi = (unsigned)__builtin_amdgcn_readfirstlane((int)ehi);
;     elo2 = (unsigned)__builtin_amdgcn_readfirstlane((int)elo2); ehi2 = (unsigned)__builtin_amdgcn_readfirstlane((int)ehi2);
	v_add_f32 v66, v66, v68
	v_add_f32 v67, v67, v69
	v_or_b32_e32 v72, 0x80000000, v107
	v_cndmask_b32_e32 v92, v13, v11, vcc
	v_not_b32_e32 v11, v23
	v_or_b32_e32 v13, 0x80000000, v23
	v_cmp_gt_i32_e32 vcc, 0, v23
	v_div_scale_f32 v68, s[4:5], v65, v65, v66
	s_nop 0
	v_cndmask_b32_e32 v91, v13, v11, vcc
	v_not_b32_e32 v11, v25
	v_or_b32_e32 v13, 0x80000000, v25
	v_cmp_gt_i32_e32 vcc, 0, v25
	v_rcp_f32_e32 v69, v68
	v_cndmask_b32_e64 v51, v91, 0, s[2:3]
	v_cndmask_b32_e32 v90, v13, v11, vcc
	v_not_b32_e32 v11, v27
	v_or_b32_e32 v13, 0x80000000, v27
	v_cmp_gt_i32_e32 vcc, 0, v27
	v_fma_f32 v99, -v68, v69, 1.0
	v_fmac_f32_e32 v69, v99, v69
	v_cndmask_b32_e32 v89, v13, v11, vcc
	v_not_b32_e32 v11, v29
	v_or_b32_e32 v13, 0x80000000, v29
	v_cmp_gt_i32_e32 vcc, 0, v29
	s_mov_b32 s2, 0xf800000
	s_mov_b32 s33, 0
	v_cndmask_b32_e32 v88, v13, v11, vcc
	v_not_b32_e32 v11, v31
	v_or_b32_e32 v13, 0x80000000, v31
	v_cmp_gt_i32_e32 vcc, 0, v31
	s_mov_b32 s24, -1
	v_cndmask_b32_e64 v71, v98, 0, s[16:17]
	v_cndmask_b32_e32 v87, v13, v11, vcc
	v_not_b32_e32 v11, v33
	v_or_b32_e32 v13, 0x80000000, v33
	v_cmp_gt_i32_e32 vcc, 0, v33
	v_cndmask_b32_e64 v63, v97, 0, s[18:19]
	v_cndmask_b32_e64 v61, v96, 0, s[22:23]
	v_cndmask_b32_e32 v86, v13, v11, vcc
	v_not_b32_e32 v11, v35
	v_or_b32_e32 v13, 0x80000000, v35
	v_cmp_gt_i32_e32 vcc, 0, v35
	v_cndmask_b32_e64 v59, v95, 0, s[26:27]
	v_cndmask_b32_e64 v57, v94, 0, s[38:39]
	v_cndmask_b32_e32 v85, v13, v11, vcc
	v_not_b32_e32 v11, v75
	v_or_b32_e32 v13, 0x80000000, v75
	v_cmp_gt_i32_e32 vcc, 0, v75
	v_cndmask_b32_e64 v55, v93, 0, s[40:41]
	v_cndmask_b32_e64 v53, v92, 0, s[60:61]
	v_cndmask_b32_e32 v84, v13, v11, vcc
	v_not_b32_e32 v11, v76
	v_or_b32_e32 v13, 0x80000000, v76
	v_cmp_gt_i32_e32 vcc, 0, v76
	v_cndmask_b32_e64 v49, v90, 0, s[6:7]
	v_cndmask_b32_e64 v47, v89, 0, s[8:9]
	v_cndmask_b32_e32 v83, v13, v11, vcc
	v_not_b32_e32 v11, v77
	v_or_b32_e32 v13, 0x80000000, v77
	v_cmp_gt_i32_e32 vcc, 0, v77
	v_cndmask_b32_e64 v45, v88, 0, s[10:11]
	v_cndmask_b32_e64 v41, v87, 0, s[14:15]
	v_cndmask_b32_e32 v82, v13, v11, vcc
	v_not_b32_e32 v11, v78
	v_or_b32_e32 v13, 0x80000000, v78
	v_cmp_gt_i32_e32 vcc, 0, v78
	v_cndmask_b32_e64 v39, v86, 0, s[20:21]
	v_cndmask_b32_e64 v37, v85, 0, s[28:29]
	v_cndmask_b32_e32 v81, v13, v11, vcc
	v_not_b32_e32 v11, v79
	v_or_b32_e32 v13, 0x80000000, v79
	v_cmp_gt_i32_e32 vcc, 0, v79
	v_cndmask_b32_e64 v35, v84, 0, s[42:43]
	v_cndmask_b32_e64 v33, v83, 0, s[44:45]
	v_cndmask_b32_e32 v80, v13, v11, vcc
	v_not_b32_e32 v11, v100
	v_or_b32_e32 v13, 0x80000000, v100
	v_cmp_gt_i32_e32 vcc, 0, v100
	v_cndmask_b32_e64 v31, v82, 0, s[46:47]
	v_cndmask_b32_e64 v29, v81, 0, s[48:49]
	v_cndmask_b32_e32 v79, v13, v11, vcc
	v_not_b32_e32 v11, v101
	v_or_b32_e32 v13, 0x80000000, v101
	v_cmp_gt_i32_e32 vcc, 0, v101
	v_cndmask_b32_e64 v27, v80, 0, s[50:51]
	v_cndmask_b32_e64 v25, v79, 0, s[52:53]
	v_cndmask_b32_e32 v78, v13, v11, vcc
	v_not_b32_e32 v11, v102
	v_or_b32_e32 v13, 0x80000000, v102
	v_cmp_gt_i32_e32 vcc, 0, v102
	v_cndmask_b32_e64 v23, v78, 0, s[54:55]
	s_movk_i32 s49, 0x800
	v_cndmask_b32_e32 v77, v13, v11, vcc
	v_not_b32_e32 v11, v103
	v_or_b32_e32 v13, 0x80000000, v103
	v_cmp_gt_i32_e32 vcc, 0, v103
	v_cndmask_b32_e64 v21, v77, 0, s[56:57]
	s_mov_b32 s47, 0
	v_cndmask_b32_e32 v76, v13, v11, vcc
	v_not_b32_e32 v11, v104
	v_or_b32_e32 v13, 0x80000000, v104
	v_cmp_gt_i32_e32 vcc, 0, v104
	v_cndmask_b32_e64 v19, v76, 0, s[58:59]
	s_mov_b32 s48, 0
	v_cndmask_b32_e32 v75, v13, v11, vcc
	v_not_b32_e32 v11, v105
	v_or_b32_e32 v13, 0x80000000, v105
	v_cmp_gt_i32_e32 vcc, 0, v105
	v_cndmask_b32_e64 v17, v75, 0, s[62:63]
	s_mov_b32 s51, 0
	v_cndmask_b32_e32 v74, v13, v11, vcc
	v_not_b32_e32 v11, v106
	v_or_b32_e32 v13, 0x80000000, v106
	v_cmp_gt_i32_e32 vcc, 0, v106
	v_cndmask_b32_e64 v15, v74, 0, s[64:65]
	s_mov_b32 s50, -1
	v_cndmask_b32_e32 v73, v13, v11, vcc
	v_not_b32_e32 v11, v107
	v_cmp_gt_i32_e32 vcc, 0, v107
	v_cndmask_b32_e64 v13, v73, 0, s[66:67]
	s_nop 0
	v_cndmask_b32_e32 v72, v72, v11, vcc
	v_div_scale_f32 v99, vcc, v66, v65, v66
	v_mul_f32_e32 v100, v99, v69
	v_fma_f32 v101, -v68, v100, v99
	v_fmac_f32_e32 v100, v101, v69
	v_fma_f32 v68, -v68, v100, v99
	v_div_fmas_f32 v68, v68, v69, v100
	v_div_fixup_f32 v68, v68, v65, v66
	v_div_scale_f32 v66, s[4:5], v65, v65, v67
	v_rcp_f32_e32 v69, v66
	v_cndmask_b32_e64 v11, v72, 0, s[68:69]
	v_fma_f32 v99, -v66, v69, 1.0
	v_fmac_f32_e32 v69, v99, v69
	v_div_scale_f32 v99, vcc, v67, v65, v67
	v_mul_f32_e32 v100, v99, v69
	v_fma_f32 v101, -v66, v100, v99
	v_fmac_f32_e32 v100, v101, v69
	v_fma_f32 v66, -v66, v100, v99
	v_div_fmas_f32 v66, v66, v69, v100
	v_div_fixup_f32 v66, v66, v65, v67
	v_fma_f32 v67, -v66, v66, v68
	v_max_f32_e32 v67, 0, v67
	v_cmp_gt_f32_e32 vcc, s2, v67
	v_mul_f32_e32 v68, 0x4f800000, v67
	s_nop 0
	v_cndmask_b32_e32 v67, v67, v68, vcc
	v_sqrt_f32_e32 v68, v67
	s_nop 0
	v_add_u32_e32 v69, -1, v68
	v_fma_f32 v99, -v69, v68, v67
	v_cmp_ge_f32_e64 s[4:5], 0, v99
	v_add_u32_e32 v99, 1, v68
	s_nop 0
	v_cndmask_b32_e64 v69, v68, v69, s[4:5]
	v_fma_f32 v68, -v99, v68, v67
	v_cmp_lt_f32_e64 s[4:5], 0, v68
	s_nop 1
	v_cndmask_b32_e64 v68, v69, v99, s[4:5]
	v_mul_f32_e32 v69, 0x37800000, v68
	v_cndmask_b32_e32 v68, v68, v69, vcc
	v_cmp_class_f32_e32 vcc, v67, v210
	s_nop 1
	v_cndmask_b32_e32 v68, v68, v67, vcc
	v_fma_f32 v100, v4, v68, v66
	v_fma_f32 v101, v5, v68, v66
	s_nop 0
	v_not_b32_e32 v67, v101
	v_or_b32_e32 v69, 0x80000000, v101
	v_cmp_gt_i32_e64 s[4:5], 0, v101
	v_cmp_gt_i32_e32 vcc, 0, v100
	v_or_b32_e32 v99, 0x80000000, v100
	v_cndmask_b32_e64 v69, v69, v67, s[4:5]
	v_not_b32_e32 v67, v100
	v_cndmask_b32_e32 v99, v99, v67, vcc
	v_fma_f32 v67, v7, v68, v66
	v_fma_f32 v66, v6, v68, v66
	v_readfirstlane_b32 s25, v69
	v_not_b32_e32 v68, v67
	v_or_b32_e32 v100, 0x80000000, v67
	v_cmp_gt_i32_e64 s[4:5], 0, v67
	v_cmp_gt_i32_e32 vcc, 0, v66
	v_readfirstlane_b32 s44, v99
	v_cndmask_b32_e64 v67, v100, v68, s[4:5]
	v_not_b32_e32 v68, v66
	v_or_b32_e32 v66, 0x80000000, v66
	v_cndmask_b32_e32 v66, v66, v68, vcc
	v_readfirstlane_b32 s45, v67
	v_readfirstlane_b32 s46, v66
	s_mov_b64 s[4:5], 0
	s_branch .LBB11_1369

; #define LAS __attribute__((address_space(3)))
; DEVI int crow(int r, int hi) { return (r & 3) + 8 * (r >> 2) + 4 * hi; }
; DEVI float xlane32(float v) { return __shfl_xor(v, 32); }
; DEVI float max3f(float a, float b, float c) { float r; asm("v_max3_f32 %0, %1, %2, %3" : "=v"(r) : "v"(a), "v"(b), "v"(c)); return r; }
; DEVI void qkt(f32x16& p0, f32x16& p1, LAS const unsigned char* Ks, const bf16x8* qr, int r32, int hi) {
;     p0 = (f32x16){0.f, 0.f, 0.f, 0.f, 0.f, 0.f, 0.f, 0.f, 0.f, 0.f, 0.f, 0.f, 0.f, 0.f, 0.f, 0.f}; p1 = p0;
; #pragma unroll
;     for (int d0 = 0; d0 < 8; ++d0) { const int cb = (d0 * 16 + hi * 8) * 2;
;         const bf16x8 b0 = *(LAS const bf16x8*)(Ks + FA_KSWZ(r32, cb));
;         const bf16x8 b1 = *(LAS const bf16x8*)(Ks + FA_KSWZ(32 + r32, cb));
;         p0 = __builtin_amdgcn_mfma_f32_32x32x16_bf16(b0, qr[d0], p0, 0, 0, 0);
;         p1 = __builtin_amdgcn_mfma_f32_32x32x16_bf16(b1, qr[d0], p1, 0, 0, 0); }
; }
; template <int MODE>
; DEVI void attn_unit(LAS unsigned char* lds, const bf16_t* Qw, int ldq, const bf16_t* Kb, const bf16_t* Vb, int ldk, bf16_t* Ow, int ldo,
;                     int j_first, int ntiles, int jstep, int wj_lo, int wj_hi, int t0) {
;     ...
;                 float pmax = fmaxf(p0[0], p1[0]);
; #pragma unroll
;                 for (int r = 1; r < 15; r += 2) pmax = max3f(pmax, p0[r], p0[r + 1]);
; #pragma unroll
;                 for (int r = 1; r < 15; r += 2) pmax = max3f(pmax, p1[r], p1[r + 1]);
;                 pmax = max3f(pmax, p0[15], p1[15]);
;                 pmax = fmaxf(pmax, xlane32(pmax));
;                 const float pm2 = (MODE == M_BAND) ? pmax : pmax * C2;
;                 float mn = m_reg;
;                 if (!__all(pm2 - m_reg <= 8.f)) {
;                     mn = fmaxf(m_reg, pm2); const float alpha = __builtin_amdgcn_exp2f(m_reg - mn); m_reg = mn; l_reg *= alpha;
;                     if (hi == 0) al_l[r32] = alpha; asm volatile("s_waitcnt lgkmcnt(0)" ::: "memory");
; #pragma unroll
;                     for (int r = 0; r < 16; ++r) { const float af = al_l[crow(r, hi)];
; #pragma unroll
;                         for (int d = 0; d < 4; ++d) o[d][r] *= af; }
.LBB11_1656:
	v_add_u32_e32 v184, s4, v175
	s_waitcnt lgkmcnt(0)
	s_barrier
	v_and_b32_e32 v186, 64, v215
	v_add_u32_e32 v186, 64, v186
	s_mov_b32 s4, 0x41000000
	v_add_u32_e32 v185, v184, v176
	ds_read_b128 v[220:223], v185 offset:32768
	ds_read_b128 v[224:227], v185 offset:40960
	v_add_u32_e32 v236, v184, v177
	ds_read_b128 v[228:231], v236 offset:32768
	ds_read_b128 v[232:235], v236 offset:40960
	s_waitcnt lgkmcnt(3)
	v_mfma_f32_32x32x16_bf16 v[68:83], v[220:223], v[100:103], 0
	v_add_u32_e32 v237, v184, v178
	ds_read_b128 v[220:223], v237 offset:32768
	s_waitcnt lgkmcnt(3)
	v_mfma_f32_32x32x16_bf16 v[84:99], v[224:227], v[100:103], 0
	ds_read_b128 v[224:227], v237 offset:40960
	s_waitcnt lgkmcnt(3)
	v_mfma_f32_32x32x16_bf16 v[68:83], v[228:231], v[104:107], v[68:83]
	v_add_u32_e32 v238, v184, v179
	ds_read_b128 v[228:231], v238 offset:32768
	s_waitcnt lgkmcnt(3)
	v_mfma_f32_32x32x16_bf16 v[84:99], v[232:235], v[104:107], v[84:99]
	ds_read_b128 v[232:235], v238 offset:40960
	s_waitcnt lgkmcnt(3)
	v_mfma_f32_32x32x16_bf16 v[68:83], v[220:223], v[108:111], v[68:83]
	v_add_u32_e32 v185, v184, v181
	ds_read_b128 v[220:223], v185 offset:32768
	s_waitcnt lgkmcnt(3)
	v_mfma_f32_32x32x16_bf16 v[84:99], v[224:227], v[108:111], v[84:99]
	ds_read_b128 v[224:227], v185 offset:40960
	s_waitcnt lgkmcnt(3)
	v_mfma_f32_32x32x16_bf16 v[68:83], v[228:231], v[112:115], v[68:83]
	v_add_u32_e32 v236, v184, v183
	ds_read_b128 v[228:231], v236 offset:32768
	s_waitcnt lgkmcnt(3)
	v_mfma_f32_32x32x16_bf16 v[84:99], v[232:235], v[112:115], v[84:99]
	ds_read_b128 v[232:235], v236 offset:40960
	s_waitcnt lgkmcnt(3)
	v_mfma_f32_32x32x16_bf16 v[68:83], v[220:223], v[116:119], v[68:83]
	v_add_u32_e32 v237, v184, v198
	ds_read_b128 v[220:223], v237 offset:32768
	s_waitcnt lgkmcnt(3)
	v_mfma_f32_32x32x16_bf16 v[84:99], v[224:227], v[116:119], v[84:99]
	ds_read_b128 v[224:227], v237 offset:40960
	s_waitcnt lgkmcnt(3)
	v_mfma_f32_32x32x16_bf16 v[68:83], v[228:231], v[120:123], v[68:83]
	v_add_u32_e32 v238, v184, v199
	ds_read_b128 v[228:231], v238 offset:40960
	s_waitcnt lgkmcnt(3)
	v_mfma_f32_32x32x16_bf16 v[84:99], v[232:235], v[120:123], v[84:99]
	ds_read_b128 v[232:235], v238 offset:32768
	s_waitcnt lgkmcnt(3)
	v_mfma_f32_32x32x16_bf16 v[68:83], v[220:223], v[124:127], v[68:83]
	s_waitcnt lgkmcnt(2)
	v_mfma_f32_32x32x16_bf16 v[84:99], v[224:227], v[124:127], v[84:99]
	s_waitcnt lgkmcnt(1)
	v_mfma_f32_32x32x16_bf16 v[84:99], v[228:231], v[128:131], v[84:99]
	s_waitcnt lgkmcnt(0)
	v_mfma_f32_32x32x16_bf16 v[68:83], v[232:235], v[128:131], v[68:83]
	s_nop 8
	v_max_f32_e32 v184, v84, v84
	s_nop 1
	v_max_f32_e32 v185, v68, v68
	v_max_f32_e32 v184, v185, v184
	v_max3_f32 v184, v184, v69, v70
	v_xor_b32_e32 v185, 32, v215
	v_max3_f32 v184, v184, v71, v72
	v_cmp_lt_i32_e32 vcc, v185, v186
	v_max3_f32 v184, v184, v73, v74
	s_nop 0
	v_max3_f32 v184, v184, v75, v76
	s_nop 0
	v_max3_f32 v184, v184, v77, v78
	v_cndmask_b32_e32 v185, v215, v185, vcc
	v_max3_f32 v184, v184, v79, v80
	v_lshlrev_b32_e32 v204, 2, v185
	v_max3_f32 v184, v184, v81, v82
	s_nop 0
	v_max3_f32 v184, v184, v85, v86
	s_nop 0
	v_max3_f32 v184, v184, v87, v88
	s_nop 0
	v_max3_f32 v184, v184, v89, v90
	s_nop 0
	v_max3_f32 v184, v184, v91, v92
	s_nop 0
	v_max3_f32 v184, v184, v93, v94
	s_nop 0
	v_max3_f32 v184, v184, v95, v96
	s_nop 0
	v_max3_f32 v184, v184, v97, v98
	s_nop 0
	v_max3_f32 v184, v184, v83, v99
	ds_bpermute_b32 v185, v204, v184
	v_max_f32_e32 v184, v184, v184
	s_waitcnt lgkmcnt(0)
	v_max_f32_e32 v185, v185, v185
	v_max_f32_e32 v205, v184, v185
	v_fma_f32 v184, v205, s0, -v206
	v_cmp_ge_f32_e32 vcc, s4, v184
	s_cmp_eq_u64 vcc, exec
	s_cbranch_scc1 .LBB11_1660
	v_mul_f32_e32 v184, 0x3e0293ee, v205
	v_max_f32_e32 v184, v184, v184
	v_max_f32_e32 v185, v206, v206
	v_max_f32_e32 v205, v185, v184
	v_sub_f32_e32 v184, v206, v205
	v_exp_f32_e32 v206, v184
	s_and_saveexec_b64 s[4:5], s[40:41]
	ds_write_b32 v180, v206 offset:128
	s_or_b64 exec, exec, s[4:5]
	s_waitcnt lgkmcnt(0)
	v_add_u32_e32 v184, v167, v162
	ds_read_b128 v[220:223], v184 offset:128
	ds_read_b128 v[224:227], v184 offset:160
	ds_read_b128 v[228:231], v184 offset:192
	ds_read_b128 v[232:235], v184 offset:224
	v_mul_f32_e32 v203, v203, v206
	s_waitcnt lgkmcnt(3)
	v_mul_f32 v6, v6, v222
	v_mul_f32 v7, v7, v223
	s_waitcnt lgkmcnt(2)
	v_mul_f32 v8, v8, v224
	v_mul_f32 v9, v9, v225
	s_waitcnt lgkmcnt(1)
	v_mul_f32 v12, v12, v228
	v_mul_f32 v13, v13, v229
	s_waitcnt lgkmcnt(0)
	v_mul_f32 v16, v16, v232
	v_mul_f32 v17, v17, v233
	v_mul_f32 v18, v18, v234
	v_mul_f32 v19, v19, v235
	v_mul_f32 v14, v14, v230
	v_mul_f32 v15, v15, v231
	v_mul_f32 v10, v10, v226
	v_mul_f32 v11, v11, v227
	v_mul_f32 v4, v4, v220
	v_mul_f32 v5, v5, v221
	v_mul_f32 v64, v64, v232
	v_mul_f32 v65, v65, v233
	v_mul_f32 v60, v60, v228
	v_mul_f32 v61, v61, v229
	v_mul_f32 v56, v56, v224
	v_mul_f32 v57, v57, v225
	v_mul_f32 v66, v66, v234
	v_mul_f32 v67, v67, v235
	v_mul_f32 v62, v62, v230
	v_mul_f32 v63, v63, v231
	v_mul_f32 v58, v58, v226
	v_mul_f32 v59, v59, v227
	v_mul_f32 v54, v54, v222
	v_mul_f32 v55, v55, v223
	v_mul_f32 v52, v52, v220
	v_mul_f32 v53, v53, v221
	v_mul_f32 v48, v48, v232
	v_mul_f32 v49, v49, v233
	v_mul_f32 v44, v44, v228
	v_mul_f32 v45, v45, v229
	v_mul_f32 v40, v40, v224
	v_mul_f32 v41, v41, v225
	v_mul_f32 v50, v50, v234
	v_mul_f32 v51, v51, v235
	v_mul_f32 v46, v46, v230
	v_mul_f32 v47, v47, v231
	v_mul_f32 v42, v42, v226
	v_mul_f32 v43, v43, v227
	v_mul_f32 v38, v38, v222
	v_mul_f32 v39, v39, v223
	v_mul_f32 v36, v36, v220
	v_mul_f32 v37, v37, v221
	v_mul_f32 v32, v32, v232
	v_mul_f32 v33, v33, v233
	v_mul_f32 v28, v28, v228
	v_mul_f32 v29, v29, v229
	v_mul_f32 v24, v24, v224
	v_mul_f32 v25, v25, v225
	v_mul_f32 v34, v34, v234
	v_mul_f32 v35, v35, v235
	v_mul_f32 v30, v30, v230
	v_mul_f32 v31, v31, v231
	v_mul_f32 v26, v26, v226
	v_mul_f32 v27, v27, v227
	v_mul_f32 v22, v22, v222
	v_mul_f32 v23, v23, v223
	v_mul_f32 v20, v20, v220
	v_mul_f32 v21, v21, v221
	s_branch .LBB11_1661

; DEVI void pack_p(const f32x16& p0, const f32x16& p1, bf16x8& pa0, bf16x8& pa1, bf16x8& pa2, bf16x8& pa3) {
;     ...
;     FA_PK4(p0, 0, pa0); FA_PK4(p0, 8, pa1); FA_PK4(p1, 0, pa2); FA_PK4(p1, 8, pa3);
;     ...
; }
; template <int MODE>
; DEVI void attn_unit(LAS unsigned char* lds, const bf16_t* Qw, int ldq, const bf16_t* Kb, const bf16_t* Vb, int ldk, bf16_t* Ow, int ldo,
;                     int j_first, int ntiles, int jstep, int wj_lo, int wj_hi, int t0) {
;     ...
;                 } else { const float nmn = -mn;
; #pragma unroll
;                     for (int r = 0; r < 16; ++r) { p0[r] = __builtin_amdgcn_exp2f(fmaf(p0[r], C2, nmn)); p1[r] = __builtin_amdgcn_exp2f(fmaf(p1[r], C2, nmn)); }
;                 }
;                 if constexpr (MODE == M_DSA) {
;                     const u64 mw = maskl[r32 * 32 + j]; const int mlo = (int)(unsigned)(mw >> (4 * hi)), mhi = (int)(unsigned)(mw >> (32 + 4 * hi));
; #pragma unroll
;                     for (int r = 0; r < 16; ++r) { const int kbit = (r & 3) + 8 * (r >> 2);
;                         unsigned ma, mb; asm("v_bfe_i32 %0, %1, %2, 1" : "=v"(ma) : "v"(mlo), "n"(kbit)); asm("v_bfe_i32 %0, %1, %2, 1" : "=v"(mb) : "v"(mhi), "n"(kbit));
;                         p0[r] = __uint_as_float(__float_as_uint(p0[r]) & ma); p1[r] = __uint_as_float(__float_as_uint(p1[r]) & mb); }
;                 }
;                 float ps = 0.f;
; #pragma unroll
;                 for (int r = 0; r < 16; ++r) ps += p0[r] + p1[r];
;                 l_reg += ps;
;                 pack_p(p0, p1, pa0, pa1, pa2, pa3);
.LBB11_1661:
	v_fma_f32 v68, v68, s0, -v205
	v_exp_f32_e32 v184, v68
	v_fma_f32 v68, v84, s0, -v205
	v_exp_f32_e32 v84, v68
	v_fma_f32 v68, v69, s0, -v205
	v_exp_f32_e32 v185, v68
	v_fma_f32 v68, v85, s0, -v205
	v_exp_f32_e32 v85, v68
	v_fma_f32 v68, v70, s0, -v205
	v_exp_f32_e32 v186, v68
	v_fma_f32 v68, v86, s0, -v205
	v_exp_f32_e32 v86, v68
	v_fma_f32 v68, v71, s0, -v205
	v_exp_f32_e32 v187, v68
	v_fma_f32 v68, v87, s0, -v205
	v_exp_f32_e32 v87, v68
	v_fma_f32 v68, v72, s0, -v205
	v_exp_f32_e32 v72, v68
	v_fma_f32 v68, v88, s0, -v205
	v_exp_f32_e32 v88, v68
	v_fma_f32 v68, v73, s0, -v205
	v_exp_f32_e32 v73, v68
	v_fma_f32 v68, v89, s0, -v205
	v_exp_f32_e32 v89, v68
	v_fma_f32 v68, v74, s0, -v205
	v_exp_f32_e32 v74, v68
	v_fma_f32 v68, v90, s0, -v205
	v_exp_f32_e32 v90, v68
	v_fma_f32 v68, v75, s0, -v205
	v_exp_f32_e32 v75, v68
	v_fma_f32 v68, v91, s0, -v205
	v_exp_f32_e32 v91, v68
	v_fma_f32 v68, v76, s0, -v205
	v_exp_f32_e32 v76, v68
	v_fma_f32 v68, v92, s0, -v205
	v_exp_f32_e32 v92, v68
	v_fma_f32 v68, v77, s0, -v205
	v_exp_f32_e32 v77, v68
	v_fma_f32 v68, v93, s0, -v205
	v_exp_f32_e32 v93, v68
	v_fma_f32 v68, v78, s0, -v205
	v_exp_f32_e32 v196, v68
	v_fma_f32 v68, v94, s0, -v205
	v_exp_f32_e32 v94, v68
	v_fma_f32 v68, v79, s0, -v205
	v_exp_f32_e32 v197, v68
	v_fma_f32 v68, v95, s0, -v205
	v_exp_f32_e32 v95, v68
	v_fma_f32 v68, v80, s0, -v205
	v_exp_f32_e32 v206, v68
	v_fma_f32 v68, v96, s0, -v205
	v_exp_f32_e32 v96, v68
	v_fma_f32 v68, v81, s0, -v205
	v_exp_f32_e32 v207, v68
	v_fma_f32 v68, v97, s0, -v205
	v_exp_f32_e32 v97, v68
	v_fma_f32 v68, v82, s0, -v205
	v_exp_f32_e32 v220, v68
	v_fma_f32 v68, v98, s0, -v205
	v_exp_f32_e32 v98, v68
	v_fma_f32 v68, v83, s0, -v205
	v_exp_f32_e32 v221, v68
	v_fma_f32 v68, v99, s0, -v205
	v_exp_f32_e32 v99, v68
	ds_read_b64 v[68:69], v202
	s_waitcnt lgkmcnt(0)
	v_lshrrev_b64 v[70:71], v164, v[68:69]
	v_lshrrev_b64 v[68:69], v166, v[68:69]
	v_bfe_i32 v69, v70, 0, 1
	v_bfe_i32 v71, v68, 0, 1
	v_bfe_i32 v78, v68, 8, 1
	v_bfe_i32 v79, v68, 9, 1
	v_bfe_i32 v82, v68, 10, 1
	v_bfe_i32 v83, v68, 11, 1
	s_nop 0
	v_and_b32_e32 v184, v69, v184
	v_and_b32_e32 v222, v71, v84
	v_bfe_i32 v69, v70, 1, 1
	v_bfe_i32 v71, v68, 1, 1
	v_bfe_i32 v227, v68, 18, 1
	v_bfe_i32 v229, v68, 19, 1
	v_bfe_i32 v231, v68, 24, 1
	v_bfe_i32 v233, v68, 25, 1
	s_nop 0
	v_and_b32_e32 v185, v69, v185
	v_and_b32_e32 v223, v71, v85
	v_bfe_i32 v69, v70, 2, 1
	v_bfe_i32 v71, v68, 2, 1
	v_bfe_i32 v85, v68, 16, 1
	v_bfe_i32 v235, v68, 26, 1
	v_bfe_i32 v237, v68, 27, 1
	v_bfe_i32 v80, v70, 10, 1
	s_nop 0
	v_and_b32_e32 v186, v69, v186
	v_and_b32_e32 v224, v71, v86
	v_bfe_i32 v69, v70, 3, 1
	v_bfe_i32 v71, v68, 3, 1
	v_bfe_i32 v81, v70, 11, 1
	v_bfe_i32 v84, v70, 16, 1
	v_bfe_i32 v86, v70, 17, 1
	v_bfe_i32 v226, v70, 18, 1
	s_nop 0
	v_and_b32_e32 v187, v69, v187
	v_and_b32_e32 v225, v71, v87
	v_bfe_i32 v87, v68, 17, 1
	v_add_f32_e32 v68, v184, v222
	v_bfe_i32 v69, v70, 8, 1
	v_bfe_i32 v71, v70, 9, 1
	v_bfe_i32 v228, v70, 19, 1
	v_bfe_i32 v230, v70, 24, 1
	v_bfe_i32 v232, v70, 25, 1
	v_bfe_i32 v234, v70, 26, 1
	v_bfe_i32 v236, v70, 27, 1
	v_add_f32_e32 v68, 0, v68
	v_add_f32_e32 v70, v185, v223
	v_add_f32_e32 v68, v68, v70
	v_add_f32_e32 v70, v186, v224
	v_add_f32_e32 v68, v68, v70
	v_add_f32_e32 v70, v187, v225
	v_add_f32_e32 v238, v68, v70
	v_and_b32_e32 v71, v71, v73
	v_and_b32_e32 v70, v69, v72
	v_and_b32_e32 v79, v79, v89
	v_and_b32_e32 v78, v78, v88
	v_add_f32 v68, v70, v78
	v_add_f32 v69, v71, v79
	v_and_b32_e32 v73, v81, v75
	v_add_f32_e32 v68, v238, v68
	v_and_b32_e32 v72, v80, v74
	v_and_b32_e32 v81, v83, v91
	v_and_b32_e32 v80, v82, v90
	v_add_f32_e32 v88, v68, v69
	v_add_f32 v68, v72, v80
	v_add_f32 v69, v73, v81
	v_and_b32_e32 v75, v86, v77
	v_add_f32_e32 v68, v88, v68
	v_and_b32_e32 v74, v84, v76
	v_and_b32_e32 v83, v87, v93
	v_and_b32_e32 v82, v85, v92
	v_add_f32_e32 v88, v68, v69
	v_add_f32 v68, v74, v82
	v_add_f32 v69, v75, v83
	v_and_b32_e32 v77, v228, v197
	v_add_f32_e32 v68, v88, v68
	v_and_b32_e32 v76, v226, v196
	v_and_b32_e32 v85, v229, v95
	v_and_b32_e32 v84, v227, v94
	v_add_f32_e32 v86, v68, v69
	v_add_f32 v68, v76, v84
	v_add_f32 v69, v77, v85
	v_and_b32_e32 v87, v232, v207
	v_add_f32_e32 v68, v86, v68
	v_and_b32_e32 v86, v230, v206
	v_and_b32_e32 v89, v233, v97
	v_and_b32_e32 v88, v231, v96
	v_add_f32_e32 v90, v68, v69
	v_add_f32 v68, v86, v88
	v_add_f32 v69, v87, v89
	v_and_b32_e32 v91, v236, v221
	v_add_f32_e32 v68, v90, v68
	v_and_b32_e32 v90, v234, v220
	v_and_b32_e32 v93, v237, v99
	v_and_b32_e32 v92, v235, v98
	v_add_f32_e32 v94, v68, v69
	v_add_f32 v68, v90, v92
	v_add_f32 v69, v91, v93
	s_nop 0
	v_add_f32_e32 v68, v94, v68
	v_add_f32_e32 v68, v68, v69
	v_add_f32_e32 v203, v203, v68
	v_cvt_pk_bf16_f32 v68, v184, v185
	v_cvt_pk_bf16_f32 v69, v186, v187
	v_cvt_pk_bf16_f32 v70, v70, v71
	v_cvt_pk_bf16_f32 v71, v72, v73
	v_cvt_pk_bf16_f32 v72, v74, v75
	v_cvt_pk_bf16_f32 v73, v76, v77
	v_cvt_pk_bf16_f32 v74, v86, v87
	v_cvt_pk_bf16_f32 v75, v90, v91
	v_cvt_pk_bf16_f32 v76, v222, v223
	v_cvt_pk_bf16_f32 v77, v224, v225
	v_cvt_pk_bf16_f32 v78, v78, v79
	v_cvt_pk_bf16_f32 v79, v80, v81
	v_cvt_pk_bf16_f32 v80, v82, v83
	v_cvt_pk_bf16_f32 v81, v84, v85
	v_cvt_pk_bf16_f32 v82, v88, v89
	v_cvt_pk_bf16_f32 v83, v92, v93
	v_add_u32_e32 v184, s8, v201
	ds_read_b64_tr_b16 v[84:85], v184 offset:0
	ds_read_b64_tr_b16 v[86:87], v184 offset:0x800
	ds_read_b64_tr_b16 v[88:89], v184 offset:0x1000
	ds_read_b64_tr_b16 v[90:91], v184 offset:0x1800
	ds_read_b64_tr_b16 v[92:93], v184 offset:0x2000
	ds_read_b64_tr_b16 v[94:95], v184 offset:0x2800
	ds_read_b64_tr_b16 v[96:97], v184 offset:0x3000
	ds_read_b64_tr_b16 v[98:99], v184 offset:0x3800
	s_waitcnt lgkmcnt(0)
; #define FA_SBAR() __builtin_amdgcn_sched_barrier(0)
; template <int OFF> DEVI s16x4 tr_read(int vb) { s16x4 r; asm volatile("ds_read_b64_tr_b16 %0, %1 offset:%2" : "=&v"(r) : "v"(vb), "i"(OFF) : "memory"); return r; }
; template <int D0> DEVI void pv_one(f32x16& od, int vb, bf16x8 pa0, bf16x8 pa1, bf16x8 pa2, bf16x8 pa3) {
;     const s16x4 l0 = tr_read<v_rd_off(D0, 0, 0)>(vb), h0 = tr_read<v_rd_off(D0, 0, 1)>(vb), l1 = tr_read<v_rd_off(D0, 1, 0)>(vb), h1 = tr_read<v_rd_off(D0, 1, 1)>(vb);
;     const s16x4 l2 = tr_read<v_rd_off(D0, 2, 0)>(vb), h2 = tr_read<v_rd_off(D0, 2, 1)>(vb), l3 = tr_read<v_rd_off(D0, 3, 0)>(vb), h3 = tr_read<v_rd_off(D0, 3, 1)>(vb);
;     asm volatile("s_waitcnt lgkmcnt(0)" ::: "memory"); FA_SBAR();
;     ...
;     od = __builtin_amdgcn_mfma_f32_32x32x16_bf16(pa0, FA_PK(l0, h0), od, 0, 0, 0);
;     od = __builtin_amdgcn_mfma_f32_32x32x16_bf16(pa1, FA_PK(l1, h1), od, 0, 0, 0);
;     od = __builtin_amdgcn_mfma_f32_32x32x16_bf16(pa2, FA_PK(l2, h2), od, 0, 0, 0);
;     od = __builtin_amdgcn_mfma_f32_32x32x16_bf16(pa3, FA_PK(l3, h3), od, 0, 0, 0);
;     ...
; }
; DEVI void pv_d0(f32x16* o, int vb, bf16x8 pa0, bf16x8 pa1, bf16x8 pa2, bf16x8 pa3) {
;     pv_one<0>(o[0], vb, pa0, pa1, pa2, pa3); pv_one<1>(o[1], vb, pa0, pa1, pa2, pa3); pv_one<2>(o[2], vb, pa0, pa1, pa2, pa3); pv_one<3>(o[3], vb, pa0, pa1, pa2, pa3);
	v_permlane32_swap_b32_e32 v68, v70
	v_permlane32_swap_b32_e32 v69, v71
	v_permlane32_swap_b32_e32 v72, v74
	v_permlane32_swap_b32_e32 v73, v75
	v_permlane32_swap_b32_e32 v76, v78
	v_permlane32_swap_b32_e32 v77, v79
	v_permlane32_swap_b32_e32 v80, v82
	v_permlane32_swap_b32_e32 v81, v83
	v_mfma_f32_32x32x16_bf16 v[4:19], v[68:71], v[84:87], v[4:19]
	ds_read_b64_tr_b16 v[84:85], v184 offset:0x200
	ds_read_b64_tr_b16 v[86:87], v184 offset:0xa00
	v_mfma_f32_32x32x16_bf16 v[4:19], v[72:75], v[88:91], v[4:19]
	ds_read_b64_tr_b16 v[88:89], v184 offset:0x1200
	ds_read_b64_tr_b16 v[90:91], v184 offset:0x1a00
	v_mfma_f32_32x32x16_bf16 v[4:19], v[76:79], v[92:95], v[4:19]
	ds_read_b64_tr_b16 v[92:93], v184 offset:0x2200
	ds_read_b64_tr_b16 v[94:95], v184 offset:0x2a00
	v_mfma_f32_32x32x16_bf16 v[4:19], v[80:83], v[96:99], v[4:19]
	ds_read_b64_tr_b16 v[96:97], v184 offset:0x3200
	ds_read_b64_tr_b16 v[98:99], v184 offset:0x3a00
	s_waitcnt lgkmcnt(0)
	v_mfma_f32_32x32x16_bf16 v[52:67], v[68:71], v[84:87], v[52:67]
	ds_read_b64_tr_b16 v[84:85], v184 offset:0x400
	ds_read_b64_tr_b16 v[86:87], v184 offset:0xc00
	v_mfma_f32_32x32x16_bf16 v[52:67], v[72:75], v[88:91], v[52:67]
	ds_read_b64_tr_b16 v[88:89], v184 offset:0x1400
	ds_read_b64_tr_b16 v[90:91], v184 offset:0x1c00
	v_mfma_f32_32x32x16_bf16 v[52:67], v[76:79], v[92:95], v[52:67]
	ds_read_b64_tr_b16 v[92:93], v184 offset:0x2400
	ds_read_b64_tr_b16 v[94:95], v184 offset:0x2c00
	v_mfma_f32_32x32x16_bf16 v[52:67], v[80:83], v[96:99], v[52:67]
	ds_read_b64_tr_b16 v[96:97], v184 offset:0x3400
	ds_read_b64_tr_b16 v[98:99], v184 offset:0x3c00
	s_waitcnt lgkmcnt(0)
	v_mfma_f32_32x32x16_bf16 v[36:51], v[68:71], v[84:87], v[36:51]
	ds_read_b64_tr_b16 v[84:85], v184 offset:0x600
	ds_read_b64_tr_b16 v[86:87], v184 offset:0xe00
	v_mfma_f32_32x32x16_bf16 v[36:51], v[72:75], v[88:91], v[36:51]
	ds_read_b64_tr_b16 v[88:89], v184 offset:0x1600
	ds_read_b64_tr_b16 v[90:91], v184 offset:0x1e00
	v_mfma_f32_32x32x16_bf16 v[36:51], v[76:79], v[92:95], v[36:51]
	ds_read_b64_tr_b16 v[92:93], v184 offset:0x2600
	ds_read_b64_tr_b16 v[94:95], v184 offset:0x2e00
	v_mfma_f32_32x32x16_bf16 v[36:51], v[80:83], v[96:99], v[36:51]
	ds_read_b64_tr_b16 v[96:97], v184 offset:0x3600
	ds_read_b64_tr_b16 v[98:99], v184 offset:0x3e00
	s_waitcnt lgkmcnt(0)
	v_mfma_f32_32x32x16_bf16 v[20:35], v[68:71], v[84:87], v[20:35]
	s_add_u32 s2, s2, 0xb0000
	s_addc_u32 s3, s3, 0
	s_addk_i32 s6, 0x4000
	s_add_i32 s7, s7, 1
	v_add_u32_e32 v202, 8, v202
	s_cmp_eq_u32 s1, s2
	v_mfma_f32_32x32x16_bf16 v[20:35], v[72:75], v[88:91], v[20:35]
	v_mfma_f32_32x32x16_bf16 v[20:35], v[76:79], v[92:95], v[20:35]
	v_mfma_f32_32x32x16_bf16 v[20:35], v[80:83], v[96:99], v[20:35]
	s_cbranch_scc1 .LBB11_1663
	v_mov_b32_e32 v206, v205
	s_branch .LBB11_1654
